# first DMA wait of each unit deferred by two segments (peeled iteration: no wait in Q2-load(A), vmcnt(8) at end of Q1-load(B)); epilogues drain DMAs before their stores; prologue ends with vmcnt(0)
# baseline (speedup 1.0000x reference)
; #define PG8_STAGE(bufoff, gbase, voff) do { _Pragma("unroll") for (int _i = 0; _i < 2; ++_i) \
;         __builtin_amdgcn_global_load_lds((const unsigned*)((const char*)(gbase) + (voff)[_i]), (LAS unsigned*)(lds + (bufoff) + ldsw + _i * 8192), 16, 0, 0); } while (0)
; #define PG8_WAIT_V(n) asm volatile("s_waitcnt vmcnt(" #n ")" ::: "memory")
; #define PG8_BAR __builtin_amdgcn_s_barrier()
; template <class Epi, class Sched>
; __device__ __forceinline__ void gemm_phase(LAS unsigned char* lds, const Gemm g, const Sched& S, const Epi& E) {
;     ...
;     for (int i = 0; i < 2; ++i) { int R, C; stage_rc(tid * 16 + i * 8192, R, C); const int Rb = Epi::PERM ? ((R & ~31) + perm32(R & 31)) : R;
;         voffA[i] = (unsigned)(R * lda + C) * 2u; voffB[i] = (unsigned)(Rb * K + C) * 2u; }
;     const size_t kstep = (size_t)(BK * 2);
;     const size_t hstepA = (size_t)HALF * lda * 2, hstepB = (size_t)HALF * K * 2;
;     const size_t tstepA = 2 * hstepA, tstepB = 2 * hstepB;
;     const unsigned ldsw = (unsigned)wid * 1024u;
;     const int aoff = lds_byte(wr * 64 + fr, fq * 8), boff = lds_byte(wc * 32 + fr, fq * 8);
;     ...
;     PG8_STAGE(PG8_SB(0, 0), cB, voffB); PG8_STAGE(PG8_SA(0, 0), cA, voffA); PG8_STAGE(PG8_SB(0, 1), cB + hstepB, voffB); PG8_STAGE(PG8_SA(0, 1), cA + hstepA, voffA);
;     if (wr == 1) PG8_BAR;
;     PG8_WAIT_V(4); PG8_BAR;
;     PG8_STAGE(PG8_SB(1, 0), cB + kstep, voffB); PG8_STAGE(PG8_SA(1, 0), cA + kstep, voffA); PG8_STAGE(PG8_SB(1, 1), cB + hstepB + kstep, voffB);
;     PG8_WAIT_V(6); PG8_BAR;
.LBB0_345:
	v_readlane_b32 s18, v254, 37
	s_lshl_b32 s0, s0, 5
	v_mov_b32_e32 v139, v3
	v_readlane_b32 s19, v254, 38
	s_and_b32 s39, s0, 0x60
	s_add_i32 m0, s31, 0x18000
	v_lshl_add_u64 v[4:5], v[4:5], 0, s[8:9]
	v_lshl_add_u64 v[14:15], s[18:19], 0, v[138:139]
	v_mov_b32_e32 v135, v3
	s_lshl_b32 s38, s1, 6
	s_lshl_b32 s4, s1, 13
	s_lshl_b32 s5, s39, 7
	s_waitcnt vmcnt(2)
	s_barrier
	global_load_lds_dwordx4 v[4:5], off
	v_lshl_add_u64 v[4:5], v[6:7], 0, s[8:9]
	s_add_i32 m0, s31, 0x1a000
	s_add_i32 s40, s31, 0x8000
	s_add_i32 s41, s31, 0xa000
	v_lshl_add_u64 v[16:17], s[18:19], 0, v[134:135]
	global_load_lds_dwordx4 v[4:5], off
	v_lshl_add_u64 v[4:5], v[14:15], 0, s[8:9]
	s_mov_b32 m0, s40
	s_add_u32 s0, s20, 0x80080
	global_load_lds_dwordx4 v[4:5], off
	v_lshl_add_u64 v[4:5], v[16:17], 0, s[8:9]
	s_mov_b32 m0, s41
	s_addc_u32 s1, s21, 0
	global_load_lds_dwordx4 v[4:5], off
	s_add_i32 m0, s31, 0x1c000
	v_lshl_add_u64 v[4:5], s[0:1], 0, v[136:137]
	global_load_lds_dwordx4 v[4:5], off
	v_lshl_add_u64 v[4:5], s[0:1], 0, v[132:133]
	s_add_i32 m0, s31, 0x1e000
	s_movk_i32 s0, 0x3c0
	global_load_lds_dwordx4 v[4:5], off
	v_and_b32_e32 v4, 48, v1
	v_lshlrev_b32_e32 v5, 6, v1
	v_lshlrev_b32_e32 v1, 2, v1
	v_and_or_b32 v4, v5, s0, v4
	v_and_b32_e32 v1, 32, v1
	v_bitop3_b32 v5, v4, s4, v1 bitop3:0xde
	v_bitop3_b32 v1, s5, v4, v1 bitop3:0xf6
	v_lshlrev_b32_e32 v4, 15, v11
	v_and_b32_e32 v4, 0xffff0000, v4
	v_lshl_add_u32 v4, v10, 12, v4
	v_and_b32_e32 v6, 1, v11
	v_lshl_or_b32 v4, v6, 6, v4
	s_and_b32 s0, s2, 0xffffff00
	v_lshl_add_u32 v140, v12, 1, v4
	v_lshlrev_b32_e32 v4, 15, v2
	s_add_i32 s46, s0, 0
	v_readlane_b32 s4, v252, 0
	v_and_b32_e32 v4, 0xffff0000, v4
	s_waitcnt vmcnt(0)
	s_add_i32 s46, s46, 0x21000
	s_lshl_b32 s0, s39, 1
	v_readlane_b32 s6, v252, 2
	v_lshl_add_u32 v4, v8, 12, v4
	v_and_b32_e32 v2, 1, v2
	v_readlane_b32 s7, v252, 3
	s_add_u32 s47, s6, s0
	v_lshl_or_b32 v2, v2, 6, v4
	v_readlane_b32 s0, v254, 35
	s_addc_u32 s48, s7, 0
	v_mov_b32_e32 v141, v3
	v_lshl_add_u32 v142, v9, 1, v2
	v_mov_b32_e32 v143, v3
	s_mov_b32 s45, 0
	v_add_u32_e32 v149, 0, v5
	v_readlane_b32 s44, v254, 4
	s_mov_b32 s50, s0
	s_mov_b64 s[6:7], s[18:19]
	s_barrier
	v_readlane_b32 s5, v252, 1
	v_readlane_b32 s1, v254, 36
	s_branch .LBB0_347

; #define PG8_STAGE(bufoff, gbase, voff) do { _Pragma("unroll") for (int _i = 0; _i < 2; ++_i) \
;         __builtin_amdgcn_global_load_lds((const unsigned*)((const char*)(gbase) + (voff)[_i]), (LAS unsigned*)(lds + (bufoff) + ldsw + _i * 8192), 16, 0, 0); } while (0)
; #define PG8_LDA(dst, b, h) do { _Pragma("unroll") for (int m = 0; m < 4; ++m) _Pragma("unroll") for (int k = 0; k < 2; ++k) dst[m][k] = *(const LAS bf16x8*)(lds + PG8_SA(b, h) + aoff + m * 2048 + k * 1024); } while (0)
; #define PG8_LDB(dst, b, h) do { _Pragma("unroll") for (int n = 0; n < 2; ++n) _Pragma("unroll") for (int k = 0; k < 2; ++k) dst[n][k] = *(const LAS bf16x8*)(lds + PG8_SB(b, h) + boff + n * 2048 + k * 1024); } while (0)
; #define PG8_WAIT_V(n) asm volatile("s_waitcnt vmcnt(" #n ")" ::: "memory")
; #define PG8_WAIT_L(n) asm volatile("s_waitcnt lgkmcnt(" #n ")" ::: "memory")
; #define PG8_BAR __builtin_amdgcn_s_barrier()
; #define PG8_SCHED __builtin_amdgcn_sched_barrier(0)
; template <class Epi, class Sched>
; __device__ __forceinline__ void gemm_phase(LAS unsigned char* lds, const Gemm g, const Sched& S, const Epi& E) {
;     ...
;         const bool has_next = S.next(ui + 1, nxt);
;         const char* nA = has_next ? (const char*)g.A + (size_t)nxt.pm * tstepA : cA; const char* nB = has_next ? (const char*)g.Bt + (size_t)nxt.pn * tstepB : cB;
;         for (int t = 0; t < nt; t += 2) {
;             const bool last = (t == nt - 2);
;             const char* a1 = cA + (size_t)(t + 1) * kstep;
;             const char* a2 = last ? nA : cA + (size_t)(t + 2) * kstep; const char* b2 = last ? nB : cB + (size_t)(t + 2) * kstep;
;             const char* a3 = a2 + kstep; const char* b3 = b2 + kstep;
;             if (last && has_next) S.a_ready(nxt);
;             PG8_LDB(B0, 0, 0); PG8_SCHED; PG8_LDA(At, 0, 0); PG8_STAGE(PG8_SA(1, 1), a1 + hstepA, voffA);
;             PG8_WAIT_L(8); PG8_BAR; PG8_WAIT_L(0); PG8_MMA(0, 0, At, B0); PG8_BAR; PG8_SCHED;
;             PG8_LDB(B1, 0, 1); PG8_STAGE(PG8_SB(0, 0), b2, voffB);
;             PG8_BAR; PG8_WAIT_L(0); PG8_MMA(0, 1, At, B1); PG8_BAR;
;             PG8_LDA(At, 0, 1); PG8_STAGE(PG8_SA(0, 0), a2, voffA);
;             PG8_BAR; PG8_WAIT_L(0); PG8_MMA(1, 0, At, B0); PG8_BAR; PG8_SCHED;
;             PG8_STAGE(PG8_SB(0, 1), b2 + hstepB, voffB);
;             PG8_WAIT_V(6); PG8_BAR; PG8_MMA(1, 1, At, B1); PG8_BAR;
.LBB0_351:
	v_mov_b64_e32 v[4:5], 0xd80
	s_ashr_i32 s15, s14, 31
	v_cmp_lt_i64_e32 vcc, s[4:5], v[4:5]
	s_lshl_b64 s[4:5], s[14:15], 20
	s_add_u32 s18, s88, s4
	s_addc_u32 s19, s89, s5
	s_and_b64 s[4:5], vcc, exec
	s_cselect_b32 s15, s19, s7
	s_cselect_b32 s51, s18, s6
	s_ashr_i32 s1, s0, 31
	s_lshl_b64 s[4:5], s[0:1], 20
	s_add_u32 s4, s28, s4
	s_addc_u32 s5, s29, s5
	s_and_b64 s[24:25], vcc, exec
	s_cselect_b32 s1, s5, s21
	s_cselect_b32 s52, s4, s20
	s_add_u32 s6, s6, 0x80080
	s_addc_u32 s7, s7, 0
	s_add_u32 s53, s20, 0x100
	s_addc_u32 s54, s21, 0
	s_mov_b32 s55, -2
	s_waitcnt lgkmcnt(0)
	s_setprio 0
	s_add_u32 s20, s6, 0xfff80080
	s_addc_u32 s21, s7, -1
	s_add_i32 s56, 0, 0x10000
	v_add_u32_e32 v2, s56, v1
	ds_read_b128 v[144:147], v2
	ds_read_b128 v[150:153], v2 offset:1024
	ds_read_b128 v[154:157], v2 offset:2048
	ds_read_b128 v[158:161], v2 offset:3072
	s_cmp_eq_u32 s55, 28
	s_cselect_b32 s25, s15, s21
	s_cselect_b32 s24, s51, s20
	s_cselect_b32 s21, s1, s54
	s_cselect_b32 s20, s52, s53
	ds_read_b128 v[162:165], v149
	ds_read_b128 v[166:169], v149 offset:1024
	ds_read_b128 v[170:173], v149 offset:2048
	ds_read_b128 v[174:177], v149 offset:3072
	ds_read_b128 v[178:181], v149 offset:4096
	ds_read_b128 v[182:185], v149 offset:5120
	ds_read_b128 v[186:189], v149 offset:6144
	ds_read_b128 v[190:193], v149 offset:7168
	s_add_i32 s58, 0, 0x14000
	v_add_u32_e32 v2, s58, v1
	ds_read_b128 v[194:197], v2
	ds_read_b128 v[198:201], v2 offset:1024
	ds_read_b128 v[202:205], v2 offset:2048
	ds_read_b128 v[206:209], v2 offset:3072
	s_add_i32 m0, s31, 0xc000
	s_nop 0
	global_load_lds_dwordx4 v140, s[6:7]
	s_add_i32 m0, s31, 0xe000
	s_nop 0
	global_load_lds_dwordx4 v142, s[6:7]
	s_waitcnt lgkmcnt(0)
	s_setprio 1
	s_barrier
	v_mfma_f32_16x16x32_bf16 v[128:131], v[144:147], v[162:165], 0
	v_mfma_f32_16x16x32_bf16 v[124:127], v[154:157], v[162:165], 0
	v_mfma_f32_16x16x32_bf16 v[112:115], v[144:147], v[170:173], 0
	v_mfma_f32_16x16x32_bf16 v[108:111], v[154:157], v[170:173], 0
	v_mfma_f32_16x16x32_bf16 v[96:99], v[144:147], v[178:181], 0
	v_mfma_f32_16x16x32_bf16 v[92:95], v[154:157], v[178:181], 0
	v_mfma_f32_16x16x32_bf16 v[80:83], v[144:147], v[186:189], 0
	v_mfma_f32_16x16x32_bf16 v[76:79], v[154:157], v[186:189], 0
	v_mfma_f32_16x16x32_bf16 v[128:131], v[150:153], v[166:169], v[128:131]
	v_mfma_f32_16x16x32_bf16 v[124:127], v[158:161], v[166:169], v[124:127]
	v_mfma_f32_16x16x32_bf16 v[112:115], v[150:153], v[174:177], v[112:115]
	v_mfma_f32_16x16x32_bf16 v[108:111], v[158:161], v[174:177], v[108:111]
	v_mfma_f32_16x16x32_bf16 v[96:99], v[150:153], v[182:185], v[96:99]
	v_mfma_f32_16x16x32_bf16 v[92:95], v[158:161], v[182:185], v[92:95]
	v_mfma_f32_16x16x32_bf16 v[80:83], v[150:153], v[190:193], v[80:83]
	v_mfma_f32_16x16x32_bf16 v[76:79], v[158:161], v[190:193], v[76:79]
	v_mfma_f32_16x16x32_bf16 v[120:123], v[194:197], v[162:165], 0
	v_mfma_f32_16x16x32_bf16 v[116:119], v[202:205], v[162:165], 0
	v_mfma_f32_16x16x32_bf16 v[104:107], v[194:197], v[170:173], 0
	v_mfma_f32_16x16x32_bf16 v[100:103], v[202:205], v[170:173], 0
	v_mfma_f32_16x16x32_bf16 v[88:91], v[194:197], v[178:181], 0
	v_mfma_f32_16x16x32_bf16 v[84:87], v[202:205], v[178:181], 0
	v_mfma_f32_16x16x32_bf16 v[72:75], v[194:197], v[186:189], 0
	v_mfma_f32_16x16x32_bf16 v[68:71], v[202:205], v[186:189], 0
	v_mfma_f32_16x16x32_bf16 v[120:123], v[198:201], v[166:169], v[120:123]
	v_mfma_f32_16x16x32_bf16 v[116:119], v[206:209], v[166:169], v[116:119]
	v_mfma_f32_16x16x32_bf16 v[104:107], v[198:201], v[174:177], v[104:107]
	v_mfma_f32_16x16x32_bf16 v[100:103], v[206:209], v[174:177], v[100:103]
	v_mfma_f32_16x16x32_bf16 v[88:91], v[198:201], v[182:185], v[88:91]
	v_mfma_f32_16x16x32_bf16 v[84:87], v[206:209], v[182:185], v[84:87]
	v_mfma_f32_16x16x32_bf16 v[72:75], v[198:201], v[190:193], v[72:75]
	v_mfma_f32_16x16x32_bf16 v[68:71], v[206:209], v[190:193], v[68:71]
	s_barrier
	s_setprio 0
	ds_read_b128 v[162:165], v149 offset:16384
	ds_read_b128 v[166:169], v149 offset:17408
	ds_read_b128 v[170:173], v149 offset:18432
	ds_read_b128 v[174:177], v149 offset:19456
	ds_read_b128 v[178:181], v149 offset:20480
	ds_read_b128 v[182:185], v149 offset:21504
	ds_read_b128 v[186:189], v149 offset:22528
	ds_read_b128 v[190:193], v149 offset:23552
	s_add_i32 s56, s56, s30
	v_lshl_add_u64 v[210:211], s[20:21], 0, v[136:137]
	s_mov_b32 m0, s56
	s_nop 0
	global_load_lds_dwordx4 v[210:211], off
	v_lshl_add_u64 v[212:213], s[20:21], 0, v[132:133]
	s_add_i32 m0, s56, 0x2000
	s_nop 0
	global_load_lds_dwordx4 v[212:213], off
	s_mov_b32 m0, s31
	v_lshl_add_u64 v[216:217], s[24:25], 0, v[138:139]
	global_load_lds_dwordx4 v[216:217], off
	v_lshl_add_u64 v[218:219], s[24:25], 0, v[134:135]
	s_mov_b32 m0, s35
	s_nop 0
	global_load_lds_dwordx4 v[218:219], off
	s_add_u32 s56, s20, 0x80000
	s_addc_u32 s57, s21, 0
	s_add_i32 s58, s58, s30
	s_mov_b32 m0, s58
	s_nop 0
	global_load_lds_dwordx4 v136, s[56:57]
	s_add_i32 m0, s58, 0x2000
	s_nop 0
	global_load_lds_dwordx4 v132, s[56:57]
	s_waitcnt lgkmcnt(0)
	s_setprio 1
	s_barrier
; #define PG8_STAGE(bufoff, gbase, voff) do { _Pragma("unroll") for (int _i = 0; _i < 2; ++_i) \
;         __builtin_amdgcn_global_load_lds((const unsigned*)((const char*)(gbase) + (voff)[_i]), (LAS unsigned*)(lds + (bufoff) + ldsw + _i * 8192), 16, 0, 0); } while (0)
; #define PG8_LDA(dst, b, h) do { _Pragma("unroll") for (int m = 0; m < 4; ++m) _Pragma("unroll") for (int k = 0; k < 2; ++k) dst[m][k] = *(const LAS bf16x8*)(lds + PG8_SA(b, h) + aoff + m * 2048 + k * 1024); } while (0)
; #define PG8_LDB(dst, b, h) do { _Pragma("unroll") for (int n = 0; n < 2; ++n) _Pragma("unroll") for (int k = 0; k < 2; ++k) dst[n][k] = *(const LAS bf16x8*)(lds + PG8_SB(b, h) + boff + n * 2048 + k * 1024); } while (0)
; #define PG8_MMA(ai, bj, At, Bt) do { __builtin_amdgcn_s_setprio(1); _Pragma("unroll") for (int m = 0; m < 4; ++m) _Pragma("unroll") for (int n = 0; n < 2; ++n) _Pragma("unroll") for (int k = 0; k < 2; ++k) \
;         acc[ai][bj][m][n] = __builtin_amdgcn_mfma_f32_16x16x32_bf16(Bt[n][k], At[m][k], acc[ai][bj][m][n], 0, 0, 0); __builtin_amdgcn_s_setprio(0); } while (0)
; #define PG8_WAIT_V(n) asm volatile("s_waitcnt vmcnt(" #n ")" ::: "memory")
; #define PG8_WAIT_L(n) asm volatile("s_waitcnt lgkmcnt(" #n ")" ::: "memory")
; #define PG8_BAR __builtin_amdgcn_s_barrier()
; #define PG8_SCHED __builtin_amdgcn_sched_barrier(0)
; template <class Epi, class Sched>
; __device__ __forceinline__ void gemm_phase(LAS unsigned char* lds, const Gemm g, const Sched& S, const Epi& E) {
;     ...
;             PG8_WAIT_V(6); PG8_BAR; PG8_MMA(1, 1, At, B1); PG8_BAR;
;             PG8_LDB(B0, 1, 0); PG8_SCHED; PG8_LDA(At, 1, 0); PG8_STAGE(PG8_SA(0, 1), a2 + hstepA, voffA);
;             PG8_WAIT_L(8); PG8_BAR; PG8_WAIT_L(0); PG8_MMA(0, 0, At, B0); PG8_BAR; PG8_SCHED;
;             PG8_LDB(B1, 1, 1); PG8_STAGE(PG8_SB(1, 0), b3, voffB);
;             PG8_BAR; PG8_WAIT_L(0); PG8_MMA(0, 1, At, B1); PG8_BAR;
;             PG8_LDA(At, 1, 1); PG8_STAGE(PG8_SA(1, 0), a3, voffA);
;             PG8_BAR; PG8_WAIT_L(0); PG8_MMA(1, 0, At, B0); PG8_BAR; PG8_SCHED;
	v_mfma_f32_16x16x32_bf16 v[64:67], v[144:147], v[162:165], 0
	v_mfma_f32_16x16x32_bf16 v[60:63], v[154:157], v[162:165], 0
	v_mfma_f32_16x16x32_bf16 v[48:51], v[144:147], v[170:173], 0
	v_mfma_f32_16x16x32_bf16 v[44:47], v[154:157], v[170:173], 0
	v_mfma_f32_16x16x32_bf16 v[32:35], v[144:147], v[178:181], 0
	v_mfma_f32_16x16x32_bf16 v[28:31], v[154:157], v[178:181], 0
	v_mfma_f32_16x16x32_bf16 v[16:19], v[144:147], v[186:189], 0
	v_mfma_f32_16x16x32_bf16 v[12:15], v[154:157], v[186:189], 0
	v_mfma_f32_16x16x32_bf16 v[64:67], v[150:153], v[166:169], v[64:67]
	v_mfma_f32_16x16x32_bf16 v[60:63], v[158:161], v[166:169], v[60:63]
	v_mfma_f32_16x16x32_bf16 v[48:51], v[150:153], v[174:177], v[48:51]
	v_mfma_f32_16x16x32_bf16 v[44:47], v[158:161], v[174:177], v[44:47]
	v_mfma_f32_16x16x32_bf16 v[32:35], v[150:153], v[182:185], v[32:35]
	v_mfma_f32_16x16x32_bf16 v[28:31], v[158:161], v[182:185], v[28:31]
	v_mfma_f32_16x16x32_bf16 v[16:19], v[150:153], v[190:193], v[16:19]
	v_mfma_f32_16x16x32_bf16 v[12:15], v[158:161], v[190:193], v[12:15]
	v_mfma_f32_16x16x32_bf16 v[56:59], v[194:197], v[162:165], 0
	v_mfma_f32_16x16x32_bf16 v[52:55], v[202:205], v[162:165], 0
	v_mfma_f32_16x16x32_bf16 v[40:43], v[194:197], v[170:173], 0
	v_mfma_f32_16x16x32_bf16 v[36:39], v[202:205], v[170:173], 0
	v_mfma_f32_16x16x32_bf16 v[24:27], v[194:197], v[178:181], 0
	v_mfma_f32_16x16x32_bf16 v[20:23], v[202:205], v[178:181], 0
	v_mfma_f32_16x16x32_bf16 v[8:11], v[194:197], v[186:189], 0
	v_mfma_f32_16x16x32_bf16 v[4:7], v[202:205], v[186:189], 0
	v_mfma_f32_16x16x32_bf16 v[56:59], v[198:201], v[166:169], v[56:59]
	v_mfma_f32_16x16x32_bf16 v[52:55], v[206:209], v[166:169], v[52:55]
	v_mfma_f32_16x16x32_bf16 v[40:43], v[198:201], v[174:177], v[40:43]
	v_mfma_f32_16x16x32_bf16 v[36:39], v[206:209], v[174:177], v[36:39]
	v_mfma_f32_16x16x32_bf16 v[24:27], v[198:201], v[182:185], v[24:27]
	v_mfma_f32_16x16x32_bf16 v[20:23], v[206:209], v[182:185], v[20:23]
	v_mfma_f32_16x16x32_bf16 v[8:11], v[198:201], v[190:193], v[8:11]
	v_mfma_f32_16x16x32_bf16 v[4:7], v[206:209], v[190:193], v[4:7]
	s_barrier
	s_setprio 0
	s_add_i32 s56, 0, 0x18000
	v_add_u32_e32 v2, s56, v1
	ds_read_b128 v[144:147], v2
	ds_read_b128 v[150:153], v2 offset:1024
	ds_read_b128 v[154:157], v2 offset:2048
	ds_read_b128 v[158:161], v2 offset:3072
	s_add_u32 s24, s24, 0x80000
	s_addc_u32 s25, s25, 0
	ds_read_b128 v[162:165], v149 offset:32768
	ds_read_b128 v[166:169], v149 offset:33792
	ds_read_b128 v[170:173], v149 offset:34816
	ds_read_b128 v[174:177], v149 offset:35840
	ds_read_b128 v[178:181], v149 offset:36864
	ds_read_b128 v[182:185], v149 offset:37888
	ds_read_b128 v[186:189], v149 offset:38912
	ds_read_b128 v[190:193], v149 offset:39936
	s_mov_b32 m0, s36
	s_nop 0
	global_load_lds_dwordx4 v138, s[24:25]
	s_mov_b32 m0, s37
	s_nop 0
	global_load_lds_dwordx4 v134, s[24:25]
	s_add_i32 s24, 0, 0x1c000
	v_add_u32_e32 v2, s24, v1
	ds_read_b128 v[194:197], v2
	ds_read_b128 v[198:201], v2 offset:1024
	ds_read_b128 v[202:205], v2 offset:2048
	ds_read_b128 v[206:209], v2 offset:3072
	s_waitcnt lgkmcnt(0)
	s_setprio 1
	s_waitcnt vmcnt(8)
	s_barrier
	v_mfma_f32_16x16x32_bf16 v[128:131], v[144:147], v[162:165], v[128:131]
	v_mfma_f32_16x16x32_bf16 v[124:127], v[154:157], v[162:165], v[124:127]
	v_mfma_f32_16x16x32_bf16 v[112:115], v[144:147], v[170:173], v[112:115]
	v_mfma_f32_16x16x32_bf16 v[108:111], v[154:157], v[170:173], v[108:111]
	v_mfma_f32_16x16x32_bf16 v[96:99], v[144:147], v[178:181], v[96:99]
	v_mfma_f32_16x16x32_bf16 v[92:95], v[154:157], v[178:181], v[92:95]
	v_mfma_f32_16x16x32_bf16 v[80:83], v[144:147], v[186:189], v[80:83]
	v_mfma_f32_16x16x32_bf16 v[76:79], v[154:157], v[186:189], v[76:79]
	v_mfma_f32_16x16x32_bf16 v[128:131], v[150:153], v[166:169], v[128:131]
	v_mfma_f32_16x16x32_bf16 v[124:127], v[158:161], v[166:169], v[124:127]
	v_mfma_f32_16x16x32_bf16 v[112:115], v[150:153], v[174:177], v[112:115]
	v_mfma_f32_16x16x32_bf16 v[108:111], v[158:161], v[174:177], v[108:111]
	v_mfma_f32_16x16x32_bf16 v[96:99], v[150:153], v[182:185], v[96:99]
	v_mfma_f32_16x16x32_bf16 v[92:95], v[158:161], v[182:185], v[92:95]
	v_mfma_f32_16x16x32_bf16 v[80:83], v[150:153], v[190:193], v[80:83]
	v_mfma_f32_16x16x32_bf16 v[76:79], v[158:161], v[190:193], v[76:79]
	v_mfma_f32_16x16x32_bf16 v[120:123], v[194:197], v[162:165], v[120:123]
	v_mfma_f32_16x16x32_bf16 v[116:119], v[202:205], v[162:165], v[116:119]
	v_mfma_f32_16x16x32_bf16 v[104:107], v[194:197], v[170:173], v[104:107]
	v_mfma_f32_16x16x32_bf16 v[100:103], v[202:205], v[170:173], v[100:103]
	v_mfma_f32_16x16x32_bf16 v[88:91], v[194:197], v[178:181], v[88:91]
	v_mfma_f32_16x16x32_bf16 v[84:87], v[202:205], v[178:181], v[84:87]
	v_mfma_f32_16x16x32_bf16 v[72:75], v[194:197], v[186:189], v[72:75]
	v_mfma_f32_16x16x32_bf16 v[68:71], v[202:205], v[186:189], v[68:71]
	v_mfma_f32_16x16x32_bf16 v[120:123], v[198:201], v[166:169], v[120:123]
	v_mfma_f32_16x16x32_bf16 v[116:119], v[206:209], v[166:169], v[116:119]
	v_mfma_f32_16x16x32_bf16 v[104:107], v[198:201], v[174:177], v[104:107]
	v_mfma_f32_16x16x32_bf16 v[100:103], v[206:209], v[174:177], v[100:103]
	v_mfma_f32_16x16x32_bf16 v[88:91], v[198:201], v[182:185], v[88:91]
	v_mfma_f32_16x16x32_bf16 v[84:87], v[206:209], v[182:185], v[84:87]
	v_mfma_f32_16x16x32_bf16 v[72:75], v[198:201], v[190:193], v[72:75]
	v_mfma_f32_16x16x32_bf16 v[68:71], v[206:209], v[190:193], v[68:71]
	s_barrier
; #define PG8_STAGE(bufoff, gbase, voff) do { _Pragma("unroll") for (int _i = 0; _i < 2; ++_i) \
;         __builtin_amdgcn_global_load_lds((const unsigned*)((const char*)(gbase) + (voff)[_i]), (LAS unsigned*)(lds + (bufoff) + ldsw + _i * 8192), 16, 0, 0); } while (0)
; #define PG8_LDA(dst, b, h) do { _Pragma("unroll") for (int m = 0; m < 4; ++m) _Pragma("unroll") for (int k = 0; k < 2; ++k) dst[m][k] = *(const LAS bf16x8*)(lds + PG8_SA(b, h) + aoff + m * 2048 + k * 1024); } while (0)
; #define PG8_LDB(dst, b, h) do { _Pragma("unroll") for (int n = 0; n < 2; ++n) _Pragma("unroll") for (int k = 0; k < 2; ++k) dst[n][k] = *(const LAS bf16x8*)(lds + PG8_SB(b, h) + boff + n * 2048 + k * 1024); } while (0)
; #define PG8_WAIT_V(n) asm volatile("s_waitcnt vmcnt(" #n ")" ::: "memory")
; #define PG8_WAIT_L(n) asm volatile("s_waitcnt lgkmcnt(" #n ")" ::: "memory")
; #define PG8_BAR __builtin_amdgcn_s_barrier()
; #define PG8_SCHED __builtin_amdgcn_sched_barrier(0)
; template <class Epi, class Sched>
; __device__ __forceinline__ void gemm_phase(LAS unsigned char* lds, const Gemm g, const Sched& S, const Epi& E) {
;     ...
;         for (int t = 0; t < nt; t += 2) {
;             const bool last = (t == nt - 2);
;             const char* a1 = cA + (size_t)(t + 1) * kstep;
;             const char* a2 = last ? nA : cA + (size_t)(t + 2) * kstep; const char* b2 = last ? nB : cB + (size_t)(t + 2) * kstep;
;             const char* a3 = a2 + kstep; const char* b3 = b2 + kstep;
;             if (last && has_next) S.a_ready(nxt);
;             PG8_LDB(B0, 0, 0); PG8_SCHED; PG8_LDA(At, 0, 0); PG8_STAGE(PG8_SA(1, 1), a1 + hstepA, voffA);
;             PG8_WAIT_L(8); PG8_BAR; PG8_WAIT_L(0); PG8_MMA(0, 0, At, B0); PG8_BAR; PG8_SCHED;
;     ...
;             PG8_LDB(B0, 1, 0); PG8_SCHED; PG8_LDA(At, 1, 0); PG8_STAGE(PG8_SA(0, 1), a2 + hstepA, voffA);
;             PG8_WAIT_L(8); PG8_BAR; PG8_WAIT_L(0); PG8_MMA(0, 0, At, B0); PG8_BAR; PG8_SCHED;
;             PG8_LDB(B1, 1, 1); PG8_STAGE(PG8_SB(1, 0), b3, voffB);
;             PG8_BAR; PG8_WAIT_L(0); PG8_MMA(0, 1, At, B1); PG8_BAR;
;             PG8_LDA(At, 1, 1); PG8_STAGE(PG8_SA(1, 0), a3, voffA);
;             PG8_BAR; PG8_WAIT_L(0); PG8_MMA(1, 0, At, B0); PG8_BAR; PG8_SCHED;
;             PG8_STAGE(PG8_SB(1, 1), b3 + hstepB, voffB);
;             PG8_WAIT_V(6); PG8_BAR; PG8_MMA(1, 1, At, B1); PG8_BAR;
	s_setprio 0
	ds_read_b128 v[162:165], v149 offset:49152
	ds_read_b128 v[166:169], v149 offset:50176
	ds_read_b128 v[170:173], v149 offset:51200
	ds_read_b128 v[174:177], v149 offset:52224
	ds_read_b128 v[178:181], v149 offset:53248
	ds_read_b128 v[182:185], v149 offset:54272
	ds_read_b128 v[186:189], v149 offset:55296
	ds_read_b128 v[190:193], v149 offset:56320
	s_add_i32 s25, s56, s30
	v_lshl_add_u64 v[210:211], v[210:211], 0, s[8:9]
	s_mov_b32 m0, s25
	s_nop 0
	global_load_lds_dwordx4 v[210:211], off
	v_lshl_add_u64 v[210:211], v[212:213], 0, s[8:9]
	s_add_i32 m0, s25, 0x2000
	s_nop 0
	global_load_lds_dwordx4 v[210:211], off
	s_mov_b32 m0, s40
	v_lshl_add_u64 v[210:211], v[216:217], 0, s[8:9]
	global_load_lds_dwordx4 v[210:211], off
	v_lshl_add_u64 v[210:211], v[218:219], 0, s[8:9]
	s_mov_b32 m0, s41
	s_nop 0
	global_load_lds_dwordx4 v[210:211], off
	s_add_u32 s20, s20, 0x80080
	s_addc_u32 s21, s21, 0
	s_add_i32 s24, s24, s30
	s_mov_b32 m0, s24
	s_nop 0
	global_load_lds_dwordx4 v136, s[20:21]
	s_add_i32 m0, s24, 0x2000
	s_nop 0
	global_load_lds_dwordx4 v132, s[20:21]
	s_add_i32 s55, s55, 2
	s_add_u32 s6, s6, 0x100
	s_addc_u32 s7, s7, 0
	s_add_u32 s53, s53, 0x100
	s_addc_u32 s54, s54, 0
	s_cmp_gt_u32 s55, 29
	s_waitcnt lgkmcnt(0)
	s_waitcnt vmcnt(6)
	s_setprio 1
	s_barrier
	v_mfma_f32_16x16x32_bf16 v[64:67], v[144:147], v[162:165], v[64:67]
	v_mfma_f32_16x16x32_bf16 v[60:63], v[154:157], v[162:165], v[60:63]
	v_mfma_f32_16x16x32_bf16 v[48:51], v[144:147], v[170:173], v[48:51]
	v_mfma_f32_16x16x32_bf16 v[44:47], v[154:157], v[170:173], v[44:47]
	v_mfma_f32_16x16x32_bf16 v[32:35], v[144:147], v[178:181], v[32:35]
	v_mfma_f32_16x16x32_bf16 v[28:31], v[154:157], v[178:181], v[28:31]
	v_mfma_f32_16x16x32_bf16 v[16:19], v[144:147], v[186:189], v[16:19]
	v_mfma_f32_16x16x32_bf16 v[12:15], v[154:157], v[186:189], v[12:15]
	v_mfma_f32_16x16x32_bf16 v[64:67], v[150:153], v[166:169], v[64:67]
	v_mfma_f32_16x16x32_bf16 v[60:63], v[158:161], v[166:169], v[60:63]
	v_mfma_f32_16x16x32_bf16 v[48:51], v[150:153], v[174:177], v[48:51]
	v_mfma_f32_16x16x32_bf16 v[44:47], v[158:161], v[174:177], v[44:47]
	v_mfma_f32_16x16x32_bf16 v[32:35], v[150:153], v[182:185], v[32:35]
	v_mfma_f32_16x16x32_bf16 v[28:31], v[158:161], v[182:185], v[28:31]
	v_mfma_f32_16x16x32_bf16 v[16:19], v[150:153], v[190:193], v[16:19]
	v_mfma_f32_16x16x32_bf16 v[12:15], v[158:161], v[190:193], v[12:15]
	v_mfma_f32_16x16x32_bf16 v[56:59], v[194:197], v[162:165], v[56:59]
	v_mfma_f32_16x16x32_bf16 v[52:55], v[202:205], v[162:165], v[52:55]
	v_mfma_f32_16x16x32_bf16 v[40:43], v[194:197], v[170:173], v[40:43]
	v_mfma_f32_16x16x32_bf16 v[36:39], v[202:205], v[170:173], v[36:39]
	v_mfma_f32_16x16x32_bf16 v[24:27], v[194:197], v[178:181], v[24:27]
	v_mfma_f32_16x16x32_bf16 v[20:23], v[202:205], v[178:181], v[20:23]
	v_mfma_f32_16x16x32_bf16 v[8:11], v[194:197], v[186:189], v[8:11]
	v_mfma_f32_16x16x32_bf16 v[4:7], v[202:205], v[186:189], v[4:7]
	v_mfma_f32_16x16x32_bf16 v[56:59], v[198:201], v[166:169], v[56:59]
	v_mfma_f32_16x16x32_bf16 v[52:55], v[206:209], v[166:169], v[52:55]
	v_mfma_f32_16x16x32_bf16 v[40:43], v[198:201], v[174:177], v[40:43]
	v_mfma_f32_16x16x32_bf16 v[36:39], v[206:209], v[174:177], v[36:39]
	v_mfma_f32_16x16x32_bf16 v[24:27], v[198:201], v[182:185], v[24:27]
	v_mfma_f32_16x16x32_bf16 v[20:23], v[206:209], v[182:185], v[20:23]
	v_mfma_f32_16x16x32_bf16 v[8:11], v[198:201], v[190:193], v[8:11]
	v_mfma_f32_16x16x32_bf16 v[4:7], v[206:209], v[190:193], v[4:7]
	s_barrier
	s_setprio 0
.LBB0_352:
	s_setprio 0
	s_add_u32 s20, s6, 0xfff80080
	s_addc_u32 s21, s7, -1
	s_add_i32 s56, 0, 0x10000
	v_add_u32_e32 v2, s56, v1
	ds_read_b128 v[144:147], v2
	ds_read_b128 v[150:153], v2 offset:1024
	ds_read_b128 v[154:157], v2 offset:2048
	ds_read_b128 v[158:161], v2 offset:3072
	s_cmp_eq_u32 s55, 28
	s_cselect_b32 s25, s15, s21
	s_cselect_b32 s24, s51, s20
	s_cselect_b32 s21, s1, s54
	s_cselect_b32 s20, s52, s53
	ds_read_b128 v[162:165], v149
	ds_read_b128 v[166:169], v149 offset:1024
	ds_read_b128 v[170:173], v149 offset:2048
	ds_read_b128 v[174:177], v149 offset:3072
	ds_read_b128 v[178:181], v149 offset:4096
	ds_read_b128 v[182:185], v149 offset:5120
	ds_read_b128 v[186:189], v149 offset:6144
	ds_read_b128 v[190:193], v149 offset:7168
	s_add_i32 s58, 0, 0x14000
	v_add_u32_e32 v2, s58, v1
	ds_read_b128 v[194:197], v2
	ds_read_b128 v[198:201], v2 offset:1024
	ds_read_b128 v[202:205], v2 offset:2048
	ds_read_b128 v[206:209], v2 offset:3072
	s_add_i32 m0, s31, 0xc000
	s_nop 0
	global_load_lds_dwordx4 v140, s[6:7]
	s_add_i32 m0, s31, 0xe000
	s_nop 0
	global_load_lds_dwordx4 v142, s[6:7]
	s_waitcnt lgkmcnt(0)
	s_setprio 1
	s_barrier
; #define PG8_STAGE(bufoff, gbase, voff) do { _Pragma("unroll") for (int _i = 0; _i < 2; ++_i) \
;         __builtin_amdgcn_global_load_lds((const unsigned*)((const char*)(gbase) + (voff)[_i]), (LAS unsigned*)(lds + (bufoff) + ldsw + _i * 8192), 16, 0, 0); } while (0)
; #define PG8_LDA(dst, b, h) do { _Pragma("unroll") for (int m = 0; m < 4; ++m) _Pragma("unroll") for (int k = 0; k < 2; ++k) dst[m][k] = *(const LAS bf16x8*)(lds + PG8_SA(b, h) + aoff + m * 2048 + k * 1024); } while (0)
; #define PG8_LDB(dst, b, h) do { _Pragma("unroll") for (int n = 0; n < 2; ++n) _Pragma("unroll") for (int k = 0; k < 2; ++k) dst[n][k] = *(const LAS bf16x8*)(lds + PG8_SB(b, h) + boff + n * 2048 + k * 1024); } while (0)
; #define PG8_MMA(ai, bj, At, Bt) do { __builtin_amdgcn_s_setprio(1); _Pragma("unroll") for (int m = 0; m < 4; ++m) _Pragma("unroll") for (int n = 0; n < 2; ++n) _Pragma("unroll") for (int k = 0; k < 2; ++k) \
;         acc[ai][bj][m][n] = __builtin_amdgcn_mfma_f32_16x16x32_bf16(Bt[n][k], At[m][k], acc[ai][bj][m][n], 0, 0, 0); __builtin_amdgcn_s_setprio(0); } while (0)
; #define PG8_WAIT_V(n) asm volatile("s_waitcnt vmcnt(" #n ")" ::: "memory")
; #define PG8_WAIT_L(n) asm volatile("s_waitcnt lgkmcnt(" #n ")" ::: "memory")
; #define PG8_BAR __builtin_amdgcn_s_barrier()
; #define PG8_SCHED __builtin_amdgcn_sched_barrier(0)
; template <class Epi, class Sched>
; __device__ __forceinline__ void gemm_phase(LAS unsigned char* lds, const Gemm g, const Sched& S, const Epi& E) {
;     ...
;             PG8_WAIT_L(8); PG8_BAR; PG8_WAIT_L(0); PG8_MMA(0, 0, At, B0); PG8_BAR; PG8_SCHED;
;             PG8_LDB(B1, 0, 1); PG8_STAGE(PG8_SB(0, 0), b2, voffB);
;             PG8_BAR; PG8_WAIT_L(0); PG8_MMA(0, 1, At, B1); PG8_BAR;
;             PG8_LDA(At, 0, 1); PG8_STAGE(PG8_SA(0, 0), a2, voffA);
;             PG8_BAR; PG8_WAIT_L(0); PG8_MMA(1, 0, At, B0); PG8_BAR; PG8_SCHED;
;             PG8_STAGE(PG8_SB(0, 1), b2 + hstepB, voffB);
;             PG8_WAIT_V(6); PG8_BAR; PG8_MMA(1, 1, At, B1); PG8_BAR;
	v_mfma_f32_16x16x32_bf16 v[128:131], v[144:147], v[162:165], v[128:131]
	v_mfma_f32_16x16x32_bf16 v[124:127], v[154:157], v[162:165], v[124:127]
	v_mfma_f32_16x16x32_bf16 v[112:115], v[144:147], v[170:173], v[112:115]
	v_mfma_f32_16x16x32_bf16 v[108:111], v[154:157], v[170:173], v[108:111]
	v_mfma_f32_16x16x32_bf16 v[96:99], v[144:147], v[178:181], v[96:99]
	v_mfma_f32_16x16x32_bf16 v[92:95], v[154:157], v[178:181], v[92:95]
	v_mfma_f32_16x16x32_bf16 v[80:83], v[144:147], v[186:189], v[80:83]
	v_mfma_f32_16x16x32_bf16 v[76:79], v[154:157], v[186:189], v[76:79]
	v_mfma_f32_16x16x32_bf16 v[128:131], v[150:153], v[166:169], v[128:131]
	v_mfma_f32_16x16x32_bf16 v[124:127], v[158:161], v[166:169], v[124:127]
	v_mfma_f32_16x16x32_bf16 v[112:115], v[150:153], v[174:177], v[112:115]
	v_mfma_f32_16x16x32_bf16 v[108:111], v[158:161], v[174:177], v[108:111]
	v_mfma_f32_16x16x32_bf16 v[96:99], v[150:153], v[182:185], v[96:99]
	v_mfma_f32_16x16x32_bf16 v[92:95], v[158:161], v[182:185], v[92:95]
	v_mfma_f32_16x16x32_bf16 v[80:83], v[150:153], v[190:193], v[80:83]
	v_mfma_f32_16x16x32_bf16 v[76:79], v[158:161], v[190:193], v[76:79]
	v_mfma_f32_16x16x32_bf16 v[120:123], v[194:197], v[162:165], v[120:123]
	v_mfma_f32_16x16x32_bf16 v[116:119], v[202:205], v[162:165], v[116:119]
	v_mfma_f32_16x16x32_bf16 v[104:107], v[194:197], v[170:173], v[104:107]
	v_mfma_f32_16x16x32_bf16 v[100:103], v[202:205], v[170:173], v[100:103]
	v_mfma_f32_16x16x32_bf16 v[88:91], v[194:197], v[178:181], v[88:91]
	v_mfma_f32_16x16x32_bf16 v[84:87], v[202:205], v[178:181], v[84:87]
	v_mfma_f32_16x16x32_bf16 v[72:75], v[194:197], v[186:189], v[72:75]
	v_mfma_f32_16x16x32_bf16 v[68:71], v[202:205], v[186:189], v[68:71]
	v_mfma_f32_16x16x32_bf16 v[120:123], v[198:201], v[166:169], v[120:123]
	v_mfma_f32_16x16x32_bf16 v[116:119], v[206:209], v[166:169], v[116:119]
	v_mfma_f32_16x16x32_bf16 v[104:107], v[198:201], v[174:177], v[104:107]
	v_mfma_f32_16x16x32_bf16 v[100:103], v[206:209], v[174:177], v[100:103]
	v_mfma_f32_16x16x32_bf16 v[88:91], v[198:201], v[182:185], v[88:91]
	v_mfma_f32_16x16x32_bf16 v[84:87], v[206:209], v[182:185], v[84:87]
	v_mfma_f32_16x16x32_bf16 v[72:75], v[198:201], v[190:193], v[72:75]
	v_mfma_f32_16x16x32_bf16 v[68:71], v[206:209], v[190:193], v[68:71]
	s_barrier
	s_setprio 0
	ds_read_b128 v[162:165], v149 offset:16384
	ds_read_b128 v[166:169], v149 offset:17408
	ds_read_b128 v[170:173], v149 offset:18432
	ds_read_b128 v[174:177], v149 offset:19456
	ds_read_b128 v[178:181], v149 offset:20480
	ds_read_b128 v[182:185], v149 offset:21504
	ds_read_b128 v[186:189], v149 offset:22528
	ds_read_b128 v[190:193], v149 offset:23552
	s_add_i32 s56, s56, s30
	v_lshl_add_u64 v[210:211], s[20:21], 0, v[136:137]
	s_mov_b32 m0, s56
	s_nop 0
	global_load_lds_dwordx4 v[210:211], off
	v_lshl_add_u64 v[212:213], s[20:21], 0, v[132:133]
	s_add_i32 m0, s56, 0x2000
	s_nop 0
	global_load_lds_dwordx4 v[212:213], off
	s_mov_b32 m0, s31
	v_lshl_add_u64 v[216:217], s[24:25], 0, v[138:139]
	global_load_lds_dwordx4 v[216:217], off
	v_lshl_add_u64 v[218:219], s[24:25], 0, v[134:135]
	s_mov_b32 m0, s35
	s_nop 0
	global_load_lds_dwordx4 v[218:219], off
	s_add_u32 s56, s20, 0x80000
	s_addc_u32 s57, s21, 0
	s_add_i32 s58, s58, s30
	s_mov_b32 m0, s58
	s_nop 0
	global_load_lds_dwordx4 v136, s[56:57]
	s_add_i32 m0, s58, 0x2000
	s_nop 0
	global_load_lds_dwordx4 v132, s[56:57]
	s_waitcnt lgkmcnt(0)
	s_waitcnt vmcnt(6)
	s_setprio 1
	s_barrier
	v_mfma_f32_16x16x32_bf16 v[64:67], v[144:147], v[162:165], v[64:67]
	v_mfma_f32_16x16x32_bf16 v[60:63], v[154:157], v[162:165], v[60:63]
	v_mfma_f32_16x16x32_bf16 v[48:51], v[144:147], v[170:173], v[48:51]
	v_mfma_f32_16x16x32_bf16 v[44:47], v[154:157], v[170:173], v[44:47]
	v_mfma_f32_16x16x32_bf16 v[32:35], v[144:147], v[178:181], v[32:35]
	v_mfma_f32_16x16x32_bf16 v[28:31], v[154:157], v[178:181], v[28:31]
	v_mfma_f32_16x16x32_bf16 v[16:19], v[144:147], v[186:189], v[16:19]
	v_mfma_f32_16x16x32_bf16 v[12:15], v[154:157], v[186:189], v[12:15]
	v_mfma_f32_16x16x32_bf16 v[64:67], v[150:153], v[166:169], v[64:67]
	v_mfma_f32_16x16x32_bf16 v[60:63], v[158:161], v[166:169], v[60:63]
	v_mfma_f32_16x16x32_bf16 v[48:51], v[150:153], v[174:177], v[48:51]
	v_mfma_f32_16x16x32_bf16 v[44:47], v[158:161], v[174:177], v[44:47]
	v_mfma_f32_16x16x32_bf16 v[32:35], v[150:153], v[182:185], v[32:35]
	v_mfma_f32_16x16x32_bf16 v[28:31], v[158:161], v[182:185], v[28:31]
	v_mfma_f32_16x16x32_bf16 v[16:19], v[150:153], v[190:193], v[16:19]
	v_mfma_f32_16x16x32_bf16 v[12:15], v[158:161], v[190:193], v[12:15]
	v_mfma_f32_16x16x32_bf16 v[56:59], v[194:197], v[162:165], v[56:59]
	v_mfma_f32_16x16x32_bf16 v[52:55], v[202:205], v[162:165], v[52:55]
	v_mfma_f32_16x16x32_bf16 v[40:43], v[194:197], v[170:173], v[40:43]
	v_mfma_f32_16x16x32_bf16 v[36:39], v[202:205], v[170:173], v[36:39]
	v_mfma_f32_16x16x32_bf16 v[24:27], v[194:197], v[178:181], v[24:27]
	v_mfma_f32_16x16x32_bf16 v[20:23], v[202:205], v[178:181], v[20:23]
	v_mfma_f32_16x16x32_bf16 v[8:11], v[194:197], v[186:189], v[8:11]
	v_mfma_f32_16x16x32_bf16 v[4:7], v[202:205], v[186:189], v[4:7]
	v_mfma_f32_16x16x32_bf16 v[56:59], v[198:201], v[166:169], v[56:59]
	v_mfma_f32_16x16x32_bf16 v[52:55], v[206:209], v[166:169], v[52:55]
	v_mfma_f32_16x16x32_bf16 v[40:43], v[198:201], v[174:177], v[40:43]
	v_mfma_f32_16x16x32_bf16 v[36:39], v[206:209], v[174:177], v[36:39]
	v_mfma_f32_16x16x32_bf16 v[24:27], v[198:201], v[182:185], v[24:27]
	v_mfma_f32_16x16x32_bf16 v[20:23], v[206:209], v[182:185], v[20:23]
	v_mfma_f32_16x16x32_bf16 v[8:11], v[198:201], v[190:193], v[8:11]
	v_mfma_f32_16x16x32_bf16 v[4:7], v[206:209], v[190:193], v[4:7]
	s_barrier
; #define PG8_STAGE(bufoff, gbase, voff) do { _Pragma("unroll") for (int _i = 0; _i < 2; ++_i) \
;         __builtin_amdgcn_global_load_lds((const unsigned*)((const char*)(gbase) + (voff)[_i]), (LAS unsigned*)(lds + (bufoff) + ldsw + _i * 8192), 16, 0, 0); } while (0)
; #define PG8_LDA(dst, b, h) do { _Pragma("unroll") for (int m = 0; m < 4; ++m) _Pragma("unroll") for (int k = 0; k < 2; ++k) dst[m][k] = *(const LAS bf16x8*)(lds + PG8_SA(b, h) + aoff + m * 2048 + k * 1024); } while (0)
; #define PG8_LDB(dst, b, h) do { _Pragma("unroll") for (int n = 0; n < 2; ++n) _Pragma("unroll") for (int k = 0; k < 2; ++k) dst[n][k] = *(const LAS bf16x8*)(lds + PG8_SB(b, h) + boff + n * 2048 + k * 1024); } while (0)
; #define PG8_MMA(ai, bj, At, Bt) do { __builtin_amdgcn_s_setprio(1); _Pragma("unroll") for (int m = 0; m < 4; ++m) _Pragma("unroll") for (int n = 0; n < 2; ++n) _Pragma("unroll") for (int k = 0; k < 2; ++k) \
;         acc[ai][bj][m][n] = __builtin_amdgcn_mfma_f32_16x16x32_bf16(Bt[n][k], At[m][k], acc[ai][bj][m][n], 0, 0, 0); __builtin_amdgcn_s_setprio(0); } while (0)
; #define PG8_WAIT_V(n) asm volatile("s_waitcnt vmcnt(" #n ")" ::: "memory")
; #define PG8_WAIT_L(n) asm volatile("s_waitcnt lgkmcnt(" #n ")" ::: "memory")
; #define PG8_BAR __builtin_amdgcn_s_barrier()
; #define PG8_SCHED __builtin_amdgcn_sched_barrier(0)
; template <class Epi, class Sched>
; __device__ __forceinline__ void gemm_phase(LAS unsigned char* lds, const Gemm g, const Sched& S, const Epi& E) {
;     ...
;             PG8_LDB(B0, 1, 0); PG8_SCHED; PG8_LDA(At, 1, 0); PG8_STAGE(PG8_SA(0, 1), a2 + hstepA, voffA);
;             PG8_WAIT_L(8); PG8_BAR; PG8_WAIT_L(0); PG8_MMA(0, 0, At, B0); PG8_BAR; PG8_SCHED;
;             PG8_LDB(B1, 1, 1); PG8_STAGE(PG8_SB(1, 0), b3, voffB);
;             PG8_BAR; PG8_WAIT_L(0); PG8_MMA(0, 1, At, B1); PG8_BAR;
;             PG8_LDA(At, 1, 1); PG8_STAGE(PG8_SA(1, 0), a3, voffA);
;             PG8_BAR; PG8_WAIT_L(0); PG8_MMA(1, 0, At, B0); PG8_BAR; PG8_SCHED;
;             PG8_STAGE(PG8_SB(1, 1), b3 + hstepB, voffB);
;             PG8_WAIT_V(6); PG8_BAR; PG8_MMA(1, 1, At, B1); PG8_BAR;
	s_setprio 0
	s_add_i32 s56, 0, 0x18000
	v_add_u32_e32 v2, s56, v1
	ds_read_b128 v[144:147], v2
	ds_read_b128 v[150:153], v2 offset:1024
	ds_read_b128 v[154:157], v2 offset:2048
	ds_read_b128 v[158:161], v2 offset:3072
	s_add_u32 s24, s24, 0x80000
	s_addc_u32 s25, s25, 0
	ds_read_b128 v[162:165], v149 offset:32768
	ds_read_b128 v[166:169], v149 offset:33792
	ds_read_b128 v[170:173], v149 offset:34816
	ds_read_b128 v[174:177], v149 offset:35840
	ds_read_b128 v[178:181], v149 offset:36864
	ds_read_b128 v[182:185], v149 offset:37888
	ds_read_b128 v[186:189], v149 offset:38912
	ds_read_b128 v[190:193], v149 offset:39936
	s_mov_b32 m0, s36
	s_nop 0
	global_load_lds_dwordx4 v138, s[24:25]
	s_mov_b32 m0, s37
	s_nop 0
	global_load_lds_dwordx4 v134, s[24:25]
	s_add_i32 s24, 0, 0x1c000
	v_add_u32_e32 v2, s24, v1
	ds_read_b128 v[194:197], v2
	ds_read_b128 v[198:201], v2 offset:1024
	ds_read_b128 v[202:205], v2 offset:2048
	ds_read_b128 v[206:209], v2 offset:3072
	s_waitcnt lgkmcnt(0)
	s_setprio 1
	s_barrier
	v_mfma_f32_16x16x32_bf16 v[128:131], v[144:147], v[162:165], v[128:131]
	v_mfma_f32_16x16x32_bf16 v[124:127], v[154:157], v[162:165], v[124:127]
	v_mfma_f32_16x16x32_bf16 v[112:115], v[144:147], v[170:173], v[112:115]
	v_mfma_f32_16x16x32_bf16 v[108:111], v[154:157], v[170:173], v[108:111]
	v_mfma_f32_16x16x32_bf16 v[96:99], v[144:147], v[178:181], v[96:99]
	v_mfma_f32_16x16x32_bf16 v[92:95], v[154:157], v[178:181], v[92:95]
	v_mfma_f32_16x16x32_bf16 v[80:83], v[144:147], v[186:189], v[80:83]
	v_mfma_f32_16x16x32_bf16 v[76:79], v[154:157], v[186:189], v[76:79]
	v_mfma_f32_16x16x32_bf16 v[128:131], v[150:153], v[166:169], v[128:131]
	v_mfma_f32_16x16x32_bf16 v[124:127], v[158:161], v[166:169], v[124:127]
	v_mfma_f32_16x16x32_bf16 v[112:115], v[150:153], v[174:177], v[112:115]
	v_mfma_f32_16x16x32_bf16 v[108:111], v[158:161], v[174:177], v[108:111]
	v_mfma_f32_16x16x32_bf16 v[96:99], v[150:153], v[182:185], v[96:99]
	v_mfma_f32_16x16x32_bf16 v[92:95], v[158:161], v[182:185], v[92:95]
	v_mfma_f32_16x16x32_bf16 v[80:83], v[150:153], v[190:193], v[80:83]
	v_mfma_f32_16x16x32_bf16 v[76:79], v[158:161], v[190:193], v[76:79]
	v_mfma_f32_16x16x32_bf16 v[120:123], v[194:197], v[162:165], v[120:123]
	v_mfma_f32_16x16x32_bf16 v[116:119], v[202:205], v[162:165], v[116:119]
	v_mfma_f32_16x16x32_bf16 v[104:107], v[194:197], v[170:173], v[104:107]
	v_mfma_f32_16x16x32_bf16 v[100:103], v[202:205], v[170:173], v[100:103]
	v_mfma_f32_16x16x32_bf16 v[88:91], v[194:197], v[178:181], v[88:91]
	v_mfma_f32_16x16x32_bf16 v[84:87], v[202:205], v[178:181], v[84:87]
	v_mfma_f32_16x16x32_bf16 v[72:75], v[194:197], v[186:189], v[72:75]
	v_mfma_f32_16x16x32_bf16 v[68:71], v[202:205], v[186:189], v[68:71]
	v_mfma_f32_16x16x32_bf16 v[120:123], v[198:201], v[166:169], v[120:123]
	v_mfma_f32_16x16x32_bf16 v[116:119], v[206:209], v[166:169], v[116:119]
	v_mfma_f32_16x16x32_bf16 v[104:107], v[198:201], v[174:177], v[104:107]
	v_mfma_f32_16x16x32_bf16 v[100:103], v[206:209], v[174:177], v[100:103]
	v_mfma_f32_16x16x32_bf16 v[88:91], v[198:201], v[182:185], v[88:91]
	v_mfma_f32_16x16x32_bf16 v[84:87], v[206:209], v[182:185], v[84:87]
	v_mfma_f32_16x16x32_bf16 v[72:75], v[198:201], v[190:193], v[72:75]
	v_mfma_f32_16x16x32_bf16 v[68:71], v[206:209], v[190:193], v[68:71]
	s_barrier
	s_setprio 0
	ds_read_b128 v[162:165], v149 offset:49152
	ds_read_b128 v[166:169], v149 offset:50176
	ds_read_b128 v[170:173], v149 offset:51200
	ds_read_b128 v[174:177], v149 offset:52224
	ds_read_b128 v[178:181], v149 offset:53248
	ds_read_b128 v[182:185], v149 offset:54272
	ds_read_b128 v[186:189], v149 offset:55296
	ds_read_b128 v[190:193], v149 offset:56320
	s_add_i32 s25, s56, s30
	v_lshl_add_u64 v[210:211], v[210:211], 0, s[8:9]
	s_mov_b32 m0, s25
	s_nop 0
	global_load_lds_dwordx4 v[210:211], off
	v_lshl_add_u64 v[210:211], v[212:213], 0, s[8:9]
	s_add_i32 m0, s25, 0x2000
	s_nop 0
	global_load_lds_dwordx4 v[210:211], off
	s_mov_b32 m0, s40
	v_lshl_add_u64 v[210:211], v[216:217], 0, s[8:9]
	global_load_lds_dwordx4 v[210:211], off
	v_lshl_add_u64 v[210:211], v[218:219], 0, s[8:9]
	s_mov_b32 m0, s41
	s_nop 0
	global_load_lds_dwordx4 v[210:211], off
	s_add_u32 s20, s20, 0x80080
	s_addc_u32 s21, s21, 0
	s_add_i32 s24, s24, s30
	s_mov_b32 m0, s24
	s_nop 0
	global_load_lds_dwordx4 v136, s[20:21]
	s_add_i32 m0, s24, 0x2000
	s_nop 0
	global_load_lds_dwordx4 v132, s[20:21]
	s_add_i32 s55, s55, 2
	s_add_u32 s6, s6, 0x100
	s_addc_u32 s7, s7, 0
	s_add_u32 s53, s53, 0x100
	s_addc_u32 s54, s54, 0
	s_cmp_gt_u32 s55, 29
	s_waitcnt lgkmcnt(0)
	s_waitcnt vmcnt(6)
	s_setprio 1
	s_barrier
; __device__ __forceinline__ unsigned cvt_pk_bf16(float lo, float hi) { const f32x2 v = {lo, hi}; const bf16v2_ r = __builtin_convertvector(v, bf16v2_); return __builtin_bit_cast(unsigned, r); }
; __device__ __forceinline__ int opaque_tid() { int t = threadIdx.x; asm volatile("" : "+v"(t)); return t; }
; #define PG8_MMA(ai, bj, At, Bt) do { __builtin_amdgcn_s_setprio(1); _Pragma("unroll") for (int m = 0; m < 4; ++m) _Pragma("unroll") for (int n = 0; n < 2; ++n) _Pragma("unroll") for (int k = 0; k < 2; ++k) \
;         acc[ai][bj][m][n] = __builtin_amdgcn_mfma_f32_16x16x32_bf16(Bt[n][k], At[m][k], acc[ai][bj][m][n], 0, 0, 0); __builtin_amdgcn_s_setprio(0); } while (0)
; #define PG8_WAIT_V(n) asm volatile("s_waitcnt vmcnt(" #n ")" ::: "memory")
; #define PG8_BAR __builtin_amdgcn_s_barrier()
; template <class Epi, class Sched>
; __device__ __forceinline__ void gemm_phase(LAS unsigned char* lds, const Gemm g, const Sched& S, const Epi& E) {
;     ...
;             PG8_WAIT_V(6); PG8_BAR; PG8_MMA(1, 1, At, B1); PG8_BAR;
;         }
;         E(acc, cur, wr, wc, ui, fq);
;     __device__ __forceinline__ void operator()(const f32x4 (&acc)[2][2][4][2], const Unit& u, int wr, int wc, int ui, int) const {
;         const int ol_ = opaque_tid() & 63, fr = ol_ & 15, fq = ol_ >> 4;
;         const int row0 = u.pm * BM + wr * 64 + fr, col0 = u.pn * BM + wc * 32 + 8 * fq;
;         const bool cmp = (u.pn == 8 || u.pn == 9);
;         bf16_t* cb = (u.pn == 8) ? kcmp : vcmp;
;         float r_[2][4];
;         rs_read(r_, ui, wr, fr);
; #pragma unroll
;         for (int ai = 0; ai < 2; ++ai)
; #pragma unroll
;             for (int m = 0; m < 4; ++m) { const int row = row0 + ai * HALF + m * 16; const float r = r_[ai][m];
; #pragma unroll
;                 for (int bj = 0; bj < 2; ++bj) { const f32x4 v0 = acc[ai][bj][m][0] * r, v1 = acc[ai][bj][m][1] * r;
;                     u32x4 w; w.x = cvt_pk_bf16(v0[0], v0[1]); w.y = cvt_pk_bf16(v0[2], v0[3]); w.z = cvt_pk_bf16(v1[0], v1[1]); w.w = cvt_pk_bf16(v1[2], v1[3]);
;                     bf16_t* p = cmp ? cb + ((size_t)((row / T) * 2 + bj) * T + (row % T)) * 128 + wc * 32 + 8 * fq
	v_mfma_f32_16x16x32_bf16 v[64:67], v[144:147], v[162:165], v[64:67]
	v_mfma_f32_16x16x32_bf16 v[60:63], v[154:157], v[162:165], v[60:63]
	v_mfma_f32_16x16x32_bf16 v[48:51], v[144:147], v[170:173], v[48:51]
	v_mfma_f32_16x16x32_bf16 v[44:47], v[154:157], v[170:173], v[44:47]
	v_mfma_f32_16x16x32_bf16 v[32:35], v[144:147], v[178:181], v[32:35]
	v_mfma_f32_16x16x32_bf16 v[28:31], v[154:157], v[178:181], v[28:31]
	v_mfma_f32_16x16x32_bf16 v[16:19], v[144:147], v[186:189], v[16:19]
	v_mfma_f32_16x16x32_bf16 v[12:15], v[154:157], v[186:189], v[12:15]
	v_mfma_f32_16x16x32_bf16 v[64:67], v[150:153], v[166:169], v[64:67]
	v_mfma_f32_16x16x32_bf16 v[60:63], v[158:161], v[166:169], v[60:63]
	v_mfma_f32_16x16x32_bf16 v[48:51], v[150:153], v[174:177], v[48:51]
	v_mfma_f32_16x16x32_bf16 v[44:47], v[158:161], v[174:177], v[44:47]
	v_mfma_f32_16x16x32_bf16 v[32:35], v[150:153], v[182:185], v[32:35]
	v_mfma_f32_16x16x32_bf16 v[28:31], v[158:161], v[182:185], v[28:31]
	v_mfma_f32_16x16x32_bf16 v[16:19], v[150:153], v[190:193], v[16:19]
	v_mfma_f32_16x16x32_bf16 v[12:15], v[158:161], v[190:193], v[12:15]
	v_mfma_f32_16x16x32_bf16 v[56:59], v[194:197], v[162:165], v[56:59]
	v_mfma_f32_16x16x32_bf16 v[52:55], v[202:205], v[162:165], v[52:55]
	v_mfma_f32_16x16x32_bf16 v[40:43], v[194:197], v[170:173], v[40:43]
	v_mfma_f32_16x16x32_bf16 v[36:39], v[202:205], v[170:173], v[36:39]
	v_mfma_f32_16x16x32_bf16 v[24:27], v[194:197], v[178:181], v[24:27]
	v_mfma_f32_16x16x32_bf16 v[20:23], v[202:205], v[178:181], v[20:23]
	v_mfma_f32_16x16x32_bf16 v[8:11], v[194:197], v[186:189], v[8:11]
	v_mfma_f32_16x16x32_bf16 v[4:7], v[202:205], v[186:189], v[4:7]
	v_mfma_f32_16x16x32_bf16 v[56:59], v[198:201], v[166:169], v[56:59]
	v_mfma_f32_16x16x32_bf16 v[52:55], v[206:209], v[166:169], v[52:55]
	v_mfma_f32_16x16x32_bf16 v[40:43], v[198:201], v[174:177], v[40:43]
	v_mfma_f32_16x16x32_bf16 v[36:39], v[206:209], v[174:177], v[36:39]
	v_mfma_f32_16x16x32_bf16 v[24:27], v[198:201], v[182:185], v[24:27]
	v_mfma_f32_16x16x32_bf16 v[20:23], v[206:209], v[182:185], v[20:23]
	v_mfma_f32_16x16x32_bf16 v[8:11], v[198:201], v[190:193], v[8:11]
	v_mfma_f32_16x16x32_bf16 v[4:7], v[206:209], v[190:193], v[4:7]
	s_barrier
	s_cbranch_scc0 .LBB0_352
	s_setprio 0
	s_waitcnt vmcnt(0)
	s_lshl_b32 s1, s50, 8
	s_lshl_b32 s6, s44, 8
	s_add_i32 s1, s1, s38
	s_or_b32 s6, s6, s39
	s_cmp_eq_u32 s44, 8
	s_mov_b32 s7, 0x3bcb0000
	s_cselect_b32 s15, s7, 0x3ccb4000
	s_lshl_b32 s7, s45, 10
	v_mov_b32_e32 v2, v0
	s_and_b32 s7, s7, 0x400
	s_add_i32 s7, s46, s7
	v_and_b32_e32 v144, 15, v2
	v_or_b32_e32 v148, s1, v144
	v_lshl_add_u32 v144, v144, 2, s7
	v_lshrrev_b32_e32 v2, 1, v2
	ds_read2_b32 v[164:165], v144 offset1:16
	ds_read2_b32 v[160:161], v144 offset0:32 offset1:48
	ds_read2_b32 v[156:157], v144 offset0:128 offset1:144
	ds_read2_b32 v[152:153], v144 offset0:160 offset1:176
	v_and_b32_e32 v2, 24, v2
	v_or_b32_e32 v146, s6, v2
	s_and_b32 s6, s44, -2
	s_cmp_lg_u32 s6, 8
	s_cselect_b64 s[6:7], -1, 0
	s_add_u32 s24, s47, s15
	s_waitcnt lgkmcnt(0)
	v_mov_b32_e32 v162, v165
	v_mov_b32_e32 v158, v161
	v_mov_b32_e32 v154, v157
	v_mov_b32_e32 v144, v153
	v_ashrrev_i32_e32 v147, 31, v146
	s_addc_u32 s25, s48, 0
	s_mov_b64 s[20:21], -1
	s_and_b64 vcc, exec, s[6:7]
	s_cbranch_vccz .LBB0_355
	v_mov_b64_e32 v[150:151], s[92:93]
	s_movk_i32 s15, 0x3600
	v_mad_i64_i32 v[150:151], s[20:21], v148, s15, v[150:151]
	v_lshl_add_u64 v[170:171], v[146:147], 1, v[150:151]
	s_mov_b64 s[20:21], 0

; #define PG8_STAGE(bufoff, gbase, voff) do { _Pragma("unroll") for (int _i = 0; _i < 2; ++_i) \
;         __builtin_amdgcn_global_load_lds((const unsigned*)((const char*)(gbase) + (voff)[_i]), (LAS unsigned*)(lds + (bufoff) + ldsw + _i * 8192), 16, 0, 0); } while (0)
; #define PG8_WAIT_V(n) asm volatile("s_waitcnt vmcnt(" #n ")" ::: "memory")
; #define PG8_BAR __builtin_amdgcn_s_barrier()
; template <class Epi, class Sched>
; __device__ __forceinline__ void gemm_phase(LAS unsigned char* lds, const Gemm g, const Sched& S, const Epi& E) {
;     ...
;     PG8_STAGE(PG8_SB(0, 0), cB, voffB); PG8_STAGE(PG8_SA(0, 0), cA, voffA); PG8_STAGE(PG8_SB(0, 1), cB + hstepB, voffB); PG8_STAGE(PG8_SA(0, 1), cA + hstepA, voffA);
;     if (wr == 1) PG8_BAR;
;     PG8_WAIT_V(4); PG8_BAR;
;     PG8_STAGE(PG8_SB(1, 0), cB + kstep, voffB); PG8_STAGE(PG8_SA(1, 0), cA + kstep, voffA); PG8_STAGE(PG8_SB(1, 1), cB + hstepB + kstep, voffB);
;     PG8_WAIT_V(6); PG8_BAR;
.LBB0_483:
	s_lshl_b32 s60, s6, 6
	v_and_b32_e32 v18, 48, v1
	s_lshl_b32 s1, s6, 13
	v_lshlrev_b32_e32 v19, 6, v1
	s_movk_i32 s6, 0x3c0
	v_lshlrev_b32_e32 v1, 2, v1
	v_and_or_b32 v18, v19, s6, v18
	v_and_b32_e32 v1, 32, v1
	v_bitop3_b32 v19, v18, s1, v1 bitop3:0xde
	s_lshl_b32 s1, s7, 5
	s_and_b32 s61, s1, 0x60
	s_add_i32 m0, s30, 0x18000
	v_lshl_add_u64 v[10:11], v[10:11], 0, s[8:9]
	s_lshl_b32 s1, s61, 7
	s_waitcnt vmcnt(2)
	s_barrier
	global_load_lds_dwordx4 v[10:11], off
	v_lshl_add_u64 v[8:9], v[8:9], 0, s[8:9]
	s_add_i32 m0, s30, 0x1a000
	s_add_i32 s62, s30, 0x8000
	s_add_i32 s63, s30, 0xa000
	global_load_lds_dwordx4 v[8:9], off
	v_lshl_add_u64 v[6:7], v[6:7], 0, s[8:9]
	s_mov_b32 m0, s62
	s_add_u32 s6, s44, 0x100080
	global_load_lds_dwordx4 v[6:7], off
	v_lshl_add_u64 v[4:5], v[4:5], 0, s[8:9]
	s_mov_b32 m0, s63
	s_addc_u32 s7, s45, 0
	global_load_lds_dwordx4 v[4:5], off
	s_add_i32 m0, s30, 0x1c000
	v_lshl_add_u64 v[4:5], s[6:7], 0, v[2:3]
	global_load_lds_dwordx4 v[4:5], off
	v_lshl_add_u64 v[4:5], s[6:7], 0, v[136:137]
	s_add_i32 m0, s30, 0x1e000
	v_bitop3_b32 v1, s1, v18, v1 bitop3:0xf6
	global_load_lds_dwordx4 v[4:5], off
	v_lshlrev_b32_e32 v4, 15, v12
	v_and_b32_e32 v4, 0xffff0000, v4
	v_lshl_add_u32 v4, v13, 12, v4
	v_and_b32_e32 v5, 1, v12
	v_lshl_or_b32 v4, v5, 6, v4
	v_lshl_add_u32 v138, v14, 1, v4
	v_lshlrev_b32_e32 v4, 15, v15
	s_lshl_b32 s1, s20, 13
	v_and_b32_e32 v4, 0xffff0000, v4
	s_add_i32 s6, s35, s1
	s_mov_b32 s7, s3
	v_readlane_b32 s48, v252, 0
	s_waitcnt vmcnt(0)
	v_lshl_add_u32 v4, v16, 12, v4
	v_and_b32_e32 v5, 1, v15
	s_lshl_b64 s[6:7], s[6:7], 2
	v_readlane_b32 s50, v252, 2
	v_lshl_or_b32 v4, v5, 6, v4
	v_readlane_b32 s51, v252, 3
	s_add_u32 s46, s50, s6
	v_mov_b32_e32 v139, v3
	v_lshl_add_u32 v140, v17, 1, v4
	v_mov_b32_e32 v141, v3
	s_addc_u32 s47, s51, s7
	s_mov_b32 s1, 0
	v_add_u32_e32 v156, 0, v19
	s_mov_b64 s[6:7], s[44:45]
	s_mov_b32 s64, 0
	s_barrier
	v_readlane_b32 s49, v252, 1

; #define PG8_STAGE(bufoff, gbase, voff) do { _Pragma("unroll") for (int _i = 0; _i < 2; ++_i) \
;         __builtin_amdgcn_global_load_lds((const unsigned*)((const char*)(gbase) + (voff)[_i]), (LAS unsigned*)(lds + (bufoff) + ldsw + _i * 8192), 16, 0, 0); } while (0)
; #define PG8_LDA(dst, b, h) do { _Pragma("unroll") for (int m = 0; m < 4; ++m) _Pragma("unroll") for (int k = 0; k < 2; ++k) dst[m][k] = *(const LAS bf16x8*)(lds + PG8_SA(b, h) + aoff + m * 2048 + k * 1024); } while (0)
; #define PG8_LDB(dst, b, h) do { _Pragma("unroll") for (int n = 0; n < 2; ++n) _Pragma("unroll") for (int k = 0; k < 2; ++k) dst[n][k] = *(const LAS bf16x8*)(lds + PG8_SB(b, h) + boff + n * 2048 + k * 1024); } while (0)
; #define PG8_WAIT_V(n) asm volatile("s_waitcnt vmcnt(" #n ")" ::: "memory")
; #define PG8_WAIT_L(n) asm volatile("s_waitcnt lgkmcnt(" #n ")" ::: "memory")
; #define PG8_BAR __builtin_amdgcn_s_barrier()
; #define PG8_SCHED __builtin_amdgcn_sched_barrier(0)
; template <class Epi, class Sched>
; __device__ __forceinline__ void gemm_phase(LAS unsigned char* lds, const Gemm g, const Sched& S, const Epi& E) {
;     ...
;         const bool has_next = S.next(ui + 1, nxt);
;         const char* nA = has_next ? (const char*)g.A + (size_t)nxt.pm * tstepA : cA; const char* nB = has_next ? (const char*)g.Bt + (size_t)nxt.pn * tstepB : cB;
;         for (int t = 0; t < nt; t += 2) {
;             const bool last = (t == nt - 2);
;             const char* a1 = cA + (size_t)(t + 1) * kstep;
;             const char* a2 = last ? nA : cA + (size_t)(t + 2) * kstep; const char* b2 = last ? nB : cB + (size_t)(t + 2) * kstep;
;             const char* a3 = a2 + kstep; const char* b3 = b2 + kstep;
;             if (last && has_next) S.a_ready(nxt);
;             PG8_LDB(B0, 0, 0); PG8_SCHED; PG8_LDA(At, 0, 0); PG8_STAGE(PG8_SA(1, 1), a1 + hstepA, voffA);
;             PG8_WAIT_L(8); PG8_BAR; PG8_WAIT_L(0); PG8_MMA(0, 0, At, B0); PG8_BAR; PG8_SCHED;
;             PG8_LDB(B1, 0, 1); PG8_STAGE(PG8_SB(0, 0), b2, voffB);
;             PG8_BAR; PG8_WAIT_L(0); PG8_MMA(0, 1, At, B1); PG8_BAR;
;             PG8_LDA(At, 0, 1); PG8_STAGE(PG8_SA(0, 0), a2, voffA);
;             PG8_BAR; PG8_WAIT_L(0); PG8_MMA(1, 0, At, B0); PG8_BAR; PG8_SCHED;
;             PG8_STAGE(PG8_SB(0, 1), b2 + hstepB, voffB);
;             PG8_WAIT_V(6); PG8_BAR; PG8_MMA(1, 1, At, B1); PG8_BAR;
.LBB0_490:
	s_ashr_i32 s53, s52, 31
	s_lshl_b64 s[18:19], s[52:53], 20
	s_add_u32 s54, s25, s18
	v_cmp_lt_i64_e64 s[14:15], s[14:15], 16
	s_addc_u32 s55, s28, s19
	s_and_b64 s[18:19], s[14:15], exec
	s_cselect_b32 s18, s55, s5
	s_cselect_b32 s19, s54, s4
	s_ashr_i32 s51, s50, 31
	s_lshl_b64 s[56:57], s[50:51], 21
	s_add_u32 s56, s44, s56
	s_addc_u32 s57, s45, s57
	s_and_b64 s[14:15], s[14:15], exec
	s_cselect_b32 s51, s57, s7
	s_cselect_b32 s53, s56, s6
	s_add_u32 s4, s4, 0x80080
	s_addc_u32 s5, s5, 0
	s_add_u32 s65, s6, 0x100
	s_addc_u32 s66, s7, 0
	s_mov_b32 s67, -2
	s_waitcnt lgkmcnt(0)
	s_setprio 0
	s_add_u32 s6, s4, 0xfff80080
	s_addc_u32 s7, s5, -1
	s_add_i32 s68, 0, 0x10000
	v_add_u32_e32 v154, s68, v1
	ds_read_b128 v[142:145], v154
	ds_read_b128 v[146:149], v154 offset:1024
	ds_read_b128 v[150:153], v154 offset:2048
	ds_read_b128 v[158:161], v154 offset:3072
	s_cmp_eq_u32 s67, 60
	s_cselect_b32 s15, s18, s7
	s_cselect_b32 s14, s19, s6
	s_cselect_b32 s7, s51, s66
	s_cselect_b32 s6, s53, s65
	ds_read_b128 v[162:165], v156
	ds_read_b128 v[166:169], v156 offset:1024
	ds_read_b128 v[170:173], v156 offset:2048
	ds_read_b128 v[174:177], v156 offset:3072
	ds_read_b128 v[178:181], v156 offset:4096
	ds_read_b128 v[182:185], v156 offset:5120
	ds_read_b128 v[186:189], v156 offset:6144
	ds_read_b128 v[190:193], v156 offset:7168
	s_add_i32 s70, 0, 0x14000
	v_add_u32_e32 v154, s70, v1
	ds_read_b128 v[194:197], v154
	ds_read_b128 v[198:201], v154 offset:1024
	ds_read_b128 v[202:205], v154 offset:2048
	ds_read_b128 v[206:209], v154 offset:3072
	s_add_i32 m0, s30, 0xc000
	s_nop 0
	global_load_lds_dwordx4 v138, s[4:5]
	s_add_i32 m0, s30, 0xe000
	s_nop 0
	global_load_lds_dwordx4 v140, s[4:5]
	s_waitcnt lgkmcnt(0)
	s_setprio 1
	s_barrier
	v_mfma_f32_16x16x32_bf16 v[128:131], v[142:145], v[162:165], 0
	v_mfma_f32_16x16x32_bf16 v[124:127], v[150:153], v[162:165], 0
	v_mfma_f32_16x16x32_bf16 v[120:123], v[142:145], v[170:173], 0
	v_mfma_f32_16x16x32_bf16 v[116:119], v[150:153], v[170:173], 0
	v_mfma_f32_16x16x32_bf16 v[112:115], v[142:145], v[178:181], 0
	v_mfma_f32_16x16x32_bf16 v[108:111], v[150:153], v[178:181], 0
	v_mfma_f32_16x16x32_bf16 v[104:107], v[142:145], v[186:189], 0
	v_mfma_f32_16x16x32_bf16 v[100:103], v[150:153], v[186:189], 0
	v_mfma_f32_16x16x32_bf16 v[128:131], v[146:149], v[166:169], v[128:131]
	v_mfma_f32_16x16x32_bf16 v[124:127], v[158:161], v[166:169], v[124:127]
	v_mfma_f32_16x16x32_bf16 v[120:123], v[146:149], v[174:177], v[120:123]
	v_mfma_f32_16x16x32_bf16 v[116:119], v[158:161], v[174:177], v[116:119]
	v_mfma_f32_16x16x32_bf16 v[112:115], v[146:149], v[182:185], v[112:115]
	v_mfma_f32_16x16x32_bf16 v[108:111], v[158:161], v[182:185], v[108:111]
	v_mfma_f32_16x16x32_bf16 v[104:107], v[146:149], v[190:193], v[104:107]
	v_mfma_f32_16x16x32_bf16 v[100:103], v[158:161], v[190:193], v[100:103]
	v_mfma_f32_16x16x32_bf16 v[64:67], v[194:197], v[162:165], 0
	v_mfma_f32_16x16x32_bf16 v[60:63], v[202:205], v[162:165], 0
	v_mfma_f32_16x16x32_bf16 v[56:59], v[194:197], v[170:173], 0
	v_mfma_f32_16x16x32_bf16 v[52:55], v[202:205], v[170:173], 0
	v_mfma_f32_16x16x32_bf16 v[48:51], v[194:197], v[178:181], 0
	v_mfma_f32_16x16x32_bf16 v[44:47], v[202:205], v[178:181], 0
	v_mfma_f32_16x16x32_bf16 v[40:43], v[194:197], v[186:189], 0
	v_mfma_f32_16x16x32_bf16 v[36:39], v[202:205], v[186:189], 0
	v_mfma_f32_16x16x32_bf16 v[64:67], v[198:201], v[166:169], v[64:67]
	v_mfma_f32_16x16x32_bf16 v[60:63], v[206:209], v[166:169], v[60:63]
	v_mfma_f32_16x16x32_bf16 v[56:59], v[198:201], v[174:177], v[56:59]
	v_mfma_f32_16x16x32_bf16 v[52:55], v[206:209], v[174:177], v[52:55]
	v_mfma_f32_16x16x32_bf16 v[48:51], v[198:201], v[182:185], v[48:51]
	v_mfma_f32_16x16x32_bf16 v[44:47], v[206:209], v[182:185], v[44:47]
	v_mfma_f32_16x16x32_bf16 v[40:43], v[198:201], v[190:193], v[40:43]
	v_mfma_f32_16x16x32_bf16 v[36:39], v[206:209], v[190:193], v[36:39]
	s_barrier
	s_setprio 0
	ds_read_b128 v[162:165], v156 offset:16384
	ds_read_b128 v[166:169], v156 offset:17408
	ds_read_b128 v[170:173], v156 offset:18432
	ds_read_b128 v[174:177], v156 offset:19456
	ds_read_b128 v[178:181], v156 offset:20480
	ds_read_b128 v[182:185], v156 offset:21504
	ds_read_b128 v[186:189], v156 offset:22528
	ds_read_b128 v[190:193], v156 offset:23552
	s_add_i32 s68, s68, s29
	v_lshl_add_u64 v[154:155], s[6:7], 0, v[2:3]
	s_mov_b32 m0, s68
	v_lshl_add_u64 v[210:211], s[6:7], 0, v[136:137]
	global_load_lds_dwordx4 v[154:155], off
	s_add_i32 m0, s68, 0x2000
	s_nop 0
	global_load_lds_dwordx4 v[210:211], off
	s_mov_b32 m0, s30
	v_lshl_add_u64 v[212:213], s[14:15], 0, v[132:133]
	global_load_lds_dwordx4 v[212:213], off
	v_lshl_add_u64 v[216:217], s[14:15], 0, v[134:135]
	s_mov_b32 m0, s31
	s_nop 0
	global_load_lds_dwordx4 v[216:217], off
	s_add_u32 s68, s6, 0x100000
	s_addc_u32 s69, s7, 0
	s_add_i32 s70, s70, s29
	s_mov_b32 m0, s70
	s_nop 0
	global_load_lds_dwordx4 v2, s[68:69]
	s_add_i32 m0, s70, 0x2000
	s_nop 0
	global_load_lds_dwordx4 v136, s[68:69]
	s_waitcnt lgkmcnt(0)
	s_setprio 1
	s_barrier
; #define PG8_STAGE(bufoff, gbase, voff) do { _Pragma("unroll") for (int _i = 0; _i < 2; ++_i) \
;         __builtin_amdgcn_global_load_lds((const unsigned*)((const char*)(gbase) + (voff)[_i]), (LAS unsigned*)(lds + (bufoff) + ldsw + _i * 8192), 16, 0, 0); } while (0)
; #define PG8_LDA(dst, b, h) do { _Pragma("unroll") for (int m = 0; m < 4; ++m) _Pragma("unroll") for (int k = 0; k < 2; ++k) dst[m][k] = *(const LAS bf16x8*)(lds + PG8_SA(b, h) + aoff + m * 2048 + k * 1024); } while (0)
; #define PG8_LDB(dst, b, h) do { _Pragma("unroll") for (int n = 0; n < 2; ++n) _Pragma("unroll") for (int k = 0; k < 2; ++k) dst[n][k] = *(const LAS bf16x8*)(lds + PG8_SB(b, h) + boff + n * 2048 + k * 1024); } while (0)
; #define PG8_MMA(ai, bj, At, Bt) do { __builtin_amdgcn_s_setprio(1); _Pragma("unroll") for (int m = 0; m < 4; ++m) _Pragma("unroll") for (int n = 0; n < 2; ++n) _Pragma("unroll") for (int k = 0; k < 2; ++k) \
;         acc[ai][bj][m][n] = __builtin_amdgcn_mfma_f32_16x16x32_bf16(Bt[n][k], At[m][k], acc[ai][bj][m][n], 0, 0, 0); __builtin_amdgcn_s_setprio(0); } while (0)
; #define PG8_WAIT_V(n) asm volatile("s_waitcnt vmcnt(" #n ")" ::: "memory")
; #define PG8_WAIT_L(n) asm volatile("s_waitcnt lgkmcnt(" #n ")" ::: "memory")
; #define PG8_BAR __builtin_amdgcn_s_barrier()
; #define PG8_SCHED __builtin_amdgcn_sched_barrier(0)
; template <class Epi, class Sched>
; __device__ __forceinline__ void gemm_phase(LAS unsigned char* lds, const Gemm g, const Sched& S, const Epi& E) {
;     ...
;             PG8_WAIT_V(6); PG8_BAR; PG8_MMA(1, 1, At, B1); PG8_BAR;
;             PG8_LDB(B0, 1, 0); PG8_SCHED; PG8_LDA(At, 1, 0); PG8_STAGE(PG8_SA(0, 1), a2 + hstepA, voffA);
;             PG8_WAIT_L(8); PG8_BAR; PG8_WAIT_L(0); PG8_MMA(0, 0, At, B0); PG8_BAR; PG8_SCHED;
;             PG8_LDB(B1, 1, 1); PG8_STAGE(PG8_SB(1, 0), b3, voffB);
;             PG8_BAR; PG8_WAIT_L(0); PG8_MMA(0, 1, At, B1); PG8_BAR;
;             PG8_LDA(At, 1, 1); PG8_STAGE(PG8_SA(1, 0), a3, voffA);
;             PG8_BAR; PG8_WAIT_L(0); PG8_MMA(1, 0, At, B0); PG8_BAR; PG8_SCHED;
	v_mfma_f32_16x16x32_bf16 v[96:99], v[142:145], v[162:165], 0
	v_mfma_f32_16x16x32_bf16 v[92:95], v[150:153], v[162:165], 0
	v_mfma_f32_16x16x32_bf16 v[88:91], v[142:145], v[170:173], 0
	v_mfma_f32_16x16x32_bf16 v[84:87], v[150:153], v[170:173], 0
	v_mfma_f32_16x16x32_bf16 v[80:83], v[142:145], v[178:181], 0
	v_mfma_f32_16x16x32_bf16 v[76:79], v[150:153], v[178:181], 0
	v_mfma_f32_16x16x32_bf16 v[72:75], v[142:145], v[186:189], 0
	v_mfma_f32_16x16x32_bf16 v[68:71], v[150:153], v[186:189], 0
	v_mfma_f32_16x16x32_bf16 v[96:99], v[146:149], v[166:169], v[96:99]
	v_mfma_f32_16x16x32_bf16 v[92:95], v[158:161], v[166:169], v[92:95]
	v_mfma_f32_16x16x32_bf16 v[88:91], v[146:149], v[174:177], v[88:91]
	v_mfma_f32_16x16x32_bf16 v[84:87], v[158:161], v[174:177], v[84:87]
	v_mfma_f32_16x16x32_bf16 v[80:83], v[146:149], v[182:185], v[80:83]
	v_mfma_f32_16x16x32_bf16 v[76:79], v[158:161], v[182:185], v[76:79]
	v_mfma_f32_16x16x32_bf16 v[72:75], v[146:149], v[190:193], v[72:75]
	v_mfma_f32_16x16x32_bf16 v[68:71], v[158:161], v[190:193], v[68:71]
	v_mfma_f32_16x16x32_bf16 v[32:35], v[194:197], v[162:165], 0
	v_mfma_f32_16x16x32_bf16 v[28:31], v[202:205], v[162:165], 0
	v_mfma_f32_16x16x32_bf16 v[24:27], v[194:197], v[170:173], 0
	v_mfma_f32_16x16x32_bf16 v[20:23], v[202:205], v[170:173], 0
	v_mfma_f32_16x16x32_bf16 v[16:19], v[194:197], v[178:181], 0
	v_mfma_f32_16x16x32_bf16 v[12:15], v[202:205], v[178:181], 0
	v_mfma_f32_16x16x32_bf16 v[8:11], v[194:197], v[186:189], 0
	v_mfma_f32_16x16x32_bf16 v[4:7], v[202:205], v[186:189], 0
	v_mfma_f32_16x16x32_bf16 v[32:35], v[198:201], v[166:169], v[32:35]
	v_mfma_f32_16x16x32_bf16 v[28:31], v[206:209], v[166:169], v[28:31]
	v_mfma_f32_16x16x32_bf16 v[24:27], v[198:201], v[174:177], v[24:27]
	v_mfma_f32_16x16x32_bf16 v[20:23], v[206:209], v[174:177], v[20:23]
	v_mfma_f32_16x16x32_bf16 v[16:19], v[198:201], v[182:185], v[16:19]
	v_mfma_f32_16x16x32_bf16 v[12:15], v[206:209], v[182:185], v[12:15]
	v_mfma_f32_16x16x32_bf16 v[8:11], v[198:201], v[190:193], v[8:11]
	v_mfma_f32_16x16x32_bf16 v[4:7], v[206:209], v[190:193], v[4:7]
	s_barrier
	s_setprio 0
	s_add_i32 s68, 0, 0x18000
	v_add_u32_e32 v157, s68, v1
	ds_read_b128 v[142:145], v157
	ds_read_b128 v[146:149], v157 offset:1024
	ds_read_b128 v[150:153], v157 offset:2048
	ds_read_b128 v[158:161], v157 offset:3072
	s_add_u32 s14, s14, 0x80000
	s_addc_u32 s15, s15, 0
	ds_read_b128 v[162:165], v156 offset:32768
	ds_read_b128 v[166:169], v156 offset:33792
	ds_read_b128 v[170:173], v156 offset:34816
	ds_read_b128 v[174:177], v156 offset:35840
	ds_read_b128 v[178:181], v156 offset:36864
	ds_read_b128 v[182:185], v156 offset:37888
	ds_read_b128 v[186:189], v156 offset:38912
	ds_read_b128 v[190:193], v156 offset:39936
	s_mov_b32 m0, s38
	s_nop 0
	global_load_lds_dwordx4 v132, s[14:15]
	s_mov_b32 m0, s39
	s_nop 0
	global_load_lds_dwordx4 v134, s[14:15]
	s_add_i32 s14, 0, 0x1c000
	v_add_u32_e32 v157, s14, v1
	ds_read_b128 v[194:197], v157
	ds_read_b128 v[198:201], v157 offset:1024
	ds_read_b128 v[202:205], v157 offset:2048
	ds_read_b128 v[206:209], v157 offset:3072
	s_waitcnt lgkmcnt(0)
	s_setprio 1
	s_waitcnt vmcnt(8)
	s_barrier
	v_mfma_f32_16x16x32_bf16 v[128:131], v[142:145], v[162:165], v[128:131]
	v_mfma_f32_16x16x32_bf16 v[124:127], v[150:153], v[162:165], v[124:127]
	v_mfma_f32_16x16x32_bf16 v[120:123], v[142:145], v[170:173], v[120:123]
	v_mfma_f32_16x16x32_bf16 v[116:119], v[150:153], v[170:173], v[116:119]
	v_mfma_f32_16x16x32_bf16 v[112:115], v[142:145], v[178:181], v[112:115]
	v_mfma_f32_16x16x32_bf16 v[108:111], v[150:153], v[178:181], v[108:111]
	v_mfma_f32_16x16x32_bf16 v[104:107], v[142:145], v[186:189], v[104:107]
	v_mfma_f32_16x16x32_bf16 v[100:103], v[150:153], v[186:189], v[100:103]
	v_mfma_f32_16x16x32_bf16 v[128:131], v[146:149], v[166:169], v[128:131]
	v_mfma_f32_16x16x32_bf16 v[124:127], v[158:161], v[166:169], v[124:127]
	v_mfma_f32_16x16x32_bf16 v[120:123], v[146:149], v[174:177], v[120:123]
	v_mfma_f32_16x16x32_bf16 v[116:119], v[158:161], v[174:177], v[116:119]
	v_mfma_f32_16x16x32_bf16 v[112:115], v[146:149], v[182:185], v[112:115]
	v_mfma_f32_16x16x32_bf16 v[108:111], v[158:161], v[182:185], v[108:111]
	v_mfma_f32_16x16x32_bf16 v[104:107], v[146:149], v[190:193], v[104:107]
	v_mfma_f32_16x16x32_bf16 v[100:103], v[158:161], v[190:193], v[100:103]
	v_mfma_f32_16x16x32_bf16 v[64:67], v[194:197], v[162:165], v[64:67]
	v_mfma_f32_16x16x32_bf16 v[60:63], v[202:205], v[162:165], v[60:63]
	v_mfma_f32_16x16x32_bf16 v[56:59], v[194:197], v[170:173], v[56:59]
	v_mfma_f32_16x16x32_bf16 v[52:55], v[202:205], v[170:173], v[52:55]
	v_mfma_f32_16x16x32_bf16 v[48:51], v[194:197], v[178:181], v[48:51]
	v_mfma_f32_16x16x32_bf16 v[44:47], v[202:205], v[178:181], v[44:47]
	v_mfma_f32_16x16x32_bf16 v[40:43], v[194:197], v[186:189], v[40:43]
	v_mfma_f32_16x16x32_bf16 v[36:39], v[202:205], v[186:189], v[36:39]
	v_mfma_f32_16x16x32_bf16 v[64:67], v[198:201], v[166:169], v[64:67]
	v_mfma_f32_16x16x32_bf16 v[60:63], v[206:209], v[166:169], v[60:63]
	v_mfma_f32_16x16x32_bf16 v[56:59], v[198:201], v[174:177], v[56:59]
	v_mfma_f32_16x16x32_bf16 v[52:55], v[206:209], v[174:177], v[52:55]
	v_mfma_f32_16x16x32_bf16 v[48:51], v[198:201], v[182:185], v[48:51]
	v_mfma_f32_16x16x32_bf16 v[44:47], v[206:209], v[182:185], v[44:47]
	v_mfma_f32_16x16x32_bf16 v[40:43], v[198:201], v[190:193], v[40:43]
	v_mfma_f32_16x16x32_bf16 v[36:39], v[206:209], v[190:193], v[36:39]
	s_barrier
; #define PG8_STAGE(bufoff, gbase, voff) do { _Pragma("unroll") for (int _i = 0; _i < 2; ++_i) \
;         __builtin_amdgcn_global_load_lds((const unsigned*)((const char*)(gbase) + (voff)[_i]), (LAS unsigned*)(lds + (bufoff) + ldsw + _i * 8192), 16, 0, 0); } while (0)
; #define PG8_LDA(dst, b, h) do { _Pragma("unroll") for (int m = 0; m < 4; ++m) _Pragma("unroll") for (int k = 0; k < 2; ++k) dst[m][k] = *(const LAS bf16x8*)(lds + PG8_SA(b, h) + aoff + m * 2048 + k * 1024); } while (0)
; #define PG8_LDB(dst, b, h) do { _Pragma("unroll") for (int n = 0; n < 2; ++n) _Pragma("unroll") for (int k = 0; k < 2; ++k) dst[n][k] = *(const LAS bf16x8*)(lds + PG8_SB(b, h) + boff + n * 2048 + k * 1024); } while (0)
; #define PG8_MMA(ai, bj, At, Bt) do { __builtin_amdgcn_s_setprio(1); _Pragma("unroll") for (int m = 0; m < 4; ++m) _Pragma("unroll") for (int n = 0; n < 2; ++n) _Pragma("unroll") for (int k = 0; k < 2; ++k) \
;         acc[ai][bj][m][n] = __builtin_amdgcn_mfma_f32_16x16x32_bf16(Bt[n][k], At[m][k], acc[ai][bj][m][n], 0, 0, 0); __builtin_amdgcn_s_setprio(0); } while (0)
; #define PG8_WAIT_V(n) asm volatile("s_waitcnt vmcnt(" #n ")" ::: "memory")
; #define PG8_WAIT_L(n) asm volatile("s_waitcnt lgkmcnt(" #n ")" ::: "memory")
; #define PG8_BAR __builtin_amdgcn_s_barrier()
; #define PG8_SCHED __builtin_amdgcn_sched_barrier(0)
; template <class Epi, class Sched>
; __device__ __forceinline__ void gemm_phase(LAS unsigned char* lds, const Gemm g, const Sched& S, const Epi& E) {
;     ...
;         for (int t = 0; t < nt; t += 2) {
;             const bool last = (t == nt - 2);
;             const char* a1 = cA + (size_t)(t + 1) * kstep;
;             const char* a2 = last ? nA : cA + (size_t)(t + 2) * kstep; const char* b2 = last ? nB : cB + (size_t)(t + 2) * kstep;
;             const char* a3 = a2 + kstep; const char* b3 = b2 + kstep;
;             if (last && has_next) S.a_ready(nxt);
;             PG8_LDB(B0, 0, 0); PG8_SCHED; PG8_LDA(At, 0, 0); PG8_STAGE(PG8_SA(1, 1), a1 + hstepA, voffA);
;             PG8_WAIT_L(8); PG8_BAR; PG8_WAIT_L(0); PG8_MMA(0, 0, At, B0); PG8_BAR; PG8_SCHED;
;     ...
;             PG8_LDA(At, 1, 1); PG8_STAGE(PG8_SA(1, 0), a3, voffA);
;             PG8_BAR; PG8_WAIT_L(0); PG8_MMA(1, 0, At, B0); PG8_BAR; PG8_SCHED;
;             PG8_STAGE(PG8_SB(1, 1), b3 + hstepB, voffB);
;             PG8_WAIT_V(6); PG8_BAR; PG8_MMA(1, 1, At, B1); PG8_BAR;
	s_setprio 0
	ds_read_b128 v[162:165], v156 offset:49152
	ds_read_b128 v[166:169], v156 offset:50176
	ds_read_b128 v[170:173], v156 offset:51200
	ds_read_b128 v[174:177], v156 offset:52224
	ds_read_b128 v[178:181], v156 offset:53248
	ds_read_b128 v[182:185], v156 offset:54272
	ds_read_b128 v[186:189], v156 offset:55296
	ds_read_b128 v[190:193], v156 offset:56320
	s_add_i32 s15, s68, s29
	v_lshl_add_u64 v[154:155], v[154:155], 0, s[8:9]
	s_mov_b32 m0, s15
	s_nop 0
	global_load_lds_dwordx4 v[154:155], off
	v_lshl_add_u64 v[154:155], v[210:211], 0, s[8:9]
	s_add_i32 m0, s15, 0x2000
	s_nop 0
	global_load_lds_dwordx4 v[154:155], off
	s_mov_b32 m0, s62
	v_lshl_add_u64 v[154:155], v[212:213], 0, s[8:9]
	global_load_lds_dwordx4 v[154:155], off
	v_lshl_add_u64 v[154:155], v[216:217], 0, s[8:9]
	s_mov_b32 m0, s63
	s_nop 0
	global_load_lds_dwordx4 v[154:155], off
	s_add_u32 s6, s6, 0x100080
	s_addc_u32 s7, s7, 0
	s_add_i32 s14, s14, s29
	s_mov_b32 m0, s14
	s_nop 0
	global_load_lds_dwordx4 v2, s[6:7]
	s_add_i32 m0, s14, 0x2000
	s_nop 0
	global_load_lds_dwordx4 v136, s[6:7]
	s_add_i32 s67, s67, 2
	s_add_u32 s4, s4, 0x100
	s_addc_u32 s5, s5, 0
	s_add_u32 s65, s65, 0x100
	s_addc_u32 s66, s66, 0
	s_cmp_gt_u32 s67, 61
	s_waitcnt lgkmcnt(0)
	s_waitcnt vmcnt(6)
	s_setprio 1
	s_barrier
	v_mfma_f32_16x16x32_bf16 v[96:99], v[142:145], v[162:165], v[96:99]
	v_mfma_f32_16x16x32_bf16 v[92:95], v[150:153], v[162:165], v[92:95]
	v_mfma_f32_16x16x32_bf16 v[88:91], v[142:145], v[170:173], v[88:91]
	v_mfma_f32_16x16x32_bf16 v[84:87], v[150:153], v[170:173], v[84:87]
	v_mfma_f32_16x16x32_bf16 v[80:83], v[142:145], v[178:181], v[80:83]
	v_mfma_f32_16x16x32_bf16 v[76:79], v[150:153], v[178:181], v[76:79]
	v_mfma_f32_16x16x32_bf16 v[72:75], v[142:145], v[186:189], v[72:75]
	v_mfma_f32_16x16x32_bf16 v[68:71], v[150:153], v[186:189], v[68:71]
	v_mfma_f32_16x16x32_bf16 v[96:99], v[146:149], v[166:169], v[96:99]
	v_mfma_f32_16x16x32_bf16 v[92:95], v[158:161], v[166:169], v[92:95]
	v_mfma_f32_16x16x32_bf16 v[88:91], v[146:149], v[174:177], v[88:91]
	v_mfma_f32_16x16x32_bf16 v[84:87], v[158:161], v[174:177], v[84:87]
	v_mfma_f32_16x16x32_bf16 v[80:83], v[146:149], v[182:185], v[80:83]
	v_mfma_f32_16x16x32_bf16 v[76:79], v[158:161], v[182:185], v[76:79]
	v_mfma_f32_16x16x32_bf16 v[72:75], v[146:149], v[190:193], v[72:75]
	v_mfma_f32_16x16x32_bf16 v[68:71], v[158:161], v[190:193], v[68:71]
	v_mfma_f32_16x16x32_bf16 v[32:35], v[194:197], v[162:165], v[32:35]
	v_mfma_f32_16x16x32_bf16 v[28:31], v[202:205], v[162:165], v[28:31]
	v_mfma_f32_16x16x32_bf16 v[24:27], v[194:197], v[170:173], v[24:27]
	v_mfma_f32_16x16x32_bf16 v[20:23], v[202:205], v[170:173], v[20:23]
	v_mfma_f32_16x16x32_bf16 v[16:19], v[194:197], v[178:181], v[16:19]
	v_mfma_f32_16x16x32_bf16 v[12:15], v[202:205], v[178:181], v[12:15]
	v_mfma_f32_16x16x32_bf16 v[8:11], v[194:197], v[186:189], v[8:11]
	v_mfma_f32_16x16x32_bf16 v[4:7], v[202:205], v[186:189], v[4:7]
	v_mfma_f32_16x16x32_bf16 v[32:35], v[198:201], v[166:169], v[32:35]
	v_mfma_f32_16x16x32_bf16 v[28:31], v[206:209], v[166:169], v[28:31]
	v_mfma_f32_16x16x32_bf16 v[24:27], v[198:201], v[174:177], v[24:27]
	v_mfma_f32_16x16x32_bf16 v[20:23], v[206:209], v[174:177], v[20:23]
	v_mfma_f32_16x16x32_bf16 v[16:19], v[198:201], v[182:185], v[16:19]
	v_mfma_f32_16x16x32_bf16 v[12:15], v[206:209], v[182:185], v[12:15]
	v_mfma_f32_16x16x32_bf16 v[8:11], v[198:201], v[190:193], v[8:11]
	v_mfma_f32_16x16x32_bf16 v[4:7], v[206:209], v[190:193], v[4:7]
	s_barrier
	s_setprio 0
.LBB0_491:
	s_setprio 0
	s_add_u32 s6, s4, 0xfff80080
	s_addc_u32 s7, s5, -1
	s_add_i32 s68, 0, 0x10000
	v_add_u32_e32 v154, s68, v1
	ds_read_b128 v[142:145], v154
	ds_read_b128 v[146:149], v154 offset:1024
	ds_read_b128 v[150:153], v154 offset:2048
	ds_read_b128 v[158:161], v154 offset:3072
	s_cmp_eq_u32 s67, 60
	s_cselect_b32 s15, s18, s7
	s_cselect_b32 s14, s19, s6
	s_cselect_b32 s7, s51, s66
	s_cselect_b32 s6, s53, s65
	ds_read_b128 v[162:165], v156
	ds_read_b128 v[166:169], v156 offset:1024
	ds_read_b128 v[170:173], v156 offset:2048
	ds_read_b128 v[174:177], v156 offset:3072
	ds_read_b128 v[178:181], v156 offset:4096
	ds_read_b128 v[182:185], v156 offset:5120
	ds_read_b128 v[186:189], v156 offset:6144
	ds_read_b128 v[190:193], v156 offset:7168
	s_add_i32 s70, 0, 0x14000
	v_add_u32_e32 v154, s70, v1
	ds_read_b128 v[194:197], v154
	ds_read_b128 v[198:201], v154 offset:1024
	ds_read_b128 v[202:205], v154 offset:2048
	ds_read_b128 v[206:209], v154 offset:3072
	s_add_i32 m0, s30, 0xc000
	s_nop 0
	global_load_lds_dwordx4 v138, s[4:5]
	s_add_i32 m0, s30, 0xe000
	s_nop 0
	global_load_lds_dwordx4 v140, s[4:5]
	s_waitcnt lgkmcnt(0)
	s_setprio 1
	s_barrier
; #define PG8_STAGE(bufoff, gbase, voff) do { _Pragma("unroll") for (int _i = 0; _i < 2; ++_i) \
;         __builtin_amdgcn_global_load_lds((const unsigned*)((const char*)(gbase) + (voff)[_i]), (LAS unsigned*)(lds + (bufoff) + ldsw + _i * 8192), 16, 0, 0); } while (0)
; #define PG8_LDA(dst, b, h) do { _Pragma("unroll") for (int m = 0; m < 4; ++m) _Pragma("unroll") for (int k = 0; k < 2; ++k) dst[m][k] = *(const LAS bf16x8*)(lds + PG8_SA(b, h) + aoff + m * 2048 + k * 1024); } while (0)
; #define PG8_LDB(dst, b, h) do { _Pragma("unroll") for (int n = 0; n < 2; ++n) _Pragma("unroll") for (int k = 0; k < 2; ++k) dst[n][k] = *(const LAS bf16x8*)(lds + PG8_SB(b, h) + boff + n * 2048 + k * 1024); } while (0)
; #define PG8_MMA(ai, bj, At, Bt) do { __builtin_amdgcn_s_setprio(1); _Pragma("unroll") for (int m = 0; m < 4; ++m) _Pragma("unroll") for (int n = 0; n < 2; ++n) _Pragma("unroll") for (int k = 0; k < 2; ++k) \
;         acc[ai][bj][m][n] = __builtin_amdgcn_mfma_f32_16x16x32_bf16(Bt[n][k], At[m][k], acc[ai][bj][m][n], 0, 0, 0); __builtin_amdgcn_s_setprio(0); } while (0)
; #define PG8_WAIT_V(n) asm volatile("s_waitcnt vmcnt(" #n ")" ::: "memory")
; #define PG8_WAIT_L(n) asm volatile("s_waitcnt lgkmcnt(" #n ")" ::: "memory")
; #define PG8_BAR __builtin_amdgcn_s_barrier()
; #define PG8_SCHED __builtin_amdgcn_sched_barrier(0)
; template <class Epi, class Sched>
; __device__ __forceinline__ void gemm_phase(LAS unsigned char* lds, const Gemm g, const Sched& S, const Epi& E) {
;     ...
;             PG8_WAIT_L(8); PG8_BAR; PG8_WAIT_L(0); PG8_MMA(0, 0, At, B0); PG8_BAR; PG8_SCHED;
;             PG8_LDB(B1, 0, 1); PG8_STAGE(PG8_SB(0, 0), b2, voffB);
;             PG8_BAR; PG8_WAIT_L(0); PG8_MMA(0, 1, At, B1); PG8_BAR;
;             PG8_LDA(At, 0, 1); PG8_STAGE(PG8_SA(0, 0), a2, voffA);
;             PG8_BAR; PG8_WAIT_L(0); PG8_MMA(1, 0, At, B0); PG8_BAR; PG8_SCHED;
;             PG8_STAGE(PG8_SB(0, 1), b2 + hstepB, voffB);
;             PG8_WAIT_V(6); PG8_BAR; PG8_MMA(1, 1, At, B1); PG8_BAR;
	v_mfma_f32_16x16x32_bf16 v[128:131], v[142:145], v[162:165], v[128:131]
	v_mfma_f32_16x16x32_bf16 v[124:127], v[150:153], v[162:165], v[124:127]
	v_mfma_f32_16x16x32_bf16 v[120:123], v[142:145], v[170:173], v[120:123]
	v_mfma_f32_16x16x32_bf16 v[116:119], v[150:153], v[170:173], v[116:119]
	v_mfma_f32_16x16x32_bf16 v[112:115], v[142:145], v[178:181], v[112:115]
	v_mfma_f32_16x16x32_bf16 v[108:111], v[150:153], v[178:181], v[108:111]
	v_mfma_f32_16x16x32_bf16 v[104:107], v[142:145], v[186:189], v[104:107]
	v_mfma_f32_16x16x32_bf16 v[100:103], v[150:153], v[186:189], v[100:103]
	v_mfma_f32_16x16x32_bf16 v[128:131], v[146:149], v[166:169], v[128:131]
	v_mfma_f32_16x16x32_bf16 v[124:127], v[158:161], v[166:169], v[124:127]
	v_mfma_f32_16x16x32_bf16 v[120:123], v[146:149], v[174:177], v[120:123]
	v_mfma_f32_16x16x32_bf16 v[116:119], v[158:161], v[174:177], v[116:119]
	v_mfma_f32_16x16x32_bf16 v[112:115], v[146:149], v[182:185], v[112:115]
	v_mfma_f32_16x16x32_bf16 v[108:111], v[158:161], v[182:185], v[108:111]
	v_mfma_f32_16x16x32_bf16 v[104:107], v[146:149], v[190:193], v[104:107]
	v_mfma_f32_16x16x32_bf16 v[100:103], v[158:161], v[190:193], v[100:103]
	v_mfma_f32_16x16x32_bf16 v[64:67], v[194:197], v[162:165], v[64:67]
	v_mfma_f32_16x16x32_bf16 v[60:63], v[202:205], v[162:165], v[60:63]
	v_mfma_f32_16x16x32_bf16 v[56:59], v[194:197], v[170:173], v[56:59]
	v_mfma_f32_16x16x32_bf16 v[52:55], v[202:205], v[170:173], v[52:55]
	v_mfma_f32_16x16x32_bf16 v[48:51], v[194:197], v[178:181], v[48:51]
	v_mfma_f32_16x16x32_bf16 v[44:47], v[202:205], v[178:181], v[44:47]
	v_mfma_f32_16x16x32_bf16 v[40:43], v[194:197], v[186:189], v[40:43]
	v_mfma_f32_16x16x32_bf16 v[36:39], v[202:205], v[186:189], v[36:39]
	v_mfma_f32_16x16x32_bf16 v[64:67], v[198:201], v[166:169], v[64:67]
	v_mfma_f32_16x16x32_bf16 v[60:63], v[206:209], v[166:169], v[60:63]
	v_mfma_f32_16x16x32_bf16 v[56:59], v[198:201], v[174:177], v[56:59]
	v_mfma_f32_16x16x32_bf16 v[52:55], v[206:209], v[174:177], v[52:55]
	v_mfma_f32_16x16x32_bf16 v[48:51], v[198:201], v[182:185], v[48:51]
	v_mfma_f32_16x16x32_bf16 v[44:47], v[206:209], v[182:185], v[44:47]
	v_mfma_f32_16x16x32_bf16 v[40:43], v[198:201], v[190:193], v[40:43]
	v_mfma_f32_16x16x32_bf16 v[36:39], v[206:209], v[190:193], v[36:39]
	s_barrier
	s_setprio 0
	ds_read_b128 v[162:165], v156 offset:16384
	ds_read_b128 v[166:169], v156 offset:17408
	ds_read_b128 v[170:173], v156 offset:18432
	ds_read_b128 v[174:177], v156 offset:19456
	ds_read_b128 v[178:181], v156 offset:20480
	ds_read_b128 v[182:185], v156 offset:21504
	ds_read_b128 v[186:189], v156 offset:22528
	ds_read_b128 v[190:193], v156 offset:23552
	s_add_i32 s68, s68, s29
	v_lshl_add_u64 v[154:155], s[6:7], 0, v[2:3]
	s_mov_b32 m0, s68
	v_lshl_add_u64 v[210:211], s[6:7], 0, v[136:137]
	global_load_lds_dwordx4 v[154:155], off
	s_add_i32 m0, s68, 0x2000
	s_nop 0
	global_load_lds_dwordx4 v[210:211], off
	s_mov_b32 m0, s30
	v_lshl_add_u64 v[212:213], s[14:15], 0, v[132:133]
	global_load_lds_dwordx4 v[212:213], off
	v_lshl_add_u64 v[216:217], s[14:15], 0, v[134:135]
	s_mov_b32 m0, s31
	s_nop 0
	global_load_lds_dwordx4 v[216:217], off
	s_add_u32 s68, s6, 0x100000
	s_addc_u32 s69, s7, 0
	s_add_i32 s70, s70, s29
	s_mov_b32 m0, s70
	s_nop 0
	global_load_lds_dwordx4 v2, s[68:69]
	s_add_i32 m0, s70, 0x2000
	s_nop 0
	global_load_lds_dwordx4 v136, s[68:69]
	s_waitcnt lgkmcnt(0)
	s_waitcnt vmcnt(6)
	s_setprio 1
	s_barrier
	v_mfma_f32_16x16x32_bf16 v[96:99], v[142:145], v[162:165], v[96:99]
	v_mfma_f32_16x16x32_bf16 v[92:95], v[150:153], v[162:165], v[92:95]
	v_mfma_f32_16x16x32_bf16 v[88:91], v[142:145], v[170:173], v[88:91]
	v_mfma_f32_16x16x32_bf16 v[84:87], v[150:153], v[170:173], v[84:87]
	v_mfma_f32_16x16x32_bf16 v[80:83], v[142:145], v[178:181], v[80:83]
	v_mfma_f32_16x16x32_bf16 v[76:79], v[150:153], v[178:181], v[76:79]
	v_mfma_f32_16x16x32_bf16 v[72:75], v[142:145], v[186:189], v[72:75]
	v_mfma_f32_16x16x32_bf16 v[68:71], v[150:153], v[186:189], v[68:71]
	v_mfma_f32_16x16x32_bf16 v[96:99], v[146:149], v[166:169], v[96:99]
	v_mfma_f32_16x16x32_bf16 v[92:95], v[158:161], v[166:169], v[92:95]
	v_mfma_f32_16x16x32_bf16 v[88:91], v[146:149], v[174:177], v[88:91]
	v_mfma_f32_16x16x32_bf16 v[84:87], v[158:161], v[174:177], v[84:87]
	v_mfma_f32_16x16x32_bf16 v[80:83], v[146:149], v[182:185], v[80:83]
	v_mfma_f32_16x16x32_bf16 v[76:79], v[158:161], v[182:185], v[76:79]
	v_mfma_f32_16x16x32_bf16 v[72:75], v[146:149], v[190:193], v[72:75]
	v_mfma_f32_16x16x32_bf16 v[68:71], v[158:161], v[190:193], v[68:71]
	v_mfma_f32_16x16x32_bf16 v[32:35], v[194:197], v[162:165], v[32:35]
	v_mfma_f32_16x16x32_bf16 v[28:31], v[202:205], v[162:165], v[28:31]
	v_mfma_f32_16x16x32_bf16 v[24:27], v[194:197], v[170:173], v[24:27]
	v_mfma_f32_16x16x32_bf16 v[20:23], v[202:205], v[170:173], v[20:23]
	v_mfma_f32_16x16x32_bf16 v[16:19], v[194:197], v[178:181], v[16:19]
	v_mfma_f32_16x16x32_bf16 v[12:15], v[202:205], v[178:181], v[12:15]
	v_mfma_f32_16x16x32_bf16 v[8:11], v[194:197], v[186:189], v[8:11]
	v_mfma_f32_16x16x32_bf16 v[4:7], v[202:205], v[186:189], v[4:7]
	v_mfma_f32_16x16x32_bf16 v[32:35], v[198:201], v[166:169], v[32:35]
	v_mfma_f32_16x16x32_bf16 v[28:31], v[206:209], v[166:169], v[28:31]
	v_mfma_f32_16x16x32_bf16 v[24:27], v[198:201], v[174:177], v[24:27]
	v_mfma_f32_16x16x32_bf16 v[20:23], v[206:209], v[174:177], v[20:23]
	v_mfma_f32_16x16x32_bf16 v[16:19], v[198:201], v[182:185], v[16:19]
	v_mfma_f32_16x16x32_bf16 v[12:15], v[206:209], v[182:185], v[12:15]
	v_mfma_f32_16x16x32_bf16 v[8:11], v[198:201], v[190:193], v[8:11]
	v_mfma_f32_16x16x32_bf16 v[4:7], v[206:209], v[190:193], v[4:7]
	s_barrier
; #define PG8_STAGE(bufoff, gbase, voff) do { _Pragma("unroll") for (int _i = 0; _i < 2; ++_i) \
;         __builtin_amdgcn_global_load_lds((const unsigned*)((const char*)(gbase) + (voff)[_i]), (LAS unsigned*)(lds + (bufoff) + ldsw + _i * 8192), 16, 0, 0); } while (0)
; #define PG8_LDA(dst, b, h) do { _Pragma("unroll") for (int m = 0; m < 4; ++m) _Pragma("unroll") for (int k = 0; k < 2; ++k) dst[m][k] = *(const LAS bf16x8*)(lds + PG8_SA(b, h) + aoff + m * 2048 + k * 1024); } while (0)
; #define PG8_LDB(dst, b, h) do { _Pragma("unroll") for (int n = 0; n < 2; ++n) _Pragma("unroll") for (int k = 0; k < 2; ++k) dst[n][k] = *(const LAS bf16x8*)(lds + PG8_SB(b, h) + boff + n * 2048 + k * 1024); } while (0)
; #define PG8_MMA(ai, bj, At, Bt) do { __builtin_amdgcn_s_setprio(1); _Pragma("unroll") for (int m = 0; m < 4; ++m) _Pragma("unroll") for (int n = 0; n < 2; ++n) _Pragma("unroll") for (int k = 0; k < 2; ++k) \
;         acc[ai][bj][m][n] = __builtin_amdgcn_mfma_f32_16x16x32_bf16(Bt[n][k], At[m][k], acc[ai][bj][m][n], 0, 0, 0); __builtin_amdgcn_s_setprio(0); } while (0)
; #define PG8_WAIT_L(n) asm volatile("s_waitcnt lgkmcnt(" #n ")" ::: "memory")
; #define PG8_BAR __builtin_amdgcn_s_barrier()
; #define PG8_SCHED __builtin_amdgcn_sched_barrier(0)
; template <class Epi, class Sched>
; __device__ __forceinline__ void gemm_phase(LAS unsigned char* lds, const Gemm g, const Sched& S, const Epi& E) {
;     ...
;             PG8_LDB(B0, 1, 0); PG8_SCHED; PG8_LDA(At, 1, 0); PG8_STAGE(PG8_SA(0, 1), a2 + hstepA, voffA);
;             PG8_WAIT_L(8); PG8_BAR; PG8_WAIT_L(0); PG8_MMA(0, 0, At, B0); PG8_BAR; PG8_SCHED;
;             PG8_LDB(B1, 1, 1); PG8_STAGE(PG8_SB(1, 0), b3, voffB);
;             PG8_BAR; PG8_WAIT_L(0); PG8_MMA(0, 1, At, B1); PG8_BAR;
;             PG8_LDA(At, 1, 1); PG8_STAGE(PG8_SA(1, 0), a3, voffA);
;             PG8_BAR; PG8_WAIT_L(0); PG8_MMA(1, 0, At, B0); PG8_BAR; PG8_SCHED;
	s_setprio 0
	s_add_i32 s68, 0, 0x18000
	v_add_u32_e32 v157, s68, v1
	ds_read_b128 v[142:145], v157
	ds_read_b128 v[146:149], v157 offset:1024
	ds_read_b128 v[150:153], v157 offset:2048
	ds_read_b128 v[158:161], v157 offset:3072
	s_add_u32 s14, s14, 0x80000
	s_addc_u32 s15, s15, 0
	ds_read_b128 v[162:165], v156 offset:32768
	ds_read_b128 v[166:169], v156 offset:33792
	ds_read_b128 v[170:173], v156 offset:34816
	ds_read_b128 v[174:177], v156 offset:35840
	ds_read_b128 v[178:181], v156 offset:36864
	ds_read_b128 v[182:185], v156 offset:37888
	ds_read_b128 v[186:189], v156 offset:38912
	ds_read_b128 v[190:193], v156 offset:39936
	s_mov_b32 m0, s38
	s_nop 0
	global_load_lds_dwordx4 v132, s[14:15]
	s_mov_b32 m0, s39
	s_nop 0
	global_load_lds_dwordx4 v134, s[14:15]
	s_add_i32 s14, 0, 0x1c000
	v_add_u32_e32 v157, s14, v1
	ds_read_b128 v[194:197], v157
	ds_read_b128 v[198:201], v157 offset:1024
	ds_read_b128 v[202:205], v157 offset:2048
	ds_read_b128 v[206:209], v157 offset:3072
	s_waitcnt lgkmcnt(0)
	s_setprio 1
	s_barrier
	v_mfma_f32_16x16x32_bf16 v[128:131], v[142:145], v[162:165], v[128:131]
	v_mfma_f32_16x16x32_bf16 v[124:127], v[150:153], v[162:165], v[124:127]
	v_mfma_f32_16x16x32_bf16 v[120:123], v[142:145], v[170:173], v[120:123]
	v_mfma_f32_16x16x32_bf16 v[116:119], v[150:153], v[170:173], v[116:119]
	v_mfma_f32_16x16x32_bf16 v[112:115], v[142:145], v[178:181], v[112:115]
	v_mfma_f32_16x16x32_bf16 v[108:111], v[150:153], v[178:181], v[108:111]
	v_mfma_f32_16x16x32_bf16 v[104:107], v[142:145], v[186:189], v[104:107]
	v_mfma_f32_16x16x32_bf16 v[100:103], v[150:153], v[186:189], v[100:103]
	v_mfma_f32_16x16x32_bf16 v[128:131], v[146:149], v[166:169], v[128:131]
	v_mfma_f32_16x16x32_bf16 v[124:127], v[158:161], v[166:169], v[124:127]
	v_mfma_f32_16x16x32_bf16 v[120:123], v[146:149], v[174:177], v[120:123]
	v_mfma_f32_16x16x32_bf16 v[116:119], v[158:161], v[174:177], v[116:119]
	v_mfma_f32_16x16x32_bf16 v[112:115], v[146:149], v[182:185], v[112:115]
	v_mfma_f32_16x16x32_bf16 v[108:111], v[158:161], v[182:185], v[108:111]
	v_mfma_f32_16x16x32_bf16 v[104:107], v[146:149], v[190:193], v[104:107]
	v_mfma_f32_16x16x32_bf16 v[100:103], v[158:161], v[190:193], v[100:103]
	v_mfma_f32_16x16x32_bf16 v[64:67], v[194:197], v[162:165], v[64:67]
	v_mfma_f32_16x16x32_bf16 v[60:63], v[202:205], v[162:165], v[60:63]
	v_mfma_f32_16x16x32_bf16 v[56:59], v[194:197], v[170:173], v[56:59]
	v_mfma_f32_16x16x32_bf16 v[52:55], v[202:205], v[170:173], v[52:55]
	v_mfma_f32_16x16x32_bf16 v[48:51], v[194:197], v[178:181], v[48:51]
	v_mfma_f32_16x16x32_bf16 v[44:47], v[202:205], v[178:181], v[44:47]
	v_mfma_f32_16x16x32_bf16 v[40:43], v[194:197], v[186:189], v[40:43]
	v_mfma_f32_16x16x32_bf16 v[36:39], v[202:205], v[186:189], v[36:39]
	v_mfma_f32_16x16x32_bf16 v[64:67], v[198:201], v[166:169], v[64:67]
	v_mfma_f32_16x16x32_bf16 v[60:63], v[206:209], v[166:169], v[60:63]
	v_mfma_f32_16x16x32_bf16 v[56:59], v[198:201], v[174:177], v[56:59]
	v_mfma_f32_16x16x32_bf16 v[52:55], v[206:209], v[174:177], v[52:55]
	v_mfma_f32_16x16x32_bf16 v[48:51], v[198:201], v[182:185], v[48:51]
	v_mfma_f32_16x16x32_bf16 v[44:47], v[206:209], v[182:185], v[44:47]
	v_mfma_f32_16x16x32_bf16 v[40:43], v[198:201], v[190:193], v[40:43]
	v_mfma_f32_16x16x32_bf16 v[36:39], v[206:209], v[190:193], v[36:39]
	s_barrier
; #define PG8_STAGE(bufoff, gbase, voff) do { _Pragma("unroll") for (int _i = 0; _i < 2; ++_i) \
;         __builtin_amdgcn_global_load_lds((const unsigned*)((const char*)(gbase) + (voff)[_i]), (LAS unsigned*)(lds + (bufoff) + ldsw + _i * 8192), 16, 0, 0); } while (0)
; #define PG8_LDA(dst, b, h) do { _Pragma("unroll") for (int m = 0; m < 4; ++m) _Pragma("unroll") for (int k = 0; k < 2; ++k) dst[m][k] = *(const LAS bf16x8*)(lds + PG8_SA(b, h) + aoff + m * 2048 + k * 1024); } while (0)
; #define PG8_MMA(ai, bj, At, Bt) do { __builtin_amdgcn_s_setprio(1); _Pragma("unroll") for (int m = 0; m < 4; ++m) _Pragma("unroll") for (int n = 0; n < 2; ++n) _Pragma("unroll") for (int k = 0; k < 2; ++k) \
;         acc[ai][bj][m][n] = __builtin_amdgcn_mfma_f32_16x16x32_bf16(Bt[n][k], At[m][k], acc[ai][bj][m][n], 0, 0, 0); __builtin_amdgcn_s_setprio(0); } while (0)
; #define PG8_WAIT_V(n) asm volatile("s_waitcnt vmcnt(" #n ")" ::: "memory")
; #define PG8_WAIT_L(n) asm volatile("s_waitcnt lgkmcnt(" #n ")" ::: "memory")
; #define PG8_BAR __builtin_amdgcn_s_barrier()
; #define PG8_SCHED __builtin_amdgcn_sched_barrier(0)
; template <class Epi, class Sched>
; __device__ __forceinline__ void gemm_phase(LAS unsigned char* lds, const Gemm g, const Sched& S, const Epi& E) {
;     ...
;             PG8_LDA(At, 1, 1); PG8_STAGE(PG8_SA(1, 0), a3, voffA);
;             PG8_BAR; PG8_WAIT_L(0); PG8_MMA(1, 0, At, B0); PG8_BAR; PG8_SCHED;
;             PG8_STAGE(PG8_SB(1, 1), b3 + hstepB, voffB);
;             PG8_WAIT_V(6); PG8_BAR; PG8_MMA(1, 1, At, B1); PG8_BAR;
;         }
;         E(acc, cur, wr, wc, ui, fq);
;     __device__ __forceinline__ void operator()(const f32x4 (&acc)[2][2][4][2], const Unit& u, int wr, int wc, int, int) const {
;     ...
; #pragma unroll
;         for (int bj = 0; bj < 2; ++bj) { f32x4 b0 = (f32x4){0.f, 0.f, 0.f, 0.f}, b1 = b0;
; #pragma unroll 8
;             for (int pp = 0; pp < 32; ++pp) { b0 += *(const f32x4*)(bias + pp * 256 + col0 + bj * HALF); b1 += *(const f32x4*)(bias + pp * 256 + col0 + bj * HALF + 4); }
	s_setprio 0
	ds_read_b128 v[162:165], v156 offset:49152
	ds_read_b128 v[166:169], v156 offset:50176
	ds_read_b128 v[170:173], v156 offset:51200
	ds_read_b128 v[174:177], v156 offset:52224
	ds_read_b128 v[178:181], v156 offset:53248
	ds_read_b128 v[182:185], v156 offset:54272
	ds_read_b128 v[186:189], v156 offset:55296
	ds_read_b128 v[190:193], v156 offset:56320
	s_add_i32 s15, s68, s29
	v_lshl_add_u64 v[154:155], v[154:155], 0, s[8:9]
	s_mov_b32 m0, s15
	s_nop 0
	global_load_lds_dwordx4 v[154:155], off
	v_lshl_add_u64 v[154:155], v[210:211], 0, s[8:9]
	s_add_i32 m0, s15, 0x2000
	s_nop 0
	global_load_lds_dwordx4 v[154:155], off
	s_mov_b32 m0, s62
	v_lshl_add_u64 v[154:155], v[212:213], 0, s[8:9]
	global_load_lds_dwordx4 v[154:155], off
	v_lshl_add_u64 v[154:155], v[216:217], 0, s[8:9]
	s_mov_b32 m0, s63
	s_nop 0
	global_load_lds_dwordx4 v[154:155], off
	s_add_u32 s6, s6, 0x100080
	s_addc_u32 s7, s7, 0
	s_add_i32 s14, s14, s29
	s_mov_b32 m0, s14
	s_nop 0
	global_load_lds_dwordx4 v2, s[6:7]
	s_add_i32 m0, s14, 0x2000
	s_nop 0
	global_load_lds_dwordx4 v136, s[6:7]
	s_add_i32 s67, s67, 2
	s_add_u32 s4, s4, 0x100
	s_addc_u32 s5, s5, 0
	s_add_u32 s65, s65, 0x100
	s_addc_u32 s66, s66, 0
	s_cmp_gt_u32 s67, 61
	s_waitcnt lgkmcnt(0)
	s_waitcnt vmcnt(6)
	s_setprio 1
	s_barrier
	v_mfma_f32_16x16x32_bf16 v[96:99], v[142:145], v[162:165], v[96:99]
	v_mfma_f32_16x16x32_bf16 v[92:95], v[150:153], v[162:165], v[92:95]
	v_mfma_f32_16x16x32_bf16 v[88:91], v[142:145], v[170:173], v[88:91]
	v_mfma_f32_16x16x32_bf16 v[84:87], v[150:153], v[170:173], v[84:87]
	v_mfma_f32_16x16x32_bf16 v[80:83], v[142:145], v[178:181], v[80:83]
	v_mfma_f32_16x16x32_bf16 v[76:79], v[150:153], v[178:181], v[76:79]
	v_mfma_f32_16x16x32_bf16 v[72:75], v[142:145], v[186:189], v[72:75]
	v_mfma_f32_16x16x32_bf16 v[68:71], v[150:153], v[186:189], v[68:71]
	v_mfma_f32_16x16x32_bf16 v[96:99], v[146:149], v[166:169], v[96:99]
	v_mfma_f32_16x16x32_bf16 v[92:95], v[158:161], v[166:169], v[92:95]
	v_mfma_f32_16x16x32_bf16 v[88:91], v[146:149], v[174:177], v[88:91]
	v_mfma_f32_16x16x32_bf16 v[84:87], v[158:161], v[174:177], v[84:87]
	v_mfma_f32_16x16x32_bf16 v[80:83], v[146:149], v[182:185], v[80:83]
	v_mfma_f32_16x16x32_bf16 v[76:79], v[158:161], v[182:185], v[76:79]
	v_mfma_f32_16x16x32_bf16 v[72:75], v[146:149], v[190:193], v[72:75]
	v_mfma_f32_16x16x32_bf16 v[68:71], v[158:161], v[190:193], v[68:71]
	v_mfma_f32_16x16x32_bf16 v[32:35], v[194:197], v[162:165], v[32:35]
	v_mfma_f32_16x16x32_bf16 v[28:31], v[202:205], v[162:165], v[28:31]
	v_mfma_f32_16x16x32_bf16 v[24:27], v[194:197], v[170:173], v[24:27]
	v_mfma_f32_16x16x32_bf16 v[20:23], v[202:205], v[170:173], v[20:23]
	v_mfma_f32_16x16x32_bf16 v[16:19], v[194:197], v[178:181], v[16:19]
	v_mfma_f32_16x16x32_bf16 v[12:15], v[202:205], v[178:181], v[12:15]
	v_mfma_f32_16x16x32_bf16 v[8:11], v[194:197], v[186:189], v[8:11]
	v_mfma_f32_16x16x32_bf16 v[4:7], v[202:205], v[186:189], v[4:7]
	v_mfma_f32_16x16x32_bf16 v[32:35], v[198:201], v[166:169], v[32:35]
	v_mfma_f32_16x16x32_bf16 v[28:31], v[206:209], v[166:169], v[28:31]
	v_mfma_f32_16x16x32_bf16 v[24:27], v[198:201], v[174:177], v[24:27]
	v_mfma_f32_16x16x32_bf16 v[20:23], v[206:209], v[174:177], v[20:23]
	v_mfma_f32_16x16x32_bf16 v[16:19], v[198:201], v[182:185], v[16:19]
	v_mfma_f32_16x16x32_bf16 v[12:15], v[206:209], v[182:185], v[12:15]
	v_mfma_f32_16x16x32_bf16 v[8:11], v[198:201], v[190:193], v[8:11]
	v_mfma_f32_16x16x32_bf16 v[4:7], v[206:209], v[190:193], v[4:7]
	s_barrier
	s_cbranch_scc0 .LBB0_491
	s_setprio 0
	s_waitcnt vmcnt(0)
	v_mov_b32_e32 v157, v0
	s_lshl_b32 s1, s1, 8
	v_lshrrev_b32_e32 v142, 1, v157
	v_and_or_b32 v142, v142, 24, s1
	v_or_b32_e32 v154, s61, v142
	v_ashrrev_i32_e32 v155, 31, v154
	v_mov_b32_e32 v144, 0
	v_lshl_add_u64 v[142:143], v[154:155], 2, s[46:47]
	s_mov_b64 s[4:5], 0
	v_mov_b32_e32 v145, v144
	v_mov_b32_e32 v146, v144
	v_mov_b32_e32 v147, v144
	v_mov_b32_e32 v148, v144
	v_mov_b32_e32 v149, v144
	v_mov_b32_e32 v150, v144
	v_mov_b32_e32 v151, v144

; #define PG8_STAGE(bufoff, gbase, voff) do { _Pragma("unroll") for (int _i = 0; _i < 2; ++_i) \
;         __builtin_amdgcn_global_load_lds((const unsigned*)((const char*)(gbase) + (voff)[_i]), (LAS unsigned*)(lds + (bufoff) + ldsw + _i * 8192), 16, 0, 0); } while (0)
; #define PG8_WAIT_V(n) asm volatile("s_waitcnt vmcnt(" #n ")" ::: "memory")
; #define PG8_BAR __builtin_amdgcn_s_barrier()
; template <class Epi, class Sched>
; __device__ __forceinline__ void gemm_phase(LAS unsigned char* lds, const Gemm g, const Sched& S, const Epi& E) {
;     ...
;     PG8_STAGE(PG8_SB(0, 0), cB, voffB); PG8_STAGE(PG8_SA(0, 0), cA, voffA); PG8_STAGE(PG8_SB(0, 1), cB + hstepB, voffB); PG8_STAGE(PG8_SA(0, 1), cA + hstepA, voffA);
;     if (wr == 1) PG8_BAR;
;     PG8_WAIT_V(4); PG8_BAR;
;     PG8_STAGE(PG8_SB(1, 0), cB + kstep, voffB); PG8_STAGE(PG8_SA(1, 0), cA + kstep, voffA); PG8_STAGE(PG8_SB(1, 1), cB + hstepB + kstep, voffB);
;     PG8_WAIT_V(6); PG8_BAR;
.LBB0_958:
	v_lshl_add_u64 v[10:11], s[20:21], 0, v[2:3]
	v_mov_b32_e32 v193, v3
	v_readlane_b32 s6, v254, 5
	s_lshl_b32 s0, s0, 5
	v_lshl_add_u64 v[12:13], s[20:21], 0, v[192:193]
	v_mov_b32_e32 v197, v3
	v_readlane_b32 s7, v254, 6
	v_and_b32_e32 v18, 48, v1
	v_lshlrev_b32_e32 v19, 6, v1
	s_movk_i32 s4, 0x3c0
	v_lshlrev_b32_e32 v1, 2, v1
	s_and_b32 s39, s0, 0x60
	s_add_i32 m0, s31, 0x18000
	v_lshl_add_u64 v[10:11], v[10:11], 0, s[8:9]
	v_lshl_add_u64 v[14:15], s[6:7], 0, v[196:197]
	v_mov_b32_e32 v195, v3
	s_lshl_b32 s38, s1, 6
	s_lshl_b32 s1, s1, 13
	v_and_or_b32 v18, v19, s4, v18
	v_and_b32_e32 v1, 32, v1
	s_lshl_b32 s0, s39, 7
	s_waitcnt vmcnt(2)
	s_barrier
	global_load_lds_dwordx4 v[10:11], off
	v_lshl_add_u64 v[10:11], v[12:13], 0, s[8:9]
	s_add_i32 m0, s31, 0x1a000
	s_add_i32 s40, s31, 0x8000
	s_add_i32 s41, s31, 0xa000
	v_lshl_add_u64 v[16:17], s[6:7], 0, v[194:195]
	v_bitop3_b32 v19, v18, s1, v1 bitop3:0xde
	v_bitop3_b32 v1, s0, v18, v1 bitop3:0xf6
	global_load_lds_dwordx4 v[10:11], off
	v_lshl_add_u64 v[10:11], v[14:15], 0, s[8:9]
	s_mov_b32 m0, s40
	s_add_u32 s0, s20, 0x80080
	global_load_lds_dwordx4 v[10:11], off
	v_lshl_add_u64 v[10:11], v[16:17], 0, s[8:9]
	s_mov_b32 m0, s41
	s_addc_u32 s1, s21, 0
	global_load_lds_dwordx4 v[10:11], off
	s_add_i32 m0, s31, 0x1c000
	v_lshl_add_u64 v[10:11], s[0:1], 0, v[2:3]
	global_load_lds_dwordx4 v[10:11], off
	v_lshl_add_u64 v[10:11], s[0:1], 0, v[192:193]
	s_add_i32 m0, s31, 0x1e000
	v_readlane_b32 s0, v254, 27
	global_load_lds_dwordx4 v[10:11], off
	v_lshlrev_b32_e32 v10, 15, v8
	v_and_b32_e32 v10, 0xffff0000, v10
	v_lshl_add_u32 v7, v7, 12, v10
	v_and_b32_e32 v8, 1, v8
	v_lshl_or_b32 v7, v8, 6, v7
	v_lshl_add_u32 v198, v9, 1, v7
	v_lshlrev_b32_e32 v7, 15, v4
	v_and_b32_e32 v7, 0xffff0000, v7
	s_waitcnt vmcnt(0)
	v_lshl_add_u32 v5, v5, 12, v7
	v_and_b32_e32 v4, 1, v4
	v_lshl_or_b32 v4, v4, 6, v5
	v_mov_b32_e32 v199, v3
	v_lshl_add_u32 v200, v6, 1, v4
	v_mov_b32_e32 v201, v3
	s_mov_b32 s44, 0
	v_add_u32_e32 v224, 0, v19
	v_readlane_b32 s45, v254, 1
	s_mov_b32 s46, s0
	s_barrier
	v_readlane_b32 s1, v254, 28

; #define PG8_STAGE(bufoff, gbase, voff) do { _Pragma("unroll") for (int _i = 0; _i < 2; ++_i) \
;         __builtin_amdgcn_global_load_lds((const unsigned*)((const char*)(gbase) + (voff)[_i]), (LAS unsigned*)(lds + (bufoff) + ldsw + _i * 8192), 16, 0, 0); } while (0)
; #define PG8_LDA(dst, b, h) do { _Pragma("unroll") for (int m = 0; m < 4; ++m) _Pragma("unroll") for (int k = 0; k < 2; ++k) dst[m][k] = *(const LAS bf16x8*)(lds + PG8_SA(b, h) + aoff + m * 2048 + k * 1024); } while (0)
; #define PG8_LDB(dst, b, h) do { _Pragma("unroll") for (int n = 0; n < 2; ++n) _Pragma("unroll") for (int k = 0; k < 2; ++k) dst[n][k] = *(const LAS bf16x8*)(lds + PG8_SB(b, h) + boff + n * 2048 + k * 1024); } while (0)
; #define PG8_WAIT_V(n) asm volatile("s_waitcnt vmcnt(" #n ")" ::: "memory")
; #define PG8_WAIT_L(n) asm volatile("s_waitcnt lgkmcnt(" #n ")" ::: "memory")
; #define PG8_BAR __builtin_amdgcn_s_barrier()
; #define PG8_SCHED __builtin_amdgcn_sched_barrier(0)
; template <class Epi, class Sched>
; __device__ __forceinline__ void gemm_phase(LAS unsigned char* lds, const Gemm g, const Sched& S, const Epi& E) {
;     ...
;         const bool has_next = S.next(ui + 1, nxt);
;         const char* nA = has_next ? (const char*)g.A + (size_t)nxt.pm * tstepA : cA; const char* nB = has_next ? (const char*)g.Bt + (size_t)nxt.pn * tstepB : cB;
;         for (int t = 0; t < nt; t += 2) {
;             const bool last = (t == nt - 2);
;             const char* a1 = cA + (size_t)(t + 1) * kstep;
;             const char* a2 = last ? nA : cA + (size_t)(t + 2) * kstep; const char* b2 = last ? nB : cB + (size_t)(t + 2) * kstep;
;             const char* a3 = a2 + kstep; const char* b3 = b2 + kstep;
;             if (last && has_next) S.a_ready(nxt);
;             PG8_LDB(B0, 0, 0); PG8_SCHED; PG8_LDA(At, 0, 0); PG8_STAGE(PG8_SA(1, 1), a1 + hstepA, voffA);
;             PG8_WAIT_L(8); PG8_BAR; PG8_WAIT_L(0); PG8_MMA(0, 0, At, B0); PG8_BAR; PG8_SCHED;
;             PG8_LDB(B1, 0, 1); PG8_STAGE(PG8_SB(0, 0), b2, voffB);
;             PG8_BAR; PG8_WAIT_L(0); PG8_MMA(0, 1, At, B1); PG8_BAR;
;             PG8_LDA(At, 0, 1); PG8_STAGE(PG8_SA(0, 0), a2, voffA);
;             PG8_BAR; PG8_WAIT_L(0); PG8_MMA(1, 0, At, B0); PG8_BAR; PG8_SCHED;
;             PG8_STAGE(PG8_SB(0, 1), b2 + hstepB, voffB);
;             PG8_WAIT_V(6); PG8_BAR; PG8_MMA(1, 1, At, B1); PG8_BAR;
.LBB0_965:
	v_mov_b64_e32 v[4:5], 0x400
	s_ashr_i32 s15, s14, 31
	v_cmp_lt_i64_e32 vcc, s[4:5], v[4:5]
	s_lshl_b64 s[4:5], s[14:15], 20
	v_readlane_b32 s48, v252, 0
	v_readlane_b32 s49, v252, 1
	s_add_u32 s4, s48, s4
	s_addc_u32 s5, s49, s5
	s_and_b64 s[18:19], vcc, exec
	s_cselect_b32 s15, s5, s7
	s_cselect_b32 s47, s4, s6
	s_ashr_i32 s1, s0, 31
	s_lshl_b64 s[18:19], s[0:1], 20
	s_add_u32 s18, s28, s18
	s_addc_u32 s19, s29, s19
	s_and_b64 s[24:25], vcc, exec
	s_cselect_b32 s1, s19, s21
	s_cselect_b32 s48, s18, s20
	s_add_u32 s6, s6, 0x80080
	s_addc_u32 s7, s7, 0
	v_readlane_b32 s50, v252, 2
	v_readlane_b32 s51, v252, 3
	s_add_u32 s49, s20, 0x100
	s_addc_u32 s50, s21, 0
	s_mov_b32 s51, -2
	s_waitcnt lgkmcnt(0)
	s_setprio 0
	s_add_u32 s20, s6, 0xfff80080
	s_addc_u32 s21, s7, -1
	s_add_i32 s52, 0, 0x10000
	v_add_u32_e32 v144, s52, v1
	ds_read_b128 v[132:135], v144
	ds_read_b128 v[136:139], v144 offset:1024
	ds_read_b128 v[140:143], v144 offset:2048
	ds_read_b128 v[144:147], v144 offset:3072
	s_cmp_eq_u32 s51, 28
	s_cselect_b32 s25, s15, s21
	s_cselect_b32 s24, s47, s20
	s_cselect_b32 s21, s1, s50
	s_cselect_b32 s20, s48, s49
	ds_read_b128 v[148:151], v224
	ds_read_b128 v[152:155], v224 offset:1024
	ds_read_b128 v[156:159], v224 offset:2048
	ds_read_b128 v[160:163], v224 offset:3072
	ds_read_b128 v[164:167], v224 offset:4096
	ds_read_b128 v[168:171], v224 offset:5120
	ds_read_b128 v[172:175], v224 offset:6144
	ds_read_b128 v[176:179], v224 offset:7168
	s_add_i32 s54, 0, 0x14000
	v_add_u32_e32 v202, s54, v1
	ds_read_b128 v[180:183], v202
	ds_read_b128 v[184:187], v202 offset:1024
	ds_read_b128 v[188:191], v202 offset:2048
	ds_read_b128 v[202:205], v202 offset:3072
	s_add_i32 m0, s31, 0xc000
	s_nop 0
	global_load_lds_dwordx4 v198, s[6:7]
	s_add_i32 m0, s31, 0xe000
	s_nop 0
	global_load_lds_dwordx4 v200, s[6:7]
	s_waitcnt lgkmcnt(0)
	s_setprio 1
	s_barrier
	v_mfma_f32_16x16x32_bf16 v[128:131], v[132:135], v[148:151], 0
	v_mfma_f32_16x16x32_bf16 v[124:127], v[140:143], v[148:151], 0
	v_mfma_f32_16x16x32_bf16 v[112:115], v[132:135], v[156:159], 0
	v_mfma_f32_16x16x32_bf16 v[108:111], v[140:143], v[156:159], 0
	v_mfma_f32_16x16x32_bf16 v[100:103], v[132:135], v[164:167], 0
	v_mfma_f32_16x16x32_bf16 v[92:95], v[140:143], v[164:167], 0
	v_mfma_f32_16x16x32_bf16 v[84:87], v[132:135], v[172:175], 0
	v_mfma_f32_16x16x32_bf16 v[76:79], v[140:143], v[172:175], 0
	v_mfma_f32_16x16x32_bf16 v[128:131], v[136:139], v[152:155], v[128:131]
	v_mfma_f32_16x16x32_bf16 v[124:127], v[144:147], v[152:155], v[124:127]
	v_mfma_f32_16x16x32_bf16 v[112:115], v[136:139], v[160:163], v[112:115]
	v_mfma_f32_16x16x32_bf16 v[108:111], v[144:147], v[160:163], v[108:111]
	v_mfma_f32_16x16x32_bf16 v[100:103], v[136:139], v[168:171], v[100:103]
	v_mfma_f32_16x16x32_bf16 v[92:95], v[144:147], v[168:171], v[92:95]
	v_mfma_f32_16x16x32_bf16 v[84:87], v[136:139], v[176:179], v[84:87]
	v_mfma_f32_16x16x32_bf16 v[76:79], v[144:147], v[176:179], v[76:79]
	v_mfma_f32_16x16x32_bf16 v[120:123], v[180:183], v[148:151], 0
	v_mfma_f32_16x16x32_bf16 v[116:119], v[188:191], v[148:151], 0
	v_mfma_f32_16x16x32_bf16 v[104:107], v[180:183], v[156:159], 0
	v_mfma_f32_16x16x32_bf16 v[96:99], v[188:191], v[156:159], 0
	v_mfma_f32_16x16x32_bf16 v[88:91], v[180:183], v[164:167], 0
	v_mfma_f32_16x16x32_bf16 v[80:83], v[188:191], v[164:167], 0
	v_mfma_f32_16x16x32_bf16 v[72:75], v[180:183], v[172:175], 0
	v_mfma_f32_16x16x32_bf16 v[68:71], v[188:191], v[172:175], 0
	v_mfma_f32_16x16x32_bf16 v[120:123], v[184:187], v[152:155], v[120:123]
	v_mfma_f32_16x16x32_bf16 v[116:119], v[202:205], v[152:155], v[116:119]
	v_mfma_f32_16x16x32_bf16 v[104:107], v[184:187], v[160:163], v[104:107]
	v_mfma_f32_16x16x32_bf16 v[96:99], v[202:205], v[160:163], v[96:99]
	v_mfma_f32_16x16x32_bf16 v[88:91], v[184:187], v[168:171], v[88:91]
	v_mfma_f32_16x16x32_bf16 v[80:83], v[202:205], v[168:171], v[80:83]
	v_mfma_f32_16x16x32_bf16 v[72:75], v[184:187], v[176:179], v[72:75]
	v_mfma_f32_16x16x32_bf16 v[68:71], v[202:205], v[176:179], v[68:71]
	s_barrier
	s_setprio 0
	ds_read_b128 v[148:151], v224 offset:16384
	ds_read_b128 v[152:155], v224 offset:17408
	ds_read_b128 v[156:159], v224 offset:18432
	ds_read_b128 v[160:163], v224 offset:19456
	ds_read_b128 v[164:167], v224 offset:20480
	ds_read_b128 v[168:171], v224 offset:21504
	ds_read_b128 v[172:175], v224 offset:22528
	ds_read_b128 v[176:179], v224 offset:23552
	s_add_i32 s52, s52, s30
	v_lshl_add_u64 v[206:207], s[20:21], 0, v[2:3]
	s_mov_b32 m0, s52
	s_nop 0
	global_load_lds_dwordx4 v[206:207], off
	v_lshl_add_u64 v[208:209], s[20:21], 0, v[192:193]
	s_add_i32 m0, s52, 0x2000
	s_nop 0
	global_load_lds_dwordx4 v[208:209], off
	s_mov_b32 m0, s31
	v_lshl_add_u64 v[210:211], s[24:25], 0, v[196:197]
	global_load_lds_dwordx4 v[210:211], off
	v_lshl_add_u64 v[212:213], s[24:25], 0, v[194:195]
	s_mov_b32 m0, s35
	s_nop 0
	global_load_lds_dwordx4 v[212:213], off
	s_add_u32 s52, s20, 0x80000
	s_addc_u32 s53, s21, 0
	s_add_i32 s54, s54, s30
	s_mov_b32 m0, s54
	s_nop 0
	global_load_lds_dwordx4 v2, s[52:53]
	s_add_i32 m0, s54, 0x2000
	s_nop 0
	global_load_lds_dwordx4 v192, s[52:53]
	s_waitcnt lgkmcnt(0)
	s_setprio 1
	s_barrier
; #define PG8_STAGE(bufoff, gbase, voff) do { _Pragma("unroll") for (int _i = 0; _i < 2; ++_i) \
;         __builtin_amdgcn_global_load_lds((const unsigned*)((const char*)(gbase) + (voff)[_i]), (LAS unsigned*)(lds + (bufoff) + ldsw + _i * 8192), 16, 0, 0); } while (0)
; #define PG8_LDA(dst, b, h) do { _Pragma("unroll") for (int m = 0; m < 4; ++m) _Pragma("unroll") for (int k = 0; k < 2; ++k) dst[m][k] = *(const LAS bf16x8*)(lds + PG8_SA(b, h) + aoff + m * 2048 + k * 1024); } while (0)
; #define PG8_LDB(dst, b, h) do { _Pragma("unroll") for (int n = 0; n < 2; ++n) _Pragma("unroll") for (int k = 0; k < 2; ++k) dst[n][k] = *(const LAS bf16x8*)(lds + PG8_SB(b, h) + boff + n * 2048 + k * 1024); } while (0)
; #define PG8_MMA(ai, bj, At, Bt) do { __builtin_amdgcn_s_setprio(1); _Pragma("unroll") for (int m = 0; m < 4; ++m) _Pragma("unroll") for (int n = 0; n < 2; ++n) _Pragma("unroll") for (int k = 0; k < 2; ++k) \
;         acc[ai][bj][m][n] = __builtin_amdgcn_mfma_f32_16x16x32_bf16(Bt[n][k], At[m][k], acc[ai][bj][m][n], 0, 0, 0); __builtin_amdgcn_s_setprio(0); } while (0)
; #define PG8_WAIT_V(n) asm volatile("s_waitcnt vmcnt(" #n ")" ::: "memory")
; #define PG8_WAIT_L(n) asm volatile("s_waitcnt lgkmcnt(" #n ")" ::: "memory")
; #define PG8_BAR __builtin_amdgcn_s_barrier()
; #define PG8_SCHED __builtin_amdgcn_sched_barrier(0)
; template <class Epi, class Sched>
; __device__ __forceinline__ void gemm_phase(LAS unsigned char* lds, const Gemm g, const Sched& S, const Epi& E) {
;     ...
;             PG8_WAIT_V(6); PG8_BAR; PG8_MMA(1, 1, At, B1); PG8_BAR;
;             PG8_LDB(B0, 1, 0); PG8_SCHED; PG8_LDA(At, 1, 0); PG8_STAGE(PG8_SA(0, 1), a2 + hstepA, voffA);
;             PG8_WAIT_L(8); PG8_BAR; PG8_WAIT_L(0); PG8_MMA(0, 0, At, B0); PG8_BAR; PG8_SCHED;
;             PG8_LDB(B1, 1, 1); PG8_STAGE(PG8_SB(1, 0), b3, voffB);
;             PG8_BAR; PG8_WAIT_L(0); PG8_MMA(0, 1, At, B1); PG8_BAR;
;             PG8_LDA(At, 1, 1); PG8_STAGE(PG8_SA(1, 0), a3, voffA);
	v_mfma_f32_16x16x32_bf16 v[64:67], v[132:135], v[148:151], 0
	v_mfma_f32_16x16x32_bf16 v[60:63], v[140:143], v[148:151], 0
	v_mfma_f32_16x16x32_bf16 v[52:55], v[132:135], v[156:159], 0
	v_mfma_f32_16x16x32_bf16 v[44:47], v[140:143], v[156:159], 0
	v_mfma_f32_16x16x32_bf16 v[36:39], v[132:135], v[164:167], 0
	v_mfma_f32_16x16x32_bf16 v[28:31], v[140:143], v[164:167], 0
	v_mfma_f32_16x16x32_bf16 v[20:23], v[132:135], v[172:175], 0
	v_mfma_f32_16x16x32_bf16 v[12:15], v[140:143], v[172:175], 0
	v_mfma_f32_16x16x32_bf16 v[64:67], v[136:139], v[152:155], v[64:67]
	v_mfma_f32_16x16x32_bf16 v[60:63], v[144:147], v[152:155], v[60:63]
	v_mfma_f32_16x16x32_bf16 v[52:55], v[136:139], v[160:163], v[52:55]
	v_mfma_f32_16x16x32_bf16 v[44:47], v[144:147], v[160:163], v[44:47]
	v_mfma_f32_16x16x32_bf16 v[36:39], v[136:139], v[168:171], v[36:39]
	v_mfma_f32_16x16x32_bf16 v[28:31], v[144:147], v[168:171], v[28:31]
	v_mfma_f32_16x16x32_bf16 v[20:23], v[136:139], v[176:179], v[20:23]
	v_mfma_f32_16x16x32_bf16 v[12:15], v[144:147], v[176:179], v[12:15]
	v_mfma_f32_16x16x32_bf16 v[56:59], v[180:183], v[148:151], 0
	v_mfma_f32_16x16x32_bf16 v[48:51], v[188:191], v[148:151], 0
	v_mfma_f32_16x16x32_bf16 v[40:43], v[180:183], v[156:159], 0
	v_mfma_f32_16x16x32_bf16 v[32:35], v[188:191], v[156:159], 0
	v_mfma_f32_16x16x32_bf16 v[24:27], v[180:183], v[164:167], 0
	v_mfma_f32_16x16x32_bf16 v[16:19], v[188:191], v[164:167], 0
	v_mfma_f32_16x16x32_bf16 v[8:11], v[180:183], v[172:175], 0
	v_mfma_f32_16x16x32_bf16 v[4:7], v[188:191], v[172:175], 0
	v_mfma_f32_16x16x32_bf16 v[56:59], v[184:187], v[152:155], v[56:59]
	v_mfma_f32_16x16x32_bf16 v[48:51], v[202:205], v[152:155], v[48:51]
	v_mfma_f32_16x16x32_bf16 v[40:43], v[184:187], v[160:163], v[40:43]
	v_mfma_f32_16x16x32_bf16 v[32:35], v[202:205], v[160:163], v[32:35]
	v_mfma_f32_16x16x32_bf16 v[24:27], v[184:187], v[168:171], v[24:27]
	v_mfma_f32_16x16x32_bf16 v[16:19], v[202:205], v[168:171], v[16:19]
	v_mfma_f32_16x16x32_bf16 v[8:11], v[184:187], v[176:179], v[8:11]
	v_mfma_f32_16x16x32_bf16 v[4:7], v[202:205], v[176:179], v[4:7]
	s_barrier
	s_setprio 0
	s_add_i32 s52, 0, 0x18000
	v_add_u32_e32 v144, s52, v1
	ds_read_b128 v[132:135], v144
	ds_read_b128 v[136:139], v144 offset:1024
	ds_read_b128 v[140:143], v144 offset:2048
	ds_read_b128 v[144:147], v144 offset:3072
	s_add_u32 s24, s24, 0x80000
	s_addc_u32 s25, s25, 0
	ds_read_b128 v[148:151], v224 offset:32768
	ds_read_b128 v[152:155], v224 offset:33792
	ds_read_b128 v[156:159], v224 offset:34816
	ds_read_b128 v[160:163], v224 offset:35840
	ds_read_b128 v[164:167], v224 offset:36864
	ds_read_b128 v[168:171], v224 offset:37888
	ds_read_b128 v[172:175], v224 offset:38912
	ds_read_b128 v[176:179], v224 offset:39936
	s_mov_b32 m0, s36
	s_nop 0
	global_load_lds_dwordx4 v196, s[24:25]
	s_mov_b32 m0, s37
	s_nop 0
	global_load_lds_dwordx4 v194, s[24:25]
	s_add_i32 s24, 0, 0x1c000
	v_add_u32_e32 v202, s24, v1
	ds_read_b128 v[180:183], v202
	ds_read_b128 v[184:187], v202 offset:1024
	ds_read_b128 v[188:191], v202 offset:2048
	ds_read_b128 v[202:205], v202 offset:3072
	s_waitcnt lgkmcnt(0)
	s_setprio 1
	s_waitcnt vmcnt(8)
	s_barrier
	v_mfma_f32_16x16x32_bf16 v[128:131], v[132:135], v[148:151], v[128:131]
	v_mfma_f32_16x16x32_bf16 v[124:127], v[140:143], v[148:151], v[124:127]
	v_mfma_f32_16x16x32_bf16 v[112:115], v[132:135], v[156:159], v[112:115]
	v_mfma_f32_16x16x32_bf16 v[108:111], v[140:143], v[156:159], v[108:111]
	v_mfma_f32_16x16x32_bf16 v[100:103], v[132:135], v[164:167], v[100:103]
	v_mfma_f32_16x16x32_bf16 v[92:95], v[140:143], v[164:167], v[92:95]
	v_mfma_f32_16x16x32_bf16 v[84:87], v[132:135], v[172:175], v[84:87]
	v_mfma_f32_16x16x32_bf16 v[76:79], v[140:143], v[172:175], v[76:79]
	v_mfma_f32_16x16x32_bf16 v[128:131], v[136:139], v[152:155], v[128:131]
	v_mfma_f32_16x16x32_bf16 v[124:127], v[144:147], v[152:155], v[124:127]
	v_mfma_f32_16x16x32_bf16 v[112:115], v[136:139], v[160:163], v[112:115]
	v_mfma_f32_16x16x32_bf16 v[108:111], v[144:147], v[160:163], v[108:111]
	v_mfma_f32_16x16x32_bf16 v[100:103], v[136:139], v[168:171], v[100:103]
	v_mfma_f32_16x16x32_bf16 v[92:95], v[144:147], v[168:171], v[92:95]
	v_mfma_f32_16x16x32_bf16 v[84:87], v[136:139], v[176:179], v[84:87]
	v_mfma_f32_16x16x32_bf16 v[76:79], v[144:147], v[176:179], v[76:79]
	v_mfma_f32_16x16x32_bf16 v[120:123], v[180:183], v[148:151], v[120:123]
	v_mfma_f32_16x16x32_bf16 v[116:119], v[188:191], v[148:151], v[116:119]
	v_mfma_f32_16x16x32_bf16 v[104:107], v[180:183], v[156:159], v[104:107]
	v_mfma_f32_16x16x32_bf16 v[96:99], v[188:191], v[156:159], v[96:99]
	v_mfma_f32_16x16x32_bf16 v[88:91], v[180:183], v[164:167], v[88:91]
	v_mfma_f32_16x16x32_bf16 v[80:83], v[188:191], v[164:167], v[80:83]
	v_mfma_f32_16x16x32_bf16 v[72:75], v[180:183], v[172:175], v[72:75]
	v_mfma_f32_16x16x32_bf16 v[68:71], v[188:191], v[172:175], v[68:71]
	v_mfma_f32_16x16x32_bf16 v[120:123], v[184:187], v[152:155], v[120:123]
	v_mfma_f32_16x16x32_bf16 v[116:119], v[202:205], v[152:155], v[116:119]
	v_mfma_f32_16x16x32_bf16 v[104:107], v[184:187], v[160:163], v[104:107]
	v_mfma_f32_16x16x32_bf16 v[96:99], v[202:205], v[160:163], v[96:99]
	v_mfma_f32_16x16x32_bf16 v[88:91], v[184:187], v[168:171], v[88:91]
	v_mfma_f32_16x16x32_bf16 v[80:83], v[202:205], v[168:171], v[80:83]
	v_mfma_f32_16x16x32_bf16 v[72:75], v[184:187], v[176:179], v[72:75]
	v_mfma_f32_16x16x32_bf16 v[68:71], v[202:205], v[176:179], v[68:71]
	s_barrier
; #define PG8_STAGE(bufoff, gbase, voff) do { _Pragma("unroll") for (int _i = 0; _i < 2; ++_i) \
;         __builtin_amdgcn_global_load_lds((const unsigned*)((const char*)(gbase) + (voff)[_i]), (LAS unsigned*)(lds + (bufoff) + ldsw + _i * 8192), 16, 0, 0); } while (0)
; #define PG8_LDA(dst, b, h) do { _Pragma("unroll") for (int m = 0; m < 4; ++m) _Pragma("unroll") for (int k = 0; k < 2; ++k) dst[m][k] = *(const LAS bf16x8*)(lds + PG8_SA(b, h) + aoff + m * 2048 + k * 1024); } while (0)
; #define PG8_MMA(ai, bj, At, Bt) do { __builtin_amdgcn_s_setprio(1); _Pragma("unroll") for (int m = 0; m < 4; ++m) _Pragma("unroll") for (int n = 0; n < 2; ++n) _Pragma("unroll") for (int k = 0; k < 2; ++k) \
;         acc[ai][bj][m][n] = __builtin_amdgcn_mfma_f32_16x16x32_bf16(Bt[n][k], At[m][k], acc[ai][bj][m][n], 0, 0, 0); __builtin_amdgcn_s_setprio(0); } while (0)
; #define PG8_WAIT_V(n) asm volatile("s_waitcnt vmcnt(" #n ")" ::: "memory")
; #define PG8_WAIT_L(n) asm volatile("s_waitcnt lgkmcnt(" #n ")" ::: "memory")
; #define PG8_BAR __builtin_amdgcn_s_barrier()
; #define PG8_SCHED __builtin_amdgcn_sched_barrier(0)
; template <class Epi, class Sched>
; __device__ __forceinline__ void gemm_phase(LAS unsigned char* lds, const Gemm g, const Sched& S, const Epi& E) {
;     ...
;             PG8_LDA(At, 1, 1); PG8_STAGE(PG8_SA(1, 0), a3, voffA);
;             PG8_BAR; PG8_WAIT_L(0); PG8_MMA(1, 0, At, B0); PG8_BAR; PG8_SCHED;
;             PG8_STAGE(PG8_SB(1, 1), b3 + hstepB, voffB);
;             PG8_WAIT_V(6); PG8_BAR; PG8_MMA(1, 1, At, B1); PG8_BAR;
	s_setprio 0
	ds_read_b128 v[148:151], v224 offset:49152
	ds_read_b128 v[152:155], v224 offset:50176
	ds_read_b128 v[156:159], v224 offset:51200
	ds_read_b128 v[160:163], v224 offset:52224
	ds_read_b128 v[164:167], v224 offset:53248
	ds_read_b128 v[168:171], v224 offset:54272
	ds_read_b128 v[172:175], v224 offset:55296
	ds_read_b128 v[176:179], v224 offset:56320
	s_add_i32 s25, s52, s30
	v_lshl_add_u64 v[206:207], v[206:207], 0, s[8:9]
	s_mov_b32 m0, s25
	s_nop 0
	global_load_lds_dwordx4 v[206:207], off
	v_lshl_add_u64 v[206:207], v[208:209], 0, s[8:9]
	s_add_i32 m0, s25, 0x2000
	s_nop 0
	global_load_lds_dwordx4 v[206:207], off
	s_mov_b32 m0, s40
	v_lshl_add_u64 v[206:207], v[210:211], 0, s[8:9]
	global_load_lds_dwordx4 v[206:207], off
	v_lshl_add_u64 v[206:207], v[212:213], 0, s[8:9]
	s_mov_b32 m0, s41
	s_nop 0
	global_load_lds_dwordx4 v[206:207], off
	s_add_u32 s20, s20, 0x80080
	s_addc_u32 s21, s21, 0
	s_add_i32 s24, s24, s30
	s_mov_b32 m0, s24
	s_nop 0
	global_load_lds_dwordx4 v2, s[20:21]
	s_add_i32 m0, s24, 0x2000
	s_nop 0
	global_load_lds_dwordx4 v192, s[20:21]
	s_add_i32 s51, s51, 2
	s_add_u32 s6, s6, 0x100
	s_addc_u32 s7, s7, 0
	s_add_u32 s49, s49, 0x100
	s_addc_u32 s50, s50, 0
	s_cmp_gt_u32 s51, 29
	s_waitcnt lgkmcnt(0)
	s_waitcnt vmcnt(6)
	s_setprio 1
	s_barrier
	v_mfma_f32_16x16x32_bf16 v[64:67], v[132:135], v[148:151], v[64:67]
	v_mfma_f32_16x16x32_bf16 v[60:63], v[140:143], v[148:151], v[60:63]
	v_mfma_f32_16x16x32_bf16 v[52:55], v[132:135], v[156:159], v[52:55]
	v_mfma_f32_16x16x32_bf16 v[44:47], v[140:143], v[156:159], v[44:47]
	v_mfma_f32_16x16x32_bf16 v[36:39], v[132:135], v[164:167], v[36:39]
	v_mfma_f32_16x16x32_bf16 v[28:31], v[140:143], v[164:167], v[28:31]
	v_mfma_f32_16x16x32_bf16 v[20:23], v[132:135], v[172:175], v[20:23]
	v_mfma_f32_16x16x32_bf16 v[12:15], v[140:143], v[172:175], v[12:15]
	v_mfma_f32_16x16x32_bf16 v[64:67], v[136:139], v[152:155], v[64:67]
	v_mfma_f32_16x16x32_bf16 v[60:63], v[144:147], v[152:155], v[60:63]
	v_mfma_f32_16x16x32_bf16 v[52:55], v[136:139], v[160:163], v[52:55]
	v_mfma_f32_16x16x32_bf16 v[44:47], v[144:147], v[160:163], v[44:47]
	v_mfma_f32_16x16x32_bf16 v[36:39], v[136:139], v[168:171], v[36:39]
	v_mfma_f32_16x16x32_bf16 v[28:31], v[144:147], v[168:171], v[28:31]
	v_mfma_f32_16x16x32_bf16 v[20:23], v[136:139], v[176:179], v[20:23]
	v_mfma_f32_16x16x32_bf16 v[12:15], v[144:147], v[176:179], v[12:15]
	v_mfma_f32_16x16x32_bf16 v[56:59], v[180:183], v[148:151], v[56:59]
	v_mfma_f32_16x16x32_bf16 v[48:51], v[188:191], v[148:151], v[48:51]
	v_mfma_f32_16x16x32_bf16 v[40:43], v[180:183], v[156:159], v[40:43]
	v_mfma_f32_16x16x32_bf16 v[32:35], v[188:191], v[156:159], v[32:35]
	v_mfma_f32_16x16x32_bf16 v[24:27], v[180:183], v[164:167], v[24:27]
	v_mfma_f32_16x16x32_bf16 v[16:19], v[188:191], v[164:167], v[16:19]
	v_mfma_f32_16x16x32_bf16 v[8:11], v[180:183], v[172:175], v[8:11]
	v_mfma_f32_16x16x32_bf16 v[4:7], v[188:191], v[172:175], v[4:7]
	v_mfma_f32_16x16x32_bf16 v[56:59], v[184:187], v[152:155], v[56:59]
	v_mfma_f32_16x16x32_bf16 v[48:51], v[202:205], v[152:155], v[48:51]
	v_mfma_f32_16x16x32_bf16 v[40:43], v[184:187], v[160:163], v[40:43]
	v_mfma_f32_16x16x32_bf16 v[32:35], v[202:205], v[160:163], v[32:35]
	v_mfma_f32_16x16x32_bf16 v[24:27], v[184:187], v[168:171], v[24:27]
	v_mfma_f32_16x16x32_bf16 v[16:19], v[202:205], v[168:171], v[16:19]
	v_mfma_f32_16x16x32_bf16 v[8:11], v[184:187], v[176:179], v[8:11]
	v_mfma_f32_16x16x32_bf16 v[4:7], v[202:205], v[176:179], v[4:7]
	s_barrier
	s_setprio 0

; __device__ __forceinline__ int opaque_tid() { int t = threadIdx.x; asm volatile("" : "+v"(t)); return t; }
; #define PG8_STAGE(bufoff, gbase, voff) do { _Pragma("unroll") for (int _i = 0; _i < 2; ++_i) \
;         __builtin_amdgcn_global_load_lds((const unsigned*)((const char*)(gbase) + (voff)[_i]), (LAS unsigned*)(lds + (bufoff) + ldsw + _i * 8192), 16, 0, 0); } while (0)
; #define PG8_BAR __builtin_amdgcn_s_barrier()
; template <class Epi, class Sched>
; __device__ __forceinline__ void gemm_phase(LAS unsigned char* lds, const Gemm g, const Sched& S, const Epi& E) {
;     const int tid = opaque_tid(), wid = __builtin_amdgcn_readfirstlane(tid >> 6), lane = tid & 63, wr = wid >> 2, wc = wid & 3, fr = lane & 15, fq = lane >> 4;
;     const int K = g.K, nt = K / BK, lda = g.lda;
;     unsigned voffA[2], voffB[2];
; #pragma unroll
;     for (int i = 0; i < 2; ++i) { int R, C; stage_rc(tid * 16 + i * 8192, R, C); const int Rb = Epi::PERM ? ((R & ~31) + perm32(R & 31)) : R;
;         voffA[i] = (unsigned)(R * lda + C) * 2u; voffB[i] = (unsigned)(Rb * K + C) * 2u; }
;     const size_t kstep = (size_t)(BK * 2);
;     const size_t hstepA = (size_t)HALF * lda * 2, hstepB = (size_t)HALF * K * 2;
;     const size_t tstepA = 2 * hstepA, tstepB = 2 * hstepB;
;     const unsigned ldsw = (unsigned)wid * 1024u;
;     const int aoff = lds_byte(wr * 64 + fr, fq * 8), boff = lds_byte(wc * 32 + fr, fq * 8);
;     ...
;     Unit cur, nxt; int ui = 0;
;     if (!S.next(0, cur)) return;
;     f32x4 acc[2][2][4][2];
; #pragma unroll
;     for (int a = 0; a < 2; ++a)
; #pragma unroll
;         for (int b = 0; b < 2; ++b)
; #pragma unroll
;             for (int m = 0; m < 4; ++m)
; #pragma unroll
;                 for (int n = 0; n < 2; ++n) acc[a][b][m][n] = (f32x4){0.f, 0.f, 0.f, 0.f};
;     bf16x8 At[4][2], B0[2][2], B1[2][2];
;     const char* cA = (const char*)g.A + (size_t)cur.pm * tstepA; const char* cB = (const char*)g.Bt + (size_t)cur.pn * tstepB;
;     S.a_ready(cur);
;     PG8_STAGE(PG8_SB(0, 0), cB, voffB); PG8_STAGE(PG8_SA(0, 0), cA, voffA); PG8_STAGE(PG8_SB(0, 1), cB + hstepB, voffB); PG8_STAGE(PG8_SA(0, 1), cA + hstepA, voffA);
;     if (wr == 1) PG8_BAR;
;     PG8_WAIT_V(4); PG8_BAR;
;     PG8_STAGE(PG8_SB(1, 0), cB + kstep, voffB); PG8_STAGE(PG8_SA(1, 0), cA + kstep, voffA); PG8_STAGE(PG8_SB(1, 1), cB + hstepB + kstep, voffB);
;     PG8_WAIT_V(6); PG8_BAR;
.LBB0_1088:
	v_readlane_b32 s18, v254, 14
	s_lshl_b32 s0, s0, 5
	v_mov_b32_e32 v137, v3
	v_readlane_b32 s19, v254, 15
	s_and_b32 s39, s0, 0x60
	s_add_i32 m0, s31, 0x18000
	v_lshl_add_u64 v[4:5], v[4:5], 0, s[8:9]
	v_lshl_add_u64 v[14:15], s[18:19], 0, v[136:137]
	v_mov_b32_e32 v135, v3
	s_lshl_b32 s38, s1, 6
	s_lshl_b32 s4, s1, 13
	s_lshl_b32 s5, s39, 7
	s_waitcnt vmcnt(2)
	s_barrier
	global_load_lds_dwordx4 v[4:5], off
	v_lshl_add_u64 v[4:5], v[6:7], 0, s[8:9]
	s_add_i32 m0, s31, 0x1a000
	s_add_i32 s42, s31, 0x8000
	s_add_i32 s43, s31, 0xa000
	v_lshl_add_u64 v[16:17], s[18:19], 0, v[134:135]
	global_load_lds_dwordx4 v[4:5], off
	v_lshl_add_u64 v[4:5], v[14:15], 0, s[8:9]
	s_mov_b32 m0, s42
	s_add_u32 s0, s20, 0x80080
	global_load_lds_dwordx4 v[4:5], off
	v_lshl_add_u64 v[4:5], v[16:17], 0, s[8:9]
	s_mov_b32 m0, s43
	s_addc_u32 s1, s21, 0
	global_load_lds_dwordx4 v[4:5], off
	s_add_i32 m0, s31, 0x1c000
	v_lshl_add_u64 v[4:5], s[0:1], 0, v[2:3]
	global_load_lds_dwordx4 v[4:5], off
	v_lshl_add_u64 v[4:5], s[0:1], 0, v[132:133]
	s_add_i32 m0, s31, 0x1e000
	s_movk_i32 s0, 0x3c0
	global_load_lds_dwordx4 v[4:5], off
	v_and_b32_e32 v4, 48, v1
	v_lshlrev_b32_e32 v5, 6, v1
	v_lshlrev_b32_e32 v1, 2, v1
	v_and_or_b32 v4, v5, s0, v4
	v_and_b32_e32 v1, 32, v1
	v_bitop3_b32 v5, v4, s4, v1 bitop3:0xde
	v_bitop3_b32 v1, s5, v4, v1 bitop3:0xf6
	v_lshlrev_b32_e32 v4, 15, v12
	v_and_b32_e32 v4, 0xffff0000, v4
	v_lshl_add_u32 v4, v11, 12, v4
	v_and_b32_e32 v6, 1, v12
	v_lshl_or_b32 v4, v6, 6, v4
	v_lshl_add_u32 v138, v13, 1, v4
	v_lshlrev_b32_e32 v4, 15, v8
	v_and_b32_e32 v4, 0xffff0000, v4
	s_waitcnt vmcnt(0)
	s_and_b32 s0, s2, 0xffffff00
	v_lshl_add_u32 v4, v9, 12, v4
	v_and_b32_e32 v6, 1, v8
	s_add_i32 s44, s0, 0
	v_lshl_or_b32 v4, v6, 6, v4
	v_readlane_b32 s0, v254, 12
	s_add_i32 s44, s44, 0x21000
	v_mov_b32_e32 v139, v3
	v_lshl_add_u32 v140, v10, 1, v4
	v_mov_b32_e32 v141, v3
	s_mov_b32 s48, 0
	v_add_u32_e32 v148, 0, v5
	v_readlane_b32 s47, v254, 9
	s_mov_b32 s46, s0
	s_barrier
	v_readlane_b32 s1, v254, 13
	s_waitcnt vmcnt(0)

; #define PG8_STAGE(bufoff, gbase, voff) do { _Pragma("unroll") for (int _i = 0; _i < 2; ++_i) \
;         __builtin_amdgcn_global_load_lds((const unsigned*)((const char*)(gbase) + (voff)[_i]), (LAS unsigned*)(lds + (bufoff) + ldsw + _i * 8192), 16, 0, 0); } while (0)
; #define PG8_LDA(dst, b, h) do { _Pragma("unroll") for (int m = 0; m < 4; ++m) _Pragma("unroll") for (int k = 0; k < 2; ++k) dst[m][k] = *(const LAS bf16x8*)(lds + PG8_SA(b, h) + aoff + m * 2048 + k * 1024); } while (0)
; #define PG8_LDB(dst, b, h) do { _Pragma("unroll") for (int n = 0; n < 2; ++n) _Pragma("unroll") for (int k = 0; k < 2; ++k) dst[n][k] = *(const LAS bf16x8*)(lds + PG8_SB(b, h) + boff + n * 2048 + k * 1024); } while (0)
; #define PG8_WAIT_V(n) asm volatile("s_waitcnt vmcnt(" #n ")" ::: "memory")
; #define PG8_WAIT_L(n) asm volatile("s_waitcnt lgkmcnt(" #n ")" ::: "memory")
; #define PG8_BAR __builtin_amdgcn_s_barrier()
; #define PG8_SCHED __builtin_amdgcn_sched_barrier(0)
; template <class Epi, class Sched>
; __device__ __forceinline__ void gemm_phase(LAS unsigned char* lds, const Gemm g, const Sched& S, const Epi& E) {
;     ...
;         const bool has_next = S.next(ui + 1, nxt);
;         const char* nA = has_next ? (const char*)g.A + (size_t)nxt.pm * tstepA : cA; const char* nB = has_next ? (const char*)g.Bt + (size_t)nxt.pn * tstepB : cB;
;         for (int t = 0; t < nt; t += 2) {
;             const bool last = (t == nt - 2);
;             const char* a1 = cA + (size_t)(t + 1) * kstep;
;             const char* a2 = last ? nA : cA + (size_t)(t + 2) * kstep; const char* b2 = last ? nB : cB + (size_t)(t + 2) * kstep;
;             const char* a3 = a2 + kstep; const char* b3 = b2 + kstep;
;             if (last && has_next) S.a_ready(nxt);
;             PG8_LDB(B0, 0, 0); PG8_SCHED; PG8_LDA(At, 0, 0); PG8_STAGE(PG8_SA(1, 1), a1 + hstepA, voffA);
;             PG8_WAIT_L(8); PG8_BAR; PG8_WAIT_L(0); PG8_MMA(0, 0, At, B0); PG8_BAR; PG8_SCHED;
;             PG8_LDB(B1, 0, 1); PG8_STAGE(PG8_SB(0, 0), b2, voffB);
;             PG8_BAR; PG8_WAIT_L(0); PG8_MMA(0, 1, At, B1); PG8_BAR;
;             PG8_LDA(At, 0, 1); PG8_STAGE(PG8_SA(0, 0), a2, voffA);
;             PG8_BAR; PG8_WAIT_L(0); PG8_MMA(1, 0, At, B0); PG8_BAR; PG8_SCHED;
;             PG8_STAGE(PG8_SB(0, 1), b2 + hstepB, voffB);
;             PG8_WAIT_V(6); PG8_BAR; PG8_MMA(1, 1, At, B1); PG8_BAR;
.LBB0_1093:
	v_mov_b64_e32 v[4:5], 0x900
	s_ashr_i32 s5, s4, 31
	v_cmp_lt_i64_e32 vcc, s[6:7], v[4:5]
	s_lshl_b64 s[6:7], s[4:5], 20
	s_add_u32 s6, s88, s6
	s_addc_u32 s7, s89, s7
	s_and_b64 s[14:15], vcc, exec
	s_cselect_b32 s5, s7, s19
	s_cselect_b32 s49, s6, s18
	s_ashr_i32 s1, s0, 31
	s_lshl_b64 s[14:15], s[0:1], 20
	s_add_u32 s14, s28, s14
	s_addc_u32 s15, s29, s15
	s_and_b64 s[24:25], vcc, exec
	s_cselect_b32 s1, s15, s21
	s_cselect_b32 s50, s14, s20
	s_add_u32 s18, s18, 0x80080
	s_addc_u32 s19, s19, 0
	s_add_u32 s51, s20, 0x100
	s_addc_u32 s52, s21, 0
	s_mov_b32 s53, -2
	s_setprio 0
	s_add_u32 s20, s18, 0xfff80080
	s_addc_u32 s21, s19, -1
	s_add_i32 s54, 0, 0x10000
	v_add_u32_e32 v146, s54, v1
	ds_read_b128 v[142:145], v146
	ds_read_b128 v[150:153], v146 offset:1024
	ds_read_b128 v[154:157], v146 offset:2048
	ds_read_b128 v[158:161], v146 offset:3072
	s_cmp_eq_u32 s53, 28
	s_cselect_b32 s25, s5, s21
	s_cselect_b32 s24, s49, s20
	s_cselect_b32 s21, s1, s52
	s_cselect_b32 s20, s50, s51
	ds_read_b128 v[162:165], v148
	ds_read_b128 v[166:169], v148 offset:1024
	ds_read_b128 v[170:173], v148 offset:2048
	ds_read_b128 v[174:177], v148 offset:3072
	ds_read_b128 v[178:181], v148 offset:4096
	ds_read_b128 v[182:185], v148 offset:5120
	ds_read_b128 v[186:189], v148 offset:6144
	ds_read_b128 v[190:193], v148 offset:7168
	s_add_i32 s56, 0, 0x14000
	v_add_u32_e32 v146, s56, v1
	ds_read_b128 v[194:197], v146
	ds_read_b128 v[198:201], v146 offset:1024
	ds_read_b128 v[202:205], v146 offset:2048
	ds_read_b128 v[206:209], v146 offset:3072
	s_add_i32 m0, s31, 0xc000
	s_nop 0
	global_load_lds_dwordx4 v138, s[18:19]
	s_add_i32 m0, s31, 0xe000
	s_nop 0
	global_load_lds_dwordx4 v140, s[18:19]
	s_waitcnt lgkmcnt(0)
	s_setprio 1
	s_barrier
	v_mfma_f32_16x16x32_bf16 v[128:131], v[142:145], v[162:165], 0
	v_mfma_f32_16x16x32_bf16 v[124:127], v[154:157], v[162:165], 0
	v_mfma_f32_16x16x32_bf16 v[120:123], v[142:145], v[170:173], 0
	v_mfma_f32_16x16x32_bf16 v[112:115], v[154:157], v[170:173], 0
	v_mfma_f32_16x16x32_bf16 v[104:107], v[142:145], v[178:181], 0
	v_mfma_f32_16x16x32_bf16 v[96:99], v[154:157], v[178:181], 0
	v_mfma_f32_16x16x32_bf16 v[88:91], v[142:145], v[186:189], 0
	v_mfma_f32_16x16x32_bf16 v[80:83], v[154:157], v[186:189], 0
	v_mfma_f32_16x16x32_bf16 v[128:131], v[150:153], v[166:169], v[128:131]
	v_mfma_f32_16x16x32_bf16 v[124:127], v[158:161], v[166:169], v[124:127]
	v_mfma_f32_16x16x32_bf16 v[120:123], v[150:153], v[174:177], v[120:123]
	v_mfma_f32_16x16x32_bf16 v[112:115], v[158:161], v[174:177], v[112:115]
	v_mfma_f32_16x16x32_bf16 v[104:107], v[150:153], v[182:185], v[104:107]
	v_mfma_f32_16x16x32_bf16 v[96:99], v[158:161], v[182:185], v[96:99]
	v_mfma_f32_16x16x32_bf16 v[88:91], v[150:153], v[190:193], v[88:91]
	v_mfma_f32_16x16x32_bf16 v[80:83], v[158:161], v[190:193], v[80:83]
	v_mfma_f32_16x16x32_bf16 v[116:119], v[194:197], v[162:165], 0
	v_mfma_f32_16x16x32_bf16 v[108:111], v[202:205], v[162:165], 0
	v_mfma_f32_16x16x32_bf16 v[100:103], v[194:197], v[170:173], 0
	v_mfma_f32_16x16x32_bf16 v[92:95], v[202:205], v[170:173], 0
	v_mfma_f32_16x16x32_bf16 v[84:87], v[194:197], v[178:181], 0
	v_mfma_f32_16x16x32_bf16 v[76:79], v[202:205], v[178:181], 0
	v_mfma_f32_16x16x32_bf16 v[72:75], v[194:197], v[186:189], 0
	v_mfma_f32_16x16x32_bf16 v[68:71], v[202:205], v[186:189], 0
	v_mfma_f32_16x16x32_bf16 v[116:119], v[198:201], v[166:169], v[116:119]
	v_mfma_f32_16x16x32_bf16 v[108:111], v[206:209], v[166:169], v[108:111]
	v_mfma_f32_16x16x32_bf16 v[100:103], v[198:201], v[174:177], v[100:103]
	v_mfma_f32_16x16x32_bf16 v[92:95], v[206:209], v[174:177], v[92:95]
	v_mfma_f32_16x16x32_bf16 v[84:87], v[198:201], v[182:185], v[84:87]
	v_mfma_f32_16x16x32_bf16 v[76:79], v[206:209], v[182:185], v[76:79]
	v_mfma_f32_16x16x32_bf16 v[72:75], v[198:201], v[190:193], v[72:75]
	v_mfma_f32_16x16x32_bf16 v[68:71], v[206:209], v[190:193], v[68:71]
	s_barrier
	s_setprio 0
	ds_read_b128 v[162:165], v148 offset:16384
	ds_read_b128 v[166:169], v148 offset:17408
	ds_read_b128 v[170:173], v148 offset:18432
	ds_read_b128 v[174:177], v148 offset:19456
	ds_read_b128 v[178:181], v148 offset:20480
	ds_read_b128 v[182:185], v148 offset:21504
	ds_read_b128 v[186:189], v148 offset:22528
	ds_read_b128 v[190:193], v148 offset:23552
	s_add_i32 s54, s54, s30
	v_lshl_add_u64 v[146:147], s[20:21], 0, v[2:3]
	s_mov_b32 m0, s54
	v_lshl_add_u64 v[210:211], s[20:21], 0, v[132:133]
	global_load_lds_dwordx4 v[146:147], off
	s_add_i32 m0, s54, 0x2000
	s_nop 0
	global_load_lds_dwordx4 v[210:211], off
	s_mov_b32 m0, s31
	v_lshl_add_u64 v[212:213], s[24:25], 0, v[136:137]
	global_load_lds_dwordx4 v[212:213], off
	v_lshl_add_u64 v[216:217], s[24:25], 0, v[134:135]
	s_mov_b32 m0, s35
	s_nop 0
	global_load_lds_dwordx4 v[216:217], off
	s_add_u32 s54, s20, 0x80000
	s_addc_u32 s55, s21, 0
	s_add_i32 s56, s56, s30
	s_mov_b32 m0, s56
	s_nop 0
	global_load_lds_dwordx4 v2, s[54:55]
	s_add_i32 m0, s56, 0x2000
	s_nop 0
	global_load_lds_dwordx4 v132, s[54:55]
	s_waitcnt lgkmcnt(0)
	s_setprio 1
	s_barrier
; #define PG8_STAGE(bufoff, gbase, voff) do { _Pragma("unroll") for (int _i = 0; _i < 2; ++_i) \
;         __builtin_amdgcn_global_load_lds((const unsigned*)((const char*)(gbase) + (voff)[_i]), (LAS unsigned*)(lds + (bufoff) + ldsw + _i * 8192), 16, 0, 0); } while (0)
; #define PG8_LDA(dst, b, h) do { _Pragma("unroll") for (int m = 0; m < 4; ++m) _Pragma("unroll") for (int k = 0; k < 2; ++k) dst[m][k] = *(const LAS bf16x8*)(lds + PG8_SA(b, h) + aoff + m * 2048 + k * 1024); } while (0)
; #define PG8_LDB(dst, b, h) do { _Pragma("unroll") for (int n = 0; n < 2; ++n) _Pragma("unroll") for (int k = 0; k < 2; ++k) dst[n][k] = *(const LAS bf16x8*)(lds + PG8_SB(b, h) + boff + n * 2048 + k * 1024); } while (0)
; #define PG8_MMA(ai, bj, At, Bt) do { __builtin_amdgcn_s_setprio(1); _Pragma("unroll") for (int m = 0; m < 4; ++m) _Pragma("unroll") for (int n = 0; n < 2; ++n) _Pragma("unroll") for (int k = 0; k < 2; ++k) \
;         acc[ai][bj][m][n] = __builtin_amdgcn_mfma_f32_16x16x32_bf16(Bt[n][k], At[m][k], acc[ai][bj][m][n], 0, 0, 0); __builtin_amdgcn_s_setprio(0); } while (0)
; #define PG8_WAIT_V(n) asm volatile("s_waitcnt vmcnt(" #n ")" ::: "memory")
; #define PG8_WAIT_L(n) asm volatile("s_waitcnt lgkmcnt(" #n ")" ::: "memory")
; #define PG8_BAR __builtin_amdgcn_s_barrier()
; #define PG8_SCHED __builtin_amdgcn_sched_barrier(0)
; template <class Epi, class Sched>
; __device__ __forceinline__ void gemm_phase(LAS unsigned char* lds, const Gemm g, const Sched& S, const Epi& E) {
;     ...
;             PG8_WAIT_V(6); PG8_BAR; PG8_MMA(1, 1, At, B1); PG8_BAR;
;             PG8_LDB(B0, 1, 0); PG8_SCHED; PG8_LDA(At, 1, 0); PG8_STAGE(PG8_SA(0, 1), a2 + hstepA, voffA);
;             PG8_WAIT_L(8); PG8_BAR; PG8_WAIT_L(0); PG8_MMA(0, 0, At, B0); PG8_BAR; PG8_SCHED;
;             PG8_LDB(B1, 1, 1); PG8_STAGE(PG8_SB(1, 0), b3, voffB);
;             PG8_BAR; PG8_WAIT_L(0); PG8_MMA(0, 1, At, B1); PG8_BAR;
;             PG8_LDA(At, 1, 1); PG8_STAGE(PG8_SA(1, 0), a3, voffA);
	v_mfma_f32_16x16x32_bf16 v[64:67], v[142:145], v[162:165], 0
	v_mfma_f32_16x16x32_bf16 v[60:63], v[154:157], v[162:165], 0
	v_mfma_f32_16x16x32_bf16 v[56:59], v[142:145], v[170:173], 0
	v_mfma_f32_16x16x32_bf16 v[48:51], v[154:157], v[170:173], 0
	v_mfma_f32_16x16x32_bf16 v[40:43], v[142:145], v[178:181], 0
	v_mfma_f32_16x16x32_bf16 v[32:35], v[154:157], v[178:181], 0
	v_mfma_f32_16x16x32_bf16 v[24:27], v[142:145], v[186:189], 0
	v_mfma_f32_16x16x32_bf16 v[16:19], v[154:157], v[186:189], 0
	v_mfma_f32_16x16x32_bf16 v[64:67], v[150:153], v[166:169], v[64:67]
	v_mfma_f32_16x16x32_bf16 v[60:63], v[158:161], v[166:169], v[60:63]
	v_mfma_f32_16x16x32_bf16 v[56:59], v[150:153], v[174:177], v[56:59]
	v_mfma_f32_16x16x32_bf16 v[48:51], v[158:161], v[174:177], v[48:51]
	v_mfma_f32_16x16x32_bf16 v[40:43], v[150:153], v[182:185], v[40:43]
	v_mfma_f32_16x16x32_bf16 v[32:35], v[158:161], v[182:185], v[32:35]
	v_mfma_f32_16x16x32_bf16 v[24:27], v[150:153], v[190:193], v[24:27]
	v_mfma_f32_16x16x32_bf16 v[16:19], v[158:161], v[190:193], v[16:19]
	v_mfma_f32_16x16x32_bf16 v[52:55], v[194:197], v[162:165], 0
	v_mfma_f32_16x16x32_bf16 v[44:47], v[202:205], v[162:165], 0
	v_mfma_f32_16x16x32_bf16 v[36:39], v[194:197], v[170:173], 0
	v_mfma_f32_16x16x32_bf16 v[28:31], v[202:205], v[170:173], 0
	v_mfma_f32_16x16x32_bf16 v[20:23], v[194:197], v[178:181], 0
	v_mfma_f32_16x16x32_bf16 v[12:15], v[202:205], v[178:181], 0
	v_mfma_f32_16x16x32_bf16 v[8:11], v[194:197], v[186:189], 0
	v_mfma_f32_16x16x32_bf16 v[4:7], v[202:205], v[186:189], 0
	v_mfma_f32_16x16x32_bf16 v[52:55], v[198:201], v[166:169], v[52:55]
	v_mfma_f32_16x16x32_bf16 v[44:47], v[206:209], v[166:169], v[44:47]
	v_mfma_f32_16x16x32_bf16 v[36:39], v[198:201], v[174:177], v[36:39]
	v_mfma_f32_16x16x32_bf16 v[28:31], v[206:209], v[174:177], v[28:31]
	v_mfma_f32_16x16x32_bf16 v[20:23], v[198:201], v[182:185], v[20:23]
	v_mfma_f32_16x16x32_bf16 v[12:15], v[206:209], v[182:185], v[12:15]
	v_mfma_f32_16x16x32_bf16 v[8:11], v[198:201], v[190:193], v[8:11]
	v_mfma_f32_16x16x32_bf16 v[4:7], v[206:209], v[190:193], v[4:7]
	s_barrier
	s_setprio 0
	s_add_i32 s54, 0, 0x18000
	v_add_u32_e32 v149, s54, v1
	ds_read_b128 v[142:145], v149
	ds_read_b128 v[150:153], v149 offset:1024
	ds_read_b128 v[154:157], v149 offset:2048
	ds_read_b128 v[158:161], v149 offset:3072
	s_add_u32 s24, s24, 0x80000
	s_addc_u32 s25, s25, 0
	ds_read_b128 v[162:165], v148 offset:32768
	ds_read_b128 v[166:169], v148 offset:33792
	ds_read_b128 v[170:173], v148 offset:34816
	ds_read_b128 v[174:177], v148 offset:35840
	ds_read_b128 v[178:181], v148 offset:36864
	ds_read_b128 v[182:185], v148 offset:37888
	ds_read_b128 v[186:189], v148 offset:38912
	ds_read_b128 v[190:193], v148 offset:39936
	s_mov_b32 m0, s36
	s_nop 0
	global_load_lds_dwordx4 v136, s[24:25]
	s_mov_b32 m0, s37
	s_nop 0
	global_load_lds_dwordx4 v134, s[24:25]
	s_add_i32 s24, 0, 0x1c000
	v_add_u32_e32 v149, s24, v1
	ds_read_b128 v[194:197], v149
	ds_read_b128 v[198:201], v149 offset:1024
	ds_read_b128 v[202:205], v149 offset:2048
	ds_read_b128 v[206:209], v149 offset:3072
	s_waitcnt lgkmcnt(0)
	s_setprio 1
	s_waitcnt vmcnt(8)
	s_barrier
	v_mfma_f32_16x16x32_bf16 v[128:131], v[142:145], v[162:165], v[128:131]
	v_mfma_f32_16x16x32_bf16 v[124:127], v[154:157], v[162:165], v[124:127]
	v_mfma_f32_16x16x32_bf16 v[120:123], v[142:145], v[170:173], v[120:123]
	v_mfma_f32_16x16x32_bf16 v[112:115], v[154:157], v[170:173], v[112:115]
	v_mfma_f32_16x16x32_bf16 v[104:107], v[142:145], v[178:181], v[104:107]
	v_mfma_f32_16x16x32_bf16 v[96:99], v[154:157], v[178:181], v[96:99]
	v_mfma_f32_16x16x32_bf16 v[88:91], v[142:145], v[186:189], v[88:91]
	v_mfma_f32_16x16x32_bf16 v[80:83], v[154:157], v[186:189], v[80:83]
	v_mfma_f32_16x16x32_bf16 v[128:131], v[150:153], v[166:169], v[128:131]
	v_mfma_f32_16x16x32_bf16 v[124:127], v[158:161], v[166:169], v[124:127]
	v_mfma_f32_16x16x32_bf16 v[120:123], v[150:153], v[174:177], v[120:123]
	v_mfma_f32_16x16x32_bf16 v[112:115], v[158:161], v[174:177], v[112:115]
	v_mfma_f32_16x16x32_bf16 v[104:107], v[150:153], v[182:185], v[104:107]
	v_mfma_f32_16x16x32_bf16 v[96:99], v[158:161], v[182:185], v[96:99]
	v_mfma_f32_16x16x32_bf16 v[88:91], v[150:153], v[190:193], v[88:91]
	v_mfma_f32_16x16x32_bf16 v[80:83], v[158:161], v[190:193], v[80:83]
	v_mfma_f32_16x16x32_bf16 v[116:119], v[194:197], v[162:165], v[116:119]
	v_mfma_f32_16x16x32_bf16 v[108:111], v[202:205], v[162:165], v[108:111]
	v_mfma_f32_16x16x32_bf16 v[100:103], v[194:197], v[170:173], v[100:103]
	v_mfma_f32_16x16x32_bf16 v[92:95], v[202:205], v[170:173], v[92:95]
	v_mfma_f32_16x16x32_bf16 v[84:87], v[194:197], v[178:181], v[84:87]
	v_mfma_f32_16x16x32_bf16 v[76:79], v[202:205], v[178:181], v[76:79]
	v_mfma_f32_16x16x32_bf16 v[72:75], v[194:197], v[186:189], v[72:75]
	v_mfma_f32_16x16x32_bf16 v[68:71], v[202:205], v[186:189], v[68:71]
	v_mfma_f32_16x16x32_bf16 v[116:119], v[198:201], v[166:169], v[116:119]
	v_mfma_f32_16x16x32_bf16 v[108:111], v[206:209], v[166:169], v[108:111]
	v_mfma_f32_16x16x32_bf16 v[100:103], v[198:201], v[174:177], v[100:103]
	v_mfma_f32_16x16x32_bf16 v[92:95], v[206:209], v[174:177], v[92:95]
	v_mfma_f32_16x16x32_bf16 v[84:87], v[198:201], v[182:185], v[84:87]
	v_mfma_f32_16x16x32_bf16 v[76:79], v[206:209], v[182:185], v[76:79]
	v_mfma_f32_16x16x32_bf16 v[72:75], v[198:201], v[190:193], v[72:75]
	v_mfma_f32_16x16x32_bf16 v[68:71], v[206:209], v[190:193], v[68:71]
	s_barrier
; #define PG8_STAGE(bufoff, gbase, voff) do { _Pragma("unroll") for (int _i = 0; _i < 2; ++_i) \
;         __builtin_amdgcn_global_load_lds((const unsigned*)((const char*)(gbase) + (voff)[_i]), (LAS unsigned*)(lds + (bufoff) + ldsw + _i * 8192), 16, 0, 0); } while (0)
; #define PG8_LDA(dst, b, h) do { _Pragma("unroll") for (int m = 0; m < 4; ++m) _Pragma("unroll") for (int k = 0; k < 2; ++k) dst[m][k] = *(const LAS bf16x8*)(lds + PG8_SA(b, h) + aoff + m * 2048 + k * 1024); } while (0)
; #define PG8_LDB(dst, b, h) do { _Pragma("unroll") for (int n = 0; n < 2; ++n) _Pragma("unroll") for (int k = 0; k < 2; ++k) dst[n][k] = *(const LAS bf16x8*)(lds + PG8_SB(b, h) + boff + n * 2048 + k * 1024); } while (0)
; #define PG8_WAIT_V(n) asm volatile("s_waitcnt vmcnt(" #n ")" ::: "memory")
; #define PG8_WAIT_L(n) asm volatile("s_waitcnt lgkmcnt(" #n ")" ::: "memory")
; #define PG8_BAR __builtin_amdgcn_s_barrier()
; #define PG8_SCHED __builtin_amdgcn_sched_barrier(0)
; template <class Epi, class Sched>
; __device__ __forceinline__ void gemm_phase(LAS unsigned char* lds, const Gemm g, const Sched& S, const Epi& E) {
;     ...
;             PG8_LDB(B0, 0, 0); PG8_SCHED; PG8_LDA(At, 0, 0); PG8_STAGE(PG8_SA(1, 1), a1 + hstepA, voffA);
;             PG8_WAIT_L(8); PG8_BAR; PG8_WAIT_L(0); PG8_MMA(0, 0, At, B0); PG8_BAR; PG8_SCHED;
;             PG8_LDB(B1, 0, 1); PG8_STAGE(PG8_SB(0, 0), b2, voffB);
;             PG8_BAR; PG8_WAIT_L(0); PG8_MMA(0, 1, At, B1); PG8_BAR;
;             PG8_LDA(At, 0, 1); PG8_STAGE(PG8_SA(0, 0), a2, voffA);
;             PG8_BAR; PG8_WAIT_L(0); PG8_MMA(1, 0, At, B0); PG8_BAR; PG8_SCHED;
;             PG8_STAGE(PG8_SB(0, 1), b2 + hstepB, voffB);
;             PG8_WAIT_V(6); PG8_BAR; PG8_MMA(1, 1, At, B1); PG8_BAR;
;             PG8_LDB(B0, 1, 0); PG8_SCHED; PG8_LDA(At, 1, 0); PG8_STAGE(PG8_SA(0, 1), a2 + hstepA, voffA);
;             PG8_WAIT_L(8); PG8_BAR; PG8_WAIT_L(0); PG8_MMA(0, 0, At, B0); PG8_BAR; PG8_SCHED;
;             PG8_LDB(B1, 1, 1); PG8_STAGE(PG8_SB(1, 0), b3, voffB);
;             PG8_BAR; PG8_WAIT_L(0); PG8_MMA(0, 1, At, B1); PG8_BAR;
;             PG8_LDA(At, 1, 1); PG8_STAGE(PG8_SA(1, 0), a3, voffA);
;             PG8_BAR; PG8_WAIT_L(0); PG8_MMA(1, 0, At, B0); PG8_BAR; PG8_SCHED;
;             PG8_STAGE(PG8_SB(1, 1), b3 + hstepB, voffB);
;             PG8_WAIT_V(6); PG8_BAR; PG8_MMA(1, 1, At, B1); PG8_BAR;
	s_setprio 0
	ds_read_b128 v[162:165], v148 offset:49152
	ds_read_b128 v[166:169], v148 offset:50176
	ds_read_b128 v[170:173], v148 offset:51200
	ds_read_b128 v[174:177], v148 offset:52224
	ds_read_b128 v[178:181], v148 offset:53248
	ds_read_b128 v[182:185], v148 offset:54272
	ds_read_b128 v[186:189], v148 offset:55296
	ds_read_b128 v[190:193], v148 offset:56320
	s_add_i32 s25, s54, s30
	v_lshl_add_u64 v[146:147], v[146:147], 0, s[8:9]
	s_mov_b32 m0, s25
	s_nop 0
	global_load_lds_dwordx4 v[146:147], off
	v_lshl_add_u64 v[146:147], v[210:211], 0, s[8:9]
	s_add_i32 m0, s25, 0x2000
	s_nop 0
	global_load_lds_dwordx4 v[146:147], off
	s_mov_b32 m0, s42
	v_lshl_add_u64 v[146:147], v[212:213], 0, s[8:9]
	global_load_lds_dwordx4 v[146:147], off
	v_lshl_add_u64 v[146:147], v[216:217], 0, s[8:9]
	s_mov_b32 m0, s43
	s_nop 0
	global_load_lds_dwordx4 v[146:147], off
	s_add_u32 s20, s20, 0x80080
	s_addc_u32 s21, s21, 0
	s_add_i32 s24, s24, s30
	s_mov_b32 m0, s24
	s_nop 0
	global_load_lds_dwordx4 v2, s[20:21]
	s_add_i32 m0, s24, 0x2000
	s_nop 0
	global_load_lds_dwordx4 v132, s[20:21]
	s_add_i32 s53, s53, 2
	s_add_u32 s18, s18, 0x100
	s_addc_u32 s19, s19, 0
	s_add_u32 s51, s51, 0x100
	s_addc_u32 s52, s52, 0
	s_cmp_gt_u32 s53, 29
	s_waitcnt lgkmcnt(0)
	s_waitcnt vmcnt(6)
	s_setprio 1
	s_barrier
	v_mfma_f32_16x16x32_bf16 v[64:67], v[142:145], v[162:165], v[64:67]
	v_mfma_f32_16x16x32_bf16 v[60:63], v[154:157], v[162:165], v[60:63]
	v_mfma_f32_16x16x32_bf16 v[56:59], v[142:145], v[170:173], v[56:59]
	v_mfma_f32_16x16x32_bf16 v[48:51], v[154:157], v[170:173], v[48:51]
	v_mfma_f32_16x16x32_bf16 v[40:43], v[142:145], v[178:181], v[40:43]
	v_mfma_f32_16x16x32_bf16 v[32:35], v[154:157], v[178:181], v[32:35]
	v_mfma_f32_16x16x32_bf16 v[24:27], v[142:145], v[186:189], v[24:27]
	v_mfma_f32_16x16x32_bf16 v[16:19], v[154:157], v[186:189], v[16:19]
	v_mfma_f32_16x16x32_bf16 v[64:67], v[150:153], v[166:169], v[64:67]
	v_mfma_f32_16x16x32_bf16 v[60:63], v[158:161], v[166:169], v[60:63]
	v_mfma_f32_16x16x32_bf16 v[56:59], v[150:153], v[174:177], v[56:59]
	v_mfma_f32_16x16x32_bf16 v[48:51], v[158:161], v[174:177], v[48:51]
	v_mfma_f32_16x16x32_bf16 v[40:43], v[150:153], v[182:185], v[40:43]
	v_mfma_f32_16x16x32_bf16 v[32:35], v[158:161], v[182:185], v[32:35]
	v_mfma_f32_16x16x32_bf16 v[24:27], v[150:153], v[190:193], v[24:27]
	v_mfma_f32_16x16x32_bf16 v[16:19], v[158:161], v[190:193], v[16:19]
	v_mfma_f32_16x16x32_bf16 v[52:55], v[194:197], v[162:165], v[52:55]
	v_mfma_f32_16x16x32_bf16 v[44:47], v[202:205], v[162:165], v[44:47]
	v_mfma_f32_16x16x32_bf16 v[36:39], v[194:197], v[170:173], v[36:39]
	v_mfma_f32_16x16x32_bf16 v[28:31], v[202:205], v[170:173], v[28:31]
	v_mfma_f32_16x16x32_bf16 v[20:23], v[194:197], v[178:181], v[20:23]
	v_mfma_f32_16x16x32_bf16 v[12:15], v[202:205], v[178:181], v[12:15]
	v_mfma_f32_16x16x32_bf16 v[8:11], v[194:197], v[186:189], v[8:11]
	v_mfma_f32_16x16x32_bf16 v[4:7], v[202:205], v[186:189], v[4:7]
	v_mfma_f32_16x16x32_bf16 v[52:55], v[198:201], v[166:169], v[52:55]
	v_mfma_f32_16x16x32_bf16 v[44:47], v[206:209], v[166:169], v[44:47]
	v_mfma_f32_16x16x32_bf16 v[36:39], v[198:201], v[174:177], v[36:39]
	v_mfma_f32_16x16x32_bf16 v[28:31], v[206:209], v[174:177], v[28:31]
	v_mfma_f32_16x16x32_bf16 v[20:23], v[198:201], v[182:185], v[20:23]
	v_mfma_f32_16x16x32_bf16 v[12:15], v[206:209], v[182:185], v[12:15]
	v_mfma_f32_16x16x32_bf16 v[8:11], v[198:201], v[190:193], v[8:11]
	v_mfma_f32_16x16x32_bf16 v[4:7], v[206:209], v[190:193], v[4:7]
	s_barrier
	s_setprio 0
.LBB0_1094:
	s_setprio 0
	s_add_u32 s20, s18, 0xfff80080
	s_addc_u32 s21, s19, -1
	s_add_i32 s54, 0, 0x10000
	v_add_u32_e32 v146, s54, v1
	ds_read_b128 v[142:145], v146
	ds_read_b128 v[150:153], v146 offset:1024
	ds_read_b128 v[154:157], v146 offset:2048
	ds_read_b128 v[158:161], v146 offset:3072
	s_cmp_eq_u32 s53, 28
	s_cselect_b32 s25, s5, s21
	s_cselect_b32 s24, s49, s20
	s_cselect_b32 s21, s1, s52
	s_cselect_b32 s20, s50, s51
	ds_read_b128 v[162:165], v148
	ds_read_b128 v[166:169], v148 offset:1024
	ds_read_b128 v[170:173], v148 offset:2048
	ds_read_b128 v[174:177], v148 offset:3072
	ds_read_b128 v[178:181], v148 offset:4096
	ds_read_b128 v[182:185], v148 offset:5120
	ds_read_b128 v[186:189], v148 offset:6144
	ds_read_b128 v[190:193], v148 offset:7168
	s_add_i32 s56, 0, 0x14000
	v_add_u32_e32 v146, s56, v1
	ds_read_b128 v[194:197], v146
	ds_read_b128 v[198:201], v146 offset:1024
	ds_read_b128 v[202:205], v146 offset:2048
	ds_read_b128 v[206:209], v146 offset:3072
	s_add_i32 m0, s31, 0xc000
	s_nop 0
	global_load_lds_dwordx4 v138, s[18:19]
	s_add_i32 m0, s31, 0xe000
	s_nop 0
	global_load_lds_dwordx4 v140, s[18:19]
	s_waitcnt lgkmcnt(0)
	s_setprio 1
	s_barrier
; #define PG8_STAGE(bufoff, gbase, voff) do { _Pragma("unroll") for (int _i = 0; _i < 2; ++_i) \
;         __builtin_amdgcn_global_load_lds((const unsigned*)((const char*)(gbase) + (voff)[_i]), (LAS unsigned*)(lds + (bufoff) + ldsw + _i * 8192), 16, 0, 0); } while (0)
; #define PG8_LDA(dst, b, h) do { _Pragma("unroll") for (int m = 0; m < 4; ++m) _Pragma("unroll") for (int k = 0; k < 2; ++k) dst[m][k] = *(const LAS bf16x8*)(lds + PG8_SA(b, h) + aoff + m * 2048 + k * 1024); } while (0)
; #define PG8_LDB(dst, b, h) do { _Pragma("unroll") for (int n = 0; n < 2; ++n) _Pragma("unroll") for (int k = 0; k < 2; ++k) dst[n][k] = *(const LAS bf16x8*)(lds + PG8_SB(b, h) + boff + n * 2048 + k * 1024); } while (0)
; #define PG8_MMA(ai, bj, At, Bt) do { __builtin_amdgcn_s_setprio(1); _Pragma("unroll") for (int m = 0; m < 4; ++m) _Pragma("unroll") for (int n = 0; n < 2; ++n) _Pragma("unroll") for (int k = 0; k < 2; ++k) \
;         acc[ai][bj][m][n] = __builtin_amdgcn_mfma_f32_16x16x32_bf16(Bt[n][k], At[m][k], acc[ai][bj][m][n], 0, 0, 0); __builtin_amdgcn_s_setprio(0); } while (0)
; #define PG8_WAIT_V(n) asm volatile("s_waitcnt vmcnt(" #n ")" ::: "memory")
; #define PG8_WAIT_L(n) asm volatile("s_waitcnt lgkmcnt(" #n ")" ::: "memory")
; #define PG8_BAR __builtin_amdgcn_s_barrier()
; #define PG8_SCHED __builtin_amdgcn_sched_barrier(0)
; template <class Epi, class Sched>
; __device__ __forceinline__ void gemm_phase(LAS unsigned char* lds, const Gemm g, const Sched& S, const Epi& E) {
;     ...
;             PG8_WAIT_L(8); PG8_BAR; PG8_WAIT_L(0); PG8_MMA(0, 0, At, B0); PG8_BAR; PG8_SCHED;
;             PG8_LDB(B1, 0, 1); PG8_STAGE(PG8_SB(0, 0), b2, voffB);
;             PG8_BAR; PG8_WAIT_L(0); PG8_MMA(0, 1, At, B1); PG8_BAR;
;             PG8_LDA(At, 0, 1); PG8_STAGE(PG8_SA(0, 0), a2, voffA);
;             PG8_BAR; PG8_WAIT_L(0); PG8_MMA(1, 0, At, B0); PG8_BAR; PG8_SCHED;
;             PG8_STAGE(PG8_SB(0, 1), b2 + hstepB, voffB);
;             PG8_WAIT_V(6); PG8_BAR; PG8_MMA(1, 1, At, B1); PG8_BAR;
;             PG8_LDB(B0, 1, 0); PG8_SCHED; PG8_LDA(At, 1, 0); PG8_STAGE(PG8_SA(0, 1), a2 + hstepA, voffA);
;             PG8_WAIT_L(8); PG8_BAR; PG8_WAIT_L(0); PG8_MMA(0, 0, At, B0); PG8_BAR; PG8_SCHED;
	v_mfma_f32_16x16x32_bf16 v[128:131], v[142:145], v[162:165], v[128:131]
	v_mfma_f32_16x16x32_bf16 v[124:127], v[154:157], v[162:165], v[124:127]
	v_mfma_f32_16x16x32_bf16 v[120:123], v[142:145], v[170:173], v[120:123]
	v_mfma_f32_16x16x32_bf16 v[112:115], v[154:157], v[170:173], v[112:115]
	v_mfma_f32_16x16x32_bf16 v[104:107], v[142:145], v[178:181], v[104:107]
	v_mfma_f32_16x16x32_bf16 v[96:99], v[154:157], v[178:181], v[96:99]
	v_mfma_f32_16x16x32_bf16 v[88:91], v[142:145], v[186:189], v[88:91]
	v_mfma_f32_16x16x32_bf16 v[80:83], v[154:157], v[186:189], v[80:83]
	v_mfma_f32_16x16x32_bf16 v[128:131], v[150:153], v[166:169], v[128:131]
	v_mfma_f32_16x16x32_bf16 v[124:127], v[158:161], v[166:169], v[124:127]
	v_mfma_f32_16x16x32_bf16 v[120:123], v[150:153], v[174:177], v[120:123]
	v_mfma_f32_16x16x32_bf16 v[112:115], v[158:161], v[174:177], v[112:115]
	v_mfma_f32_16x16x32_bf16 v[104:107], v[150:153], v[182:185], v[104:107]
	v_mfma_f32_16x16x32_bf16 v[96:99], v[158:161], v[182:185], v[96:99]
	v_mfma_f32_16x16x32_bf16 v[88:91], v[150:153], v[190:193], v[88:91]
	v_mfma_f32_16x16x32_bf16 v[80:83], v[158:161], v[190:193], v[80:83]
	v_mfma_f32_16x16x32_bf16 v[116:119], v[194:197], v[162:165], v[116:119]
	v_mfma_f32_16x16x32_bf16 v[108:111], v[202:205], v[162:165], v[108:111]
	v_mfma_f32_16x16x32_bf16 v[100:103], v[194:197], v[170:173], v[100:103]
	v_mfma_f32_16x16x32_bf16 v[92:95], v[202:205], v[170:173], v[92:95]
	v_mfma_f32_16x16x32_bf16 v[84:87], v[194:197], v[178:181], v[84:87]
	v_mfma_f32_16x16x32_bf16 v[76:79], v[202:205], v[178:181], v[76:79]
	v_mfma_f32_16x16x32_bf16 v[72:75], v[194:197], v[186:189], v[72:75]
	v_mfma_f32_16x16x32_bf16 v[68:71], v[202:205], v[186:189], v[68:71]
	v_mfma_f32_16x16x32_bf16 v[116:119], v[198:201], v[166:169], v[116:119]
	v_mfma_f32_16x16x32_bf16 v[108:111], v[206:209], v[166:169], v[108:111]
	v_mfma_f32_16x16x32_bf16 v[100:103], v[198:201], v[174:177], v[100:103]
	v_mfma_f32_16x16x32_bf16 v[92:95], v[206:209], v[174:177], v[92:95]
	v_mfma_f32_16x16x32_bf16 v[84:87], v[198:201], v[182:185], v[84:87]
	v_mfma_f32_16x16x32_bf16 v[76:79], v[206:209], v[182:185], v[76:79]
	v_mfma_f32_16x16x32_bf16 v[72:75], v[198:201], v[190:193], v[72:75]
	v_mfma_f32_16x16x32_bf16 v[68:71], v[206:209], v[190:193], v[68:71]
	s_barrier
	s_setprio 0
	ds_read_b128 v[162:165], v148 offset:16384
	ds_read_b128 v[166:169], v148 offset:17408
	ds_read_b128 v[170:173], v148 offset:18432
	ds_read_b128 v[174:177], v148 offset:19456
	ds_read_b128 v[178:181], v148 offset:20480
	ds_read_b128 v[182:185], v148 offset:21504
	ds_read_b128 v[186:189], v148 offset:22528
	ds_read_b128 v[190:193], v148 offset:23552
	s_add_i32 s54, s54, s30
	v_lshl_add_u64 v[146:147], s[20:21], 0, v[2:3]
	s_mov_b32 m0, s54
	v_lshl_add_u64 v[210:211], s[20:21], 0, v[132:133]
	global_load_lds_dwordx4 v[146:147], off
	s_add_i32 m0, s54, 0x2000
	s_nop 0
	global_load_lds_dwordx4 v[210:211], off
	s_mov_b32 m0, s31
	v_lshl_add_u64 v[212:213], s[24:25], 0, v[136:137]
	global_load_lds_dwordx4 v[212:213], off
	v_lshl_add_u64 v[216:217], s[24:25], 0, v[134:135]
	s_mov_b32 m0, s35
	s_nop 0
	global_load_lds_dwordx4 v[216:217], off
	s_add_u32 s54, s20, 0x80000
	s_addc_u32 s55, s21, 0
	s_add_i32 s56, s56, s30
	s_mov_b32 m0, s56
	s_nop 0
	global_load_lds_dwordx4 v2, s[54:55]
	s_add_i32 m0, s56, 0x2000
	s_nop 0
	global_load_lds_dwordx4 v132, s[54:55]
	s_waitcnt lgkmcnt(0)
	s_waitcnt vmcnt(6)
	s_setprio 1
	s_barrier
	v_mfma_f32_16x16x32_bf16 v[64:67], v[142:145], v[162:165], v[64:67]
	v_mfma_f32_16x16x32_bf16 v[60:63], v[154:157], v[162:165], v[60:63]
	v_mfma_f32_16x16x32_bf16 v[56:59], v[142:145], v[170:173], v[56:59]
	v_mfma_f32_16x16x32_bf16 v[48:51], v[154:157], v[170:173], v[48:51]
	v_mfma_f32_16x16x32_bf16 v[40:43], v[142:145], v[178:181], v[40:43]
	v_mfma_f32_16x16x32_bf16 v[32:35], v[154:157], v[178:181], v[32:35]
	v_mfma_f32_16x16x32_bf16 v[24:27], v[142:145], v[186:189], v[24:27]
	v_mfma_f32_16x16x32_bf16 v[16:19], v[154:157], v[186:189], v[16:19]
	v_mfma_f32_16x16x32_bf16 v[64:67], v[150:153], v[166:169], v[64:67]
	v_mfma_f32_16x16x32_bf16 v[60:63], v[158:161], v[166:169], v[60:63]
	v_mfma_f32_16x16x32_bf16 v[56:59], v[150:153], v[174:177], v[56:59]
	v_mfma_f32_16x16x32_bf16 v[48:51], v[158:161], v[174:177], v[48:51]
	v_mfma_f32_16x16x32_bf16 v[40:43], v[150:153], v[182:185], v[40:43]
	v_mfma_f32_16x16x32_bf16 v[32:35], v[158:161], v[182:185], v[32:35]
	v_mfma_f32_16x16x32_bf16 v[24:27], v[150:153], v[190:193], v[24:27]
	v_mfma_f32_16x16x32_bf16 v[16:19], v[158:161], v[190:193], v[16:19]
	v_mfma_f32_16x16x32_bf16 v[52:55], v[194:197], v[162:165], v[52:55]
	v_mfma_f32_16x16x32_bf16 v[44:47], v[202:205], v[162:165], v[44:47]
	v_mfma_f32_16x16x32_bf16 v[36:39], v[194:197], v[170:173], v[36:39]
	v_mfma_f32_16x16x32_bf16 v[28:31], v[202:205], v[170:173], v[28:31]
	v_mfma_f32_16x16x32_bf16 v[20:23], v[194:197], v[178:181], v[20:23]
	v_mfma_f32_16x16x32_bf16 v[12:15], v[202:205], v[178:181], v[12:15]
	v_mfma_f32_16x16x32_bf16 v[8:11], v[194:197], v[186:189], v[8:11]
	v_mfma_f32_16x16x32_bf16 v[4:7], v[202:205], v[186:189], v[4:7]
	v_mfma_f32_16x16x32_bf16 v[52:55], v[198:201], v[166:169], v[52:55]
	v_mfma_f32_16x16x32_bf16 v[44:47], v[206:209], v[166:169], v[44:47]
	v_mfma_f32_16x16x32_bf16 v[36:39], v[198:201], v[174:177], v[36:39]
	v_mfma_f32_16x16x32_bf16 v[28:31], v[206:209], v[174:177], v[28:31]
	v_mfma_f32_16x16x32_bf16 v[20:23], v[198:201], v[182:185], v[20:23]
	v_mfma_f32_16x16x32_bf16 v[12:15], v[206:209], v[182:185], v[12:15]
	v_mfma_f32_16x16x32_bf16 v[8:11], v[198:201], v[190:193], v[8:11]
	v_mfma_f32_16x16x32_bf16 v[4:7], v[206:209], v[190:193], v[4:7]
	s_barrier
; #define PG8_STAGE(bufoff, gbase, voff) do { _Pragma("unroll") for (int _i = 0; _i < 2; ++_i) \
;         __builtin_amdgcn_global_load_lds((const unsigned*)((const char*)(gbase) + (voff)[_i]), (LAS unsigned*)(lds + (bufoff) + ldsw + _i * 8192), 16, 0, 0); } while (0)
; #define PG8_LDA(dst, b, h) do { _Pragma("unroll") for (int m = 0; m < 4; ++m) _Pragma("unroll") for (int k = 0; k < 2; ++k) dst[m][k] = *(const LAS bf16x8*)(lds + PG8_SA(b, h) + aoff + m * 2048 + k * 1024); } while (0)
; #define PG8_LDB(dst, b, h) do { _Pragma("unroll") for (int n = 0; n < 2; ++n) _Pragma("unroll") for (int k = 0; k < 2; ++k) dst[n][k] = *(const LAS bf16x8*)(lds + PG8_SB(b, h) + boff + n * 2048 + k * 1024); } while (0)
; #define PG8_MMA(ai, bj, At, Bt) do { __builtin_amdgcn_s_setprio(1); _Pragma("unroll") for (int m = 0; m < 4; ++m) _Pragma("unroll") for (int n = 0; n < 2; ++n) _Pragma("unroll") for (int k = 0; k < 2; ++k) \
;         acc[ai][bj][m][n] = __builtin_amdgcn_mfma_f32_16x16x32_bf16(Bt[n][k], At[m][k], acc[ai][bj][m][n], 0, 0, 0); __builtin_amdgcn_s_setprio(0); } while (0)
; #define PG8_WAIT_V(n) asm volatile("s_waitcnt vmcnt(" #n ")" ::: "memory")
; #define PG8_WAIT_L(n) asm volatile("s_waitcnt lgkmcnt(" #n ")" ::: "memory")
; #define PG8_BAR __builtin_amdgcn_s_barrier()
; #define PG8_SCHED __builtin_amdgcn_sched_barrier(0)
; template <class Epi, class Sched>
; __device__ __forceinline__ void gemm_phase(LAS unsigned char* lds, const Gemm g, const Sched& S, const Epi& E) {
;     ...
;             PG8_WAIT_L(8); PG8_BAR; PG8_WAIT_L(0); PG8_MMA(0, 0, At, B0); PG8_BAR; PG8_SCHED;
;             PG8_LDB(B1, 1, 1); PG8_STAGE(PG8_SB(1, 0), b3, voffB);
;             PG8_BAR; PG8_WAIT_L(0); PG8_MMA(0, 1, At, B1); PG8_BAR;
;             PG8_LDA(At, 1, 1); PG8_STAGE(PG8_SA(1, 0), a3, voffA);
;             PG8_BAR; PG8_WAIT_L(0); PG8_MMA(1, 0, At, B0); PG8_BAR; PG8_SCHED;
;             PG8_STAGE(PG8_SB(1, 1), b3 + hstepB, voffB);
;             PG8_WAIT_V(6); PG8_BAR; PG8_MMA(1, 1, At, B1); PG8_BAR;
	s_setprio 0
	s_add_i32 s54, 0, 0x18000
	v_add_u32_e32 v149, s54, v1
	ds_read_b128 v[142:145], v149
	ds_read_b128 v[150:153], v149 offset:1024
	ds_read_b128 v[154:157], v149 offset:2048
	ds_read_b128 v[158:161], v149 offset:3072
	s_add_u32 s24, s24, 0x80000
	s_addc_u32 s25, s25, 0
	ds_read_b128 v[162:165], v148 offset:32768
	ds_read_b128 v[166:169], v148 offset:33792
	ds_read_b128 v[170:173], v148 offset:34816
	ds_read_b128 v[174:177], v148 offset:35840
	ds_read_b128 v[178:181], v148 offset:36864
	ds_read_b128 v[182:185], v148 offset:37888
	ds_read_b128 v[186:189], v148 offset:38912
	ds_read_b128 v[190:193], v148 offset:39936
	s_mov_b32 m0, s36
	s_nop 0
	global_load_lds_dwordx4 v136, s[24:25]
	s_mov_b32 m0, s37
	s_nop 0
	global_load_lds_dwordx4 v134, s[24:25]
	s_add_i32 s24, 0, 0x1c000
	v_add_u32_e32 v149, s24, v1
	ds_read_b128 v[194:197], v149
	ds_read_b128 v[198:201], v149 offset:1024
	ds_read_b128 v[202:205], v149 offset:2048
	ds_read_b128 v[206:209], v149 offset:3072
	s_waitcnt lgkmcnt(0)
	s_setprio 1
	s_barrier
	v_mfma_f32_16x16x32_bf16 v[128:131], v[142:145], v[162:165], v[128:131]
	v_mfma_f32_16x16x32_bf16 v[124:127], v[154:157], v[162:165], v[124:127]
	v_mfma_f32_16x16x32_bf16 v[120:123], v[142:145], v[170:173], v[120:123]
	v_mfma_f32_16x16x32_bf16 v[112:115], v[154:157], v[170:173], v[112:115]
	v_mfma_f32_16x16x32_bf16 v[104:107], v[142:145], v[178:181], v[104:107]
	v_mfma_f32_16x16x32_bf16 v[96:99], v[154:157], v[178:181], v[96:99]
	v_mfma_f32_16x16x32_bf16 v[88:91], v[142:145], v[186:189], v[88:91]
	v_mfma_f32_16x16x32_bf16 v[80:83], v[154:157], v[186:189], v[80:83]
	v_mfma_f32_16x16x32_bf16 v[128:131], v[150:153], v[166:169], v[128:131]
	v_mfma_f32_16x16x32_bf16 v[124:127], v[158:161], v[166:169], v[124:127]
	v_mfma_f32_16x16x32_bf16 v[120:123], v[150:153], v[174:177], v[120:123]
	v_mfma_f32_16x16x32_bf16 v[112:115], v[158:161], v[174:177], v[112:115]
	v_mfma_f32_16x16x32_bf16 v[104:107], v[150:153], v[182:185], v[104:107]
	v_mfma_f32_16x16x32_bf16 v[96:99], v[158:161], v[182:185], v[96:99]
	v_mfma_f32_16x16x32_bf16 v[88:91], v[150:153], v[190:193], v[88:91]
	v_mfma_f32_16x16x32_bf16 v[80:83], v[158:161], v[190:193], v[80:83]
	v_mfma_f32_16x16x32_bf16 v[116:119], v[194:197], v[162:165], v[116:119]
	v_mfma_f32_16x16x32_bf16 v[108:111], v[202:205], v[162:165], v[108:111]
	v_mfma_f32_16x16x32_bf16 v[100:103], v[194:197], v[170:173], v[100:103]
	v_mfma_f32_16x16x32_bf16 v[92:95], v[202:205], v[170:173], v[92:95]
	v_mfma_f32_16x16x32_bf16 v[84:87], v[194:197], v[178:181], v[84:87]
	v_mfma_f32_16x16x32_bf16 v[76:79], v[202:205], v[178:181], v[76:79]
	v_mfma_f32_16x16x32_bf16 v[72:75], v[194:197], v[186:189], v[72:75]
	v_mfma_f32_16x16x32_bf16 v[68:71], v[202:205], v[186:189], v[68:71]
	v_mfma_f32_16x16x32_bf16 v[116:119], v[198:201], v[166:169], v[116:119]
	v_mfma_f32_16x16x32_bf16 v[108:111], v[206:209], v[166:169], v[108:111]
	v_mfma_f32_16x16x32_bf16 v[100:103], v[198:201], v[174:177], v[100:103]
	v_mfma_f32_16x16x32_bf16 v[92:95], v[206:209], v[174:177], v[92:95]
	v_mfma_f32_16x16x32_bf16 v[84:87], v[198:201], v[182:185], v[84:87]
	v_mfma_f32_16x16x32_bf16 v[76:79], v[206:209], v[182:185], v[76:79]
	v_mfma_f32_16x16x32_bf16 v[72:75], v[198:201], v[190:193], v[72:75]
	v_mfma_f32_16x16x32_bf16 v[68:71], v[206:209], v[190:193], v[68:71]
	s_barrier
	s_setprio 0
	ds_read_b128 v[162:165], v148 offset:49152
	ds_read_b128 v[166:169], v148 offset:50176
	ds_read_b128 v[170:173], v148 offset:51200
	ds_read_b128 v[174:177], v148 offset:52224
	ds_read_b128 v[178:181], v148 offset:53248
	ds_read_b128 v[182:185], v148 offset:54272
	ds_read_b128 v[186:189], v148 offset:55296
	ds_read_b128 v[190:193], v148 offset:56320
	s_add_i32 s25, s54, s30
	v_lshl_add_u64 v[146:147], v[146:147], 0, s[8:9]
	s_mov_b32 m0, s25
	s_nop 0
	global_load_lds_dwordx4 v[146:147], off
	v_lshl_add_u64 v[146:147], v[210:211], 0, s[8:9]
	s_add_i32 m0, s25, 0x2000
	s_nop 0
	global_load_lds_dwordx4 v[146:147], off
	s_mov_b32 m0, s42
	v_lshl_add_u64 v[146:147], v[212:213], 0, s[8:9]
	global_load_lds_dwordx4 v[146:147], off
	v_lshl_add_u64 v[146:147], v[216:217], 0, s[8:9]
	s_mov_b32 m0, s43
	s_nop 0
	global_load_lds_dwordx4 v[146:147], off
	s_add_u32 s20, s20, 0x80080
	s_addc_u32 s21, s21, 0
	s_add_i32 s24, s24, s30
	s_mov_b32 m0, s24
	s_nop 0
	global_load_lds_dwordx4 v2, s[20:21]
	s_add_i32 m0, s24, 0x2000
	s_nop 0
	global_load_lds_dwordx4 v132, s[20:21]
	s_add_i32 s53, s53, 2
	s_add_u32 s18, s18, 0x100
	s_addc_u32 s19, s19, 0
	s_add_u32 s51, s51, 0x100
	s_addc_u32 s52, s52, 0
	s_cmp_gt_u32 s53, 29
	s_waitcnt lgkmcnt(0)
	s_waitcnt vmcnt(6)
	s_setprio 1
	s_barrier
; __device__ __forceinline__ unsigned cvt_pk_bf16(float lo, float hi) { const f32x2 v = {lo, hi}; const bf16v2_ r = __builtin_convertvector(v, bf16v2_); return __builtin_bit_cast(unsigned, r); }
; __device__ __forceinline__ int opaque_tid() { int t = threadIdx.x; asm volatile("" : "+v"(t)); return t; }
; #define PG8_MMA(ai, bj, At, Bt) do { __builtin_amdgcn_s_setprio(1); _Pragma("unroll") for (int m = 0; m < 4; ++m) _Pragma("unroll") for (int n = 0; n < 2; ++n) _Pragma("unroll") for (int k = 0; k < 2; ++k) \
;         acc[ai][bj][m][n] = __builtin_amdgcn_mfma_f32_16x16x32_bf16(Bt[n][k], At[m][k], acc[ai][bj][m][n], 0, 0, 0); __builtin_amdgcn_s_setprio(0); } while (0)
; #define PG8_WAIT_V(n) asm volatile("s_waitcnt vmcnt(" #n ")" ::: "memory")
; #define PG8_BAR __builtin_amdgcn_s_barrier()
;     __device__ __forceinline__ void operator()(const f32x4 (&acc)[2][2][4][2], const Unit& u, int wr, int wc, int ui, int) const {
;         const int ol_ = opaque_tid() & 63, fr = ol_ & 15, fq = ol_ >> 4;
;         const int row0 = u.pm * BM + wr * 64 + fr, col0 = u.pn * BM + wc * 32 + 8 * fq;
;         float r_[2][4];
;         if (rs) rs_read(r_, ui, wr, fr);
;         else {
; #pragma unroll
;             for (int ai = 0; ai < 2; ++ai)
; #pragma unroll
;                 for (int m = 0; m < 4; ++m) r_[ai][m] = 1.f;
;         }
; #pragma unroll
;         for (int ai = 0; ai < 2; ++ai)
; #pragma unroll
;             for (int m = 0; m < 4; ++m) { bf16_t* rowp = O + (size_t)(row0 + ai * HALF + m * 16) * ldc + col0; const float r = r_[ai][m];
; #pragma unroll
;                 for (int bj = 0; bj < 2; ++bj) { const f32x4 v0 = acc[ai][bj][m][0] * r, v1 = acc[ai][bj][m][1] * r;
;                     u32x4 w; w.x = cvt_pk_bf16(v0[0], v0[1]); w.y = cvt_pk_bf16(v0[2], v0[3]); w.z = cvt_pk_bf16(v1[0], v1[1]); w.w = cvt_pk_bf16(v1[2], v1[3]);
;                     *(u32x4*)(rowp + bj * HALF) = w; } }
; template <class Epi, class Sched>
; __device__ __forceinline__ void gemm_phase(LAS unsigned char* lds, const Gemm g, const Sched& S, const Epi& E) {
;     ...
;             PG8_WAIT_V(6); PG8_BAR; PG8_MMA(1, 1, At, B1); PG8_BAR;
;         }
;         E(acc, cur, wr, wc, ui, fq);
;         S.done(cur);
;         if (!has_next) break;
	v_mfma_f32_16x16x32_bf16 v[64:67], v[142:145], v[162:165], v[64:67]
	v_mfma_f32_16x16x32_bf16 v[60:63], v[154:157], v[162:165], v[60:63]
	v_mfma_f32_16x16x32_bf16 v[56:59], v[142:145], v[170:173], v[56:59]
	v_mfma_f32_16x16x32_bf16 v[48:51], v[154:157], v[170:173], v[48:51]
	v_mfma_f32_16x16x32_bf16 v[40:43], v[142:145], v[178:181], v[40:43]
	v_mfma_f32_16x16x32_bf16 v[32:35], v[154:157], v[178:181], v[32:35]
	v_mfma_f32_16x16x32_bf16 v[24:27], v[142:145], v[186:189], v[24:27]
	v_mfma_f32_16x16x32_bf16 v[16:19], v[154:157], v[186:189], v[16:19]
	v_mfma_f32_16x16x32_bf16 v[64:67], v[150:153], v[166:169], v[64:67]
	v_mfma_f32_16x16x32_bf16 v[60:63], v[158:161], v[166:169], v[60:63]
	v_mfma_f32_16x16x32_bf16 v[56:59], v[150:153], v[174:177], v[56:59]
	v_mfma_f32_16x16x32_bf16 v[48:51], v[158:161], v[174:177], v[48:51]
	v_mfma_f32_16x16x32_bf16 v[40:43], v[150:153], v[182:185], v[40:43]
	v_mfma_f32_16x16x32_bf16 v[32:35], v[158:161], v[182:185], v[32:35]
	v_mfma_f32_16x16x32_bf16 v[24:27], v[150:153], v[190:193], v[24:27]
	v_mfma_f32_16x16x32_bf16 v[16:19], v[158:161], v[190:193], v[16:19]
	v_mfma_f32_16x16x32_bf16 v[52:55], v[194:197], v[162:165], v[52:55]
	v_mfma_f32_16x16x32_bf16 v[44:47], v[202:205], v[162:165], v[44:47]
	v_mfma_f32_16x16x32_bf16 v[36:39], v[194:197], v[170:173], v[36:39]
	v_mfma_f32_16x16x32_bf16 v[28:31], v[202:205], v[170:173], v[28:31]
	v_mfma_f32_16x16x32_bf16 v[20:23], v[194:197], v[178:181], v[20:23]
	v_mfma_f32_16x16x32_bf16 v[12:15], v[202:205], v[178:181], v[12:15]
	v_mfma_f32_16x16x32_bf16 v[8:11], v[194:197], v[186:189], v[8:11]
	v_mfma_f32_16x16x32_bf16 v[4:7], v[202:205], v[186:189], v[4:7]
	v_mfma_f32_16x16x32_bf16 v[52:55], v[198:201], v[166:169], v[52:55]
	v_mfma_f32_16x16x32_bf16 v[44:47], v[206:209], v[166:169], v[44:47]
	v_mfma_f32_16x16x32_bf16 v[36:39], v[198:201], v[174:177], v[36:39]
	v_mfma_f32_16x16x32_bf16 v[28:31], v[206:209], v[174:177], v[28:31]
	v_mfma_f32_16x16x32_bf16 v[20:23], v[198:201], v[182:185], v[20:23]
	v_mfma_f32_16x16x32_bf16 v[12:15], v[206:209], v[182:185], v[12:15]
	v_mfma_f32_16x16x32_bf16 v[8:11], v[198:201], v[190:193], v[8:11]
	v_mfma_f32_16x16x32_bf16 v[4:7], v[206:209], v[190:193], v[4:7]
	s_barrier
	s_cbranch_scc0 .LBB0_1094
	s_setprio 0
	s_waitcnt vmcnt(0)
	s_lshl_b32 s1, s48, 10
	v_mov_b32_e32 v144, v0
	s_and_b32 s1, s1, 0x400
	s_add_i32 s1, s44, s1
	v_and_b32_e32 v145, 15, v144
	v_lshl_add_u32 v142, v145, 2, s1
	s_lshl_b32 s1, s47, 8
	v_lshrrev_b32_e32 v144, 1, v144
	v_and_or_b32 v144, v144, 24, s1
	ds_read2_b32 v[150:151], v142 offset1:16
	ds_read2_b32 v[152:153], v142 offset0:32 offset1:48
	ds_read2_b32 v[154:155], v142 offset0:128 offset1:144
	ds_read2_b32 v[142:143], v142 offset0:160 offset1:176
	v_or_b32_e32 v146, s39, v144
	v_or_b32_e32 v144, s38, v145
	v_lshl_add_u32 v149, s46, 8, v144
	v_ashrrev_i32_e32 v147, 31, v146
	v_mov_b64_e32 v[144:145], s[92:93]
	v_mad_i64_i32 v[156:157], s[18:19], v149, s11, v[144:145]
	v_lshlrev_b64 v[146:147], 1, v[146:147]
	s_waitcnt lgkmcnt(0)
	v_pk_mul_f32 v[130:131], v[130:131], v[150:151] op_sel_hi:[1,0]
	v_pk_mul_f32 v[128:129], v[128:129], v[150:151] op_sel_hi:[1,0]
	v_pk_mul_f32 v[158:159], v[126:127], v[150:151] op_sel_hi:[1,0]
	v_pk_mul_f32 v[126:127], v[124:125], v[150:151] op_sel_hi:[1,0]
	v_lshl_add_u64 v[156:157], v[156:157], 0, v[146:147]
	v_cvt_pk_bf16_f32 v124, v128, v129
	v_cvt_pk_bf16_f32 v125, v130, v131
	v_cvt_pk_bf16_f32 v126, v126, v127
	v_cvt_pk_bf16_f32 v127, v158, v159
	global_store_dwordx4 v[156:157], v[124:127], off
	v_pk_mul_f32 v[118:119], v[118:119], v[150:151] op_sel_hi:[1,0]
	v_pk_mul_f32 v[116:117], v[116:117], v[150:151] op_sel_hi:[1,0]
	v_pk_mul_f32 v[124:125], v[110:111], v[150:151] op_sel_hi:[1,0]
	v_pk_mul_f32 v[110:111], v[108:109], v[150:151] op_sel_hi:[1,0]
	v_cvt_pk_bf16_f32 v108, v116, v117
	v_cvt_pk_bf16_f32 v109, v118, v119
	v_cvt_pk_bf16_f32 v110, v110, v111
	v_cvt_pk_bf16_f32 v111, v124, v125
	global_store_dwordx4 v[156:157], v[108:111], off offset:256
	v_mov_b32_e32 v118, v151
	v_pk_mul_f32 v[114:115], v[114:115], v[118:119] op_sel_hi:[1,0]
	v_or_b32_e32 v108, 16, v149
	v_mad_i64_i32 v[108:109], s[18:19], v108, s11, v[144:145]
	v_lshl_add_u64 v[116:117], v[108:109], 0, v[146:147]
	v_pk_mul_f32 v[110:111], v[122:123], v[118:119] op_sel_hi:[1,0]
	v_pk_mul_f32 v[108:109], v[120:121], v[118:119] op_sel_hi:[1,0]
	v_pk_mul_f32 v[112:113], v[112:113], v[118:119] op_sel_hi:[1,0]
	v_cvt_pk_bf16_f32 v108, v108, v109
	v_cvt_pk_bf16_f32 v109, v110, v111
	v_cvt_pk_bf16_f32 v110, v112, v113
	v_cvt_pk_bf16_f32 v111, v114, v115
	global_store_dwordx4 v[116:117], v[108:111], off
	v_pk_mul_f32 v[102:103], v[102:103], v[118:119] op_sel_hi:[1,0]
	v_pk_mul_f32 v[100:101], v[100:101], v[118:119] op_sel_hi:[1,0]
	v_pk_mul_f32 v[108:109], v[94:95], v[118:119] op_sel_hi:[1,0]
	v_pk_mul_f32 v[94:95], v[92:93], v[118:119] op_sel_hi:[1,0]
	v_cvt_pk_bf16_f32 v92, v100, v101
	v_cvt_pk_bf16_f32 v93, v102, v103
	v_cvt_pk_bf16_f32 v94, v94, v95
	v_cvt_pk_bf16_f32 v95, v108, v109
	global_store_dwordx4 v[116:117], v[92:95], off offset:256
	v_pk_mul_f32 v[98:99], v[98:99], v[152:153] op_sel_hi:[1,0]
	v_pk_mul_f32 v[96:97], v[96:97], v[152:153] op_sel_hi:[1,0]
	v_or_b32_e32 v92, 32, v149
	v_mad_i64_i32 v[92:93], s[18:19], v92, s11, v[144:145]
	v_lshl_add_u64 v[100:101], v[92:93], 0, v[146:147]
	v_pk_mul_f32 v[94:95], v[106:107], v[152:153] op_sel_hi:[1,0]
	v_pk_mul_f32 v[92:93], v[104:105], v[152:153] op_sel_hi:[1,0]
	v_pk_mul_f32 v[86:87], v[86:87], v[152:153] op_sel_hi:[1,0]
	v_cvt_pk_bf16_f32 v92, v92, v93
	v_cvt_pk_bf16_f32 v93, v94, v95
	v_cvt_pk_bf16_f32 v94, v96, v97
	v_cvt_pk_bf16_f32 v95, v98, v99
; __device__ __forceinline__ unsigned cvt_pk_bf16(float lo, float hi) { const f32x2 v = {lo, hi}; const bf16v2_ r = __builtin_convertvector(v, bf16v2_); return __builtin_bit_cast(unsigned, r); }
; __device__ __forceinline__ int opaque_tid() { int t = threadIdx.x; asm volatile("" : "+v"(t)); return t; }
; #define PG8_WAIT_V(n) asm volatile("s_waitcnt vmcnt(" #n ")" ::: "memory")
; #define PG8_BAR __builtin_amdgcn_s_barrier()
;     __device__ __forceinline__ void operator()(const f32x4 (&acc)[2][2][4][2], const Unit& u, int wr, int wc, int ui, int) const {
;         const int ol_ = opaque_tid() & 63, fr = ol_ & 15, fq = ol_ >> 4;
;         const int row0 = u.pm * BM + wr * 64 + fr, col0 = u.pn * BM + wc * 32 + 8 * fq;
;         float r_[2][4];
;         if (rs) rs_read(r_, ui, wr, fr);
;         else {
; #pragma unroll
;             for (int ai = 0; ai < 2; ++ai)
; #pragma unroll
;                 for (int m = 0; m < 4; ++m) r_[ai][m] = 1.f;
;         }
; #pragma unroll
;         for (int ai = 0; ai < 2; ++ai)
; #pragma unroll
;             for (int m = 0; m < 4; ++m) { bf16_t* rowp = O + (size_t)(row0 + ai * HALF + m * 16) * ldc + col0; const float r = r_[ai][m];
; #pragma unroll
;                 for (int bj = 0; bj < 2; ++bj) { const f32x4 v0 = acc[ai][bj][m][0] * r, v1 = acc[ai][bj][m][1] * r;
;                     u32x4 w; w.x = cvt_pk_bf16(v0[0], v0[1]); w.y = cvt_pk_bf16(v0[2], v0[3]); w.z = cvt_pk_bf16(v1[0], v1[1]); w.w = cvt_pk_bf16(v1[2], v1[3]);
;                     *(u32x4*)(rowp + bj * HALF) = w; } }
; template <class Epi, class Sched>
; __device__ __forceinline__ void gemm_phase(LAS unsigned char* lds, const Gemm g, const Sched& S, const Epi& E) {
;     ...
;         E(acc, cur, wr, wc, ui, fq);
;         S.done(cur);
;         if (!has_next) break;
; #pragma unroll
;         for (int a = 0; a < 2; ++a)
; #pragma unroll
;             for (int b = 0; b < 2; ++b)
; #pragma unroll
;                 for (int m = 0; m < 4; ++m)
; #pragma unroll
;                     for (int n = 0; n < 2; ++n) acc[a][b][m][n] = (f32x4){0.f, 0.f, 0.f, 0.f};
;         cur = nxt; cA = nA; cB = nB; ++ui;
;     }
;     PG8_WAIT_V(0);
;     if (wr == 0) PG8_BAR;
;     PG8_BAR;
	global_store_dwordx4 v[100:101], v[92:95], off
	v_pk_mul_f32 v[84:85], v[84:85], v[152:153] op_sel_hi:[1,0]
	v_pk_mul_f32 v[66:67], v[66:67], v[154:155] op_sel_hi:[1,0]
	v_pk_mul_f32 v[92:93], v[78:79], v[152:153] op_sel_hi:[1,0]
	v_pk_mul_f32 v[78:79], v[76:77], v[152:153] op_sel_hi:[1,0]
	v_cvt_pk_bf16_f32 v76, v84, v85
	v_cvt_pk_bf16_f32 v77, v86, v87
	v_cvt_pk_bf16_f32 v78, v78, v79
	v_cvt_pk_bf16_f32 v79, v92, v93
	global_store_dwordx4 v[100:101], v[76:79], off offset:256
	v_mov_b32_e32 v86, v153
	v_pk_mul_f32 v[82:83], v[82:83], v[86:87] op_sel_hi:[1,0]
	v_or_b32_e32 v76, 48, v149
	v_mad_i64_i32 v[76:77], s[18:19], v76, s11, v[144:145]
	v_lshl_add_u64 v[84:85], v[76:77], 0, v[146:147]
	v_pk_mul_f32 v[78:79], v[90:91], v[86:87] op_sel_hi:[1,0]
	v_pk_mul_f32 v[76:77], v[88:89], v[86:87] op_sel_hi:[1,0]
	v_pk_mul_f32 v[80:81], v[80:81], v[86:87] op_sel_hi:[1,0]
	v_cvt_pk_bf16_f32 v76, v76, v77
	v_cvt_pk_bf16_f32 v77, v78, v79
	v_cvt_pk_bf16_f32 v78, v80, v81
	v_cvt_pk_bf16_f32 v79, v82, v83
	global_store_dwordx4 v[84:85], v[76:79], off
	v_pk_mul_f32 v[74:75], v[74:75], v[86:87] op_sel_hi:[1,0]
	v_pk_mul_f32 v[72:73], v[72:73], v[86:87] op_sel_hi:[1,0]
	v_pk_mul_f32 v[76:77], v[70:71], v[86:87] op_sel_hi:[1,0]
	v_pk_mul_f32 v[70:71], v[68:69], v[86:87] op_sel_hi:[1,0]
	v_cvt_pk_bf16_f32 v68, v72, v73
	v_cvt_pk_bf16_f32 v69, v74, v75
	v_cvt_pk_bf16_f32 v70, v70, v71
	v_cvt_pk_bf16_f32 v71, v76, v77
	global_store_dwordx4 v[84:85], v[68:71], off offset:256
	v_pk_mul_f32 v[64:65], v[64:65], v[154:155] op_sel_hi:[1,0]
	v_pk_mul_f32 v[54:55], v[54:55], v[154:155] op_sel_hi:[1,0]
	v_add_u32_e32 v68, 0x80, v149
	v_mad_i64_i32 v[68:69], s[18:19], v68, s11, v[144:145]
	v_pk_mul_f32 v[70:71], v[62:63], v[154:155] op_sel_hi:[1,0]
	v_pk_mul_f32 v[62:63], v[60:61], v[154:155] op_sel_hi:[1,0]
	v_lshl_add_u64 v[68:69], v[68:69], 0, v[146:147]
	v_cvt_pk_bf16_f32 v60, v64, v65
	v_cvt_pk_bf16_f32 v61, v66, v67
	v_cvt_pk_bf16_f32 v62, v62, v63
	v_cvt_pk_bf16_f32 v63, v70, v71
	global_store_dwordx4 v[68:69], v[60:63], off
	v_pk_mul_f32 v[52:53], v[52:53], v[154:155] op_sel_hi:[1,0]
	v_pk_mul_f32 v[34:35], v[34:35], v[142:143] op_sel_hi:[1,0]
	v_pk_mul_f32 v[60:61], v[46:47], v[154:155] op_sel_hi:[1,0]
	v_pk_mul_f32 v[46:47], v[44:45], v[154:155] op_sel_hi:[1,0]
	v_cvt_pk_bf16_f32 v44, v52, v53
	v_cvt_pk_bf16_f32 v45, v54, v55
	v_cvt_pk_bf16_f32 v46, v46, v47
	v_cvt_pk_bf16_f32 v47, v60, v61
	global_store_dwordx4 v[68:69], v[44:47], off offset:256
	v_mov_b32_e32 v54, v155
	v_pk_mul_f32 v[50:51], v[50:51], v[54:55] op_sel_hi:[1,0]
	v_add_u32_e32 v44, 0x90, v149
	v_mad_i64_i32 v[44:45], s[18:19], v44, s11, v[144:145]
	v_lshl_add_u64 v[52:53], v[44:45], 0, v[146:147]
	v_pk_mul_f32 v[46:47], v[58:59], v[54:55] op_sel_hi:[1,0]
	v_pk_mul_f32 v[44:45], v[56:57], v[54:55] op_sel_hi:[1,0]
	v_pk_mul_f32 v[48:49], v[48:49], v[54:55] op_sel_hi:[1,0]
	v_cvt_pk_bf16_f32 v44, v44, v45
	v_cvt_pk_bf16_f32 v45, v46, v47
	v_cvt_pk_bf16_f32 v46, v48, v49
	v_cvt_pk_bf16_f32 v47, v50, v51
	global_store_dwordx4 v[52:53], v[44:47], off
	v_pk_mul_f32 v[38:39], v[38:39], v[54:55] op_sel_hi:[1,0]
	v_pk_mul_f32 v[36:37], v[36:37], v[54:55] op_sel_hi:[1,0]
	v_pk_mul_f32 v[44:45], v[30:31], v[54:55] op_sel_hi:[1,0]
	v_pk_mul_f32 v[30:31], v[28:29], v[54:55] op_sel_hi:[1,0]
	v_cvt_pk_bf16_f32 v28, v36, v37
	v_cvt_pk_bf16_f32 v29, v38, v39
	v_cvt_pk_bf16_f32 v30, v30, v31
	v_cvt_pk_bf16_f32 v31, v44, v45
	global_store_dwordx4 v[52:53], v[28:31], off offset:256
	v_pk_mul_f32 v[32:33], v[32:33], v[142:143] op_sel_hi:[1,0]
	v_pk_mul_f32 v[22:23], v[22:23], v[142:143] op_sel_hi:[1,0]
	v_add_u32_e32 v28, 0xa0, v149
	v_mad_i64_i32 v[28:29], s[18:19], v28, s11, v[144:145]
	v_lshl_add_u64 v[36:37], v[28:29], 0, v[146:147]
	v_pk_mul_f32 v[30:31], v[42:43], v[142:143] op_sel_hi:[1,0]
	v_pk_mul_f32 v[28:29], v[40:41], v[142:143] op_sel_hi:[1,0]
	v_pk_mul_f32 v[20:21], v[20:21], v[142:143] op_sel_hi:[1,0]
	v_cvt_pk_bf16_f32 v28, v28, v29
	v_cvt_pk_bf16_f32 v29, v30, v31
	v_cvt_pk_bf16_f32 v30, v32, v33
	v_cvt_pk_bf16_f32 v31, v34, v35
	global_store_dwordx4 v[36:37], v[28:31], off
	s_and_b64 vcc, exec, s[40:41]
	s_mov_b32 s47, s0
	v_pk_mul_f32 v[28:29], v[14:15], v[142:143] op_sel_hi:[1,0]
	v_pk_mul_f32 v[14:15], v[12:13], v[142:143] op_sel_hi:[1,0]
	v_cvt_pk_bf16_f32 v12, v20, v21
	v_cvt_pk_bf16_f32 v13, v22, v23
	v_cvt_pk_bf16_f32 v14, v14, v15
	v_cvt_pk_bf16_f32 v15, v28, v29
	global_store_dwordx4 v[36:37], v[12:15], off offset:256
	v_mov_b32_e32 v22, v143
	v_pk_mul_f32 v[18:19], v[18:19], v[22:23] op_sel_hi:[1,0]
	v_add_u32_e32 v12, 0xb0, v149
	v_mad_i64_i32 v[12:13], s[18:19], v12, s11, v[144:145]
	v_lshl_add_u64 v[20:21], v[12:13], 0, v[146:147]
	v_pk_mul_f32 v[14:15], v[26:27], v[22:23] op_sel_hi:[1,0]
	v_pk_mul_f32 v[12:13], v[24:25], v[22:23] op_sel_hi:[1,0]
	v_pk_mul_f32 v[16:17], v[16:17], v[22:23] op_sel_hi:[1,0]
	v_cvt_pk_bf16_f32 v12, v12, v13
	v_cvt_pk_bf16_f32 v13, v14, v15
	v_cvt_pk_bf16_f32 v14, v16, v17
	v_cvt_pk_bf16_f32 v15, v18, v19
	global_store_dwordx4 v[20:21], v[12:15], off
	v_pk_mul_f32 v[10:11], v[10:11], v[22:23] op_sel_hi:[1,0]
	v_pk_mul_f32 v[8:9], v[8:9], v[22:23] op_sel_hi:[1,0]
	v_pk_mul_f32 v[12:13], v[6:7], v[22:23] op_sel_hi:[1,0]
	v_pk_mul_f32 v[6:7], v[4:5], v[22:23] op_sel_hi:[1,0]
	v_cvt_pk_bf16_f32 v4, v8, v9
	v_cvt_pk_bf16_f32 v5, v10, v11
	v_cvt_pk_bf16_f32 v6, v6, v7
	v_cvt_pk_bf16_f32 v7, v12, v13
	s_mov_b32 s46, s4
	s_mov_b64 s[20:21], s[14:15]
	s_mov_b64 s[18:19], s[6:7]
	s_mov_b32 s48, s45
	global_store_dwordx4 v[20:21], v[4:7], off offset:256
	s_cbranch_vccz .LBB0_1089
	s_waitcnt vmcnt(0)
	s_cmpk_gt_u32 s2, 0xff
	s_cbranch_scc1 .LBB0_1098
	s_barrier

; __device__ __forceinline__ int opaque_tid() { int t = threadIdx.x; asm volatile("" : "+v"(t)); return t; }
; #define PG8_STAGE(bufoff, gbase, voff) do { _Pragma("unroll") for (int _i = 0; _i < 2; ++_i) \
;         __builtin_amdgcn_global_load_lds((const unsigned*)((const char*)(gbase) + (voff)[_i]), (LAS unsigned*)(lds + (bufoff) + ldsw + _i * 8192), 16, 0, 0); } while (0)
; #define PG8_BAR __builtin_amdgcn_s_barrier()
; template <class Epi, class Sched>
; __device__ __forceinline__ void gemm_phase(LAS unsigned char* lds, const Gemm g, const Sched& S, const Epi& E) {
;     const int tid = opaque_tid(), wid = __builtin_amdgcn_readfirstlane(tid >> 6), lane = tid & 63, wr = wid >> 2, wc = wid & 3, fr = lane & 15, fq = lane >> 4;
;     const int K = g.K, nt = K / BK, lda = g.lda;
;     unsigned voffA[2], voffB[2];
; #pragma unroll
;     for (int i = 0; i < 2; ++i) { int R, C; stage_rc(tid * 16 + i * 8192, R, C); const int Rb = Epi::PERM ? ((R & ~31) + perm32(R & 31)) : R;
;         voffA[i] = (unsigned)(R * lda + C) * 2u; voffB[i] = (unsigned)(Rb * K + C) * 2u; }
;     const size_t kstep = (size_t)(BK * 2);
;     const size_t hstepA = (size_t)HALF * lda * 2, hstepB = (size_t)HALF * K * 2;
;     const size_t tstepA = 2 * hstepA, tstepB = 2 * hstepB;
;     const unsigned ldsw = (unsigned)wid * 1024u;
;     const int aoff = lds_byte(wr * 64 + fr, fq * 8), boff = lds_byte(wc * 32 + fr, fq * 8);
;     ...
;     Unit cur, nxt; int ui = 0;
;     if (!S.next(0, cur)) return;
;     f32x4 acc[2][2][4][2];
; #pragma unroll
;     for (int a = 0; a < 2; ++a)
; #pragma unroll
;         for (int b = 0; b < 2; ++b)
; #pragma unroll
;             for (int m = 0; m < 4; ++m)
; #pragma unroll
;                 for (int n = 0; n < 2; ++n) acc[a][b][m][n] = (f32x4){0.f, 0.f, 0.f, 0.f};
;     bf16x8 At[4][2], B0[2][2], B1[2][2];
;     const char* cA = (const char*)g.A + (size_t)cur.pm * tstepA; const char* cB = (const char*)g.Bt + (size_t)cur.pn * tstepB;
;     S.a_ready(cur);
;     PG8_STAGE(PG8_SB(0, 0), cB, voffB); PG8_STAGE(PG8_SA(0, 0), cA, voffA); PG8_STAGE(PG8_SB(0, 1), cB + hstepB, voffB); PG8_STAGE(PG8_SA(0, 1), cA + hstepA, voffA);
;     if (wr == 1) PG8_BAR;
;     PG8_WAIT_V(4); PG8_BAR;
;     PG8_STAGE(PG8_SB(1, 0), cB + kstep, voffB); PG8_STAGE(PG8_SA(1, 0), cA + kstep, voffA); PG8_STAGE(PG8_SB(1, 1), cB + hstepB + kstep, voffB);
;     PG8_WAIT_V(6); PG8_BAR;
.LBB0_1388:
	v_lshl_add_u64 v[10:11], s[20:21], 0, v[2:3]
	v_mov_b32_e32 v193, v3
	v_readlane_b32 s6, v254, 5
	s_lshl_b32 s0, s0, 5
	v_lshl_add_u64 v[12:13], s[20:21], 0, v[192:193]
	v_mov_b32_e32 v197, v3
	v_readlane_b32 s7, v254, 6
	v_and_b32_e32 v18, 48, v1
	v_lshlrev_b32_e32 v19, 6, v1
	s_movk_i32 s4, 0x3c0
	v_lshlrev_b32_e32 v1, 2, v1
	s_and_b32 s39, s0, 0x60
	s_add_i32 m0, s31, 0x18000
	v_lshl_add_u64 v[10:11], v[10:11], 0, s[8:9]
	v_lshl_add_u64 v[14:15], s[6:7], 0, v[196:197]
	v_mov_b32_e32 v195, v3
	s_lshl_b32 s38, s1, 6
	s_lshl_b32 s1, s1, 13
	v_and_or_b32 v18, v19, s4, v18
	v_and_b32_e32 v1, 32, v1
	s_lshl_b32 s0, s39, 7
	s_waitcnt vmcnt(2)
	s_barrier
	global_load_lds_dwordx4 v[10:11], off
	v_lshl_add_u64 v[10:11], v[12:13], 0, s[8:9]
	s_add_i32 m0, s31, 0x1a000
	s_add_i32 s42, s31, 0x8000
	s_add_i32 s43, s31, 0xa000
	v_lshl_add_u64 v[16:17], s[6:7], 0, v[194:195]
	v_bitop3_b32 v19, v18, s1, v1 bitop3:0xde
	v_bitop3_b32 v1, s0, v18, v1 bitop3:0xf6
	global_load_lds_dwordx4 v[10:11], off
	v_lshl_add_u64 v[10:11], v[14:15], 0, s[8:9]
	s_mov_b32 m0, s42
	s_add_u32 s0, s20, 0x80080
	global_load_lds_dwordx4 v[10:11], off
	v_lshl_add_u64 v[10:11], v[16:17], 0, s[8:9]
	s_mov_b32 m0, s43
	s_addc_u32 s1, s21, 0
	global_load_lds_dwordx4 v[10:11], off
	s_add_i32 m0, s31, 0x1c000
	v_lshl_add_u64 v[10:11], s[0:1], 0, v[2:3]
	global_load_lds_dwordx4 v[10:11], off
	v_lshl_add_u64 v[10:11], s[0:1], 0, v[192:193]
	s_add_i32 m0, s31, 0x1e000
	v_readlane_b32 s0, v254, 27
	global_load_lds_dwordx4 v[10:11], off
	v_lshlrev_b32_e32 v10, 15, v8
	v_and_b32_e32 v10, 0xffff0000, v10
	v_lshl_add_u32 v7, v7, 12, v10
	v_and_b32_e32 v8, 1, v8
	v_lshl_or_b32 v7, v8, 6, v7
	v_lshl_add_u32 v198, v9, 1, v7
	v_lshlrev_b32_e32 v7, 15, v4
	v_and_b32_e32 v7, 0xffff0000, v7
	s_waitcnt vmcnt(0)
	v_lshl_add_u32 v5, v5, 12, v7
	v_and_b32_e32 v4, 1, v4
	v_lshl_or_b32 v4, v4, 6, v5
	v_mov_b32_e32 v199, v3
	v_lshl_add_u32 v200, v6, 1, v4
	v_mov_b32_e32 v201, v3
	s_mov_b32 s44, 0
	v_add_u32_e32 v224, 0, v19
	v_readlane_b32 s45, v254, 1
	s_mov_b32 s46, s0
	s_barrier
	v_readlane_b32 s1, v254, 28

; #define PG8_STAGE(bufoff, gbase, voff) do { _Pragma("unroll") for (int _i = 0; _i < 2; ++_i) \
;         __builtin_amdgcn_global_load_lds((const unsigned*)((const char*)(gbase) + (voff)[_i]), (LAS unsigned*)(lds + (bufoff) + ldsw + _i * 8192), 16, 0, 0); } while (0)
; #define PG8_LDA(dst, b, h) do { _Pragma("unroll") for (int m = 0; m < 4; ++m) _Pragma("unroll") for (int k = 0; k < 2; ++k) dst[m][k] = *(const LAS bf16x8*)(lds + PG8_SA(b, h) + aoff + m * 2048 + k * 1024); } while (0)
; #define PG8_LDB(dst, b, h) do { _Pragma("unroll") for (int n = 0; n < 2; ++n) _Pragma("unroll") for (int k = 0; k < 2; ++k) dst[n][k] = *(const LAS bf16x8*)(lds + PG8_SB(b, h) + boff + n * 2048 + k * 1024); } while (0)
; #define PG8_WAIT_V(n) asm volatile("s_waitcnt vmcnt(" #n ")" ::: "memory")
; #define PG8_WAIT_L(n) asm volatile("s_waitcnt lgkmcnt(" #n ")" ::: "memory")
; #define PG8_BAR __builtin_amdgcn_s_barrier()
; #define PG8_SCHED __builtin_amdgcn_sched_barrier(0)
; template <class Epi, class Sched>
; __device__ __forceinline__ void gemm_phase(LAS unsigned char* lds, const Gemm g, const Sched& S, const Epi& E) {
;     ...
;         const bool has_next = S.next(ui + 1, nxt);
;         const char* nA = has_next ? (const char*)g.A + (size_t)nxt.pm * tstepA : cA; const char* nB = has_next ? (const char*)g.Bt + (size_t)nxt.pn * tstepB : cB;
;         for (int t = 0; t < nt; t += 2) {
;             const bool last = (t == nt - 2);
;             const char* a1 = cA + (size_t)(t + 1) * kstep;
;             const char* a2 = last ? nA : cA + (size_t)(t + 2) * kstep; const char* b2 = last ? nB : cB + (size_t)(t + 2) * kstep;
;             const char* a3 = a2 + kstep; const char* b3 = b2 + kstep;
;             if (last && has_next) S.a_ready(nxt);
;             PG8_LDB(B0, 0, 0); PG8_SCHED; PG8_LDA(At, 0, 0); PG8_STAGE(PG8_SA(1, 1), a1 + hstepA, voffA);
;             PG8_WAIT_L(8); PG8_BAR; PG8_WAIT_L(0); PG8_MMA(0, 0, At, B0); PG8_BAR; PG8_SCHED;
;             PG8_LDB(B1, 0, 1); PG8_STAGE(PG8_SB(0, 0), b2, voffB);
;             PG8_BAR; PG8_WAIT_L(0); PG8_MMA(0, 1, At, B1); PG8_BAR;
;             PG8_LDA(At, 0, 1); PG8_STAGE(PG8_SA(0, 0), a2, voffA);
;             PG8_BAR; PG8_WAIT_L(0); PG8_MMA(1, 0, At, B0); PG8_BAR; PG8_SCHED;
;             PG8_STAGE(PG8_SB(0, 1), b2 + hstepB, voffB);
;             PG8_WAIT_V(6); PG8_BAR; PG8_MMA(1, 1, At, B1); PG8_BAR;
.LBB0_1395:
	v_mov_b64_e32 v[4:5], 0x400
	s_ashr_i32 s15, s14, 31
	v_cmp_lt_i64_e32 vcc, s[4:5], v[4:5]
	s_lshl_b64 s[4:5], s[14:15], 20
	v_readlane_b32 s48, v252, 0
	v_readlane_b32 s49, v252, 1
	s_add_u32 s4, s48, s4
	s_addc_u32 s5, s49, s5
	s_and_b64 s[18:19], vcc, exec
	s_cselect_b32 s15, s5, s7
	s_cselect_b32 s47, s4, s6
	s_ashr_i32 s1, s0, 31
	s_lshl_b64 s[18:19], s[0:1], 20
	s_add_u32 s18, s28, s18
	s_addc_u32 s19, s29, s19
	s_and_b64 s[24:25], vcc, exec
	s_cselect_b32 s1, s19, s21
	s_cselect_b32 s48, s18, s20
	s_add_u32 s6, s6, 0x80080
	s_addc_u32 s7, s7, 0
	v_readlane_b32 s50, v252, 2
	v_readlane_b32 s51, v252, 3
	s_add_u32 s49, s20, 0x100
	s_addc_u32 s50, s21, 0
	s_mov_b32 s51, -2
	s_setprio 0
	s_add_u32 s20, s6, 0xfff80080
	s_addc_u32 s21, s7, -1
	s_add_i32 s52, 0, 0x10000
	v_add_u32_e32 v144, s52, v1
	ds_read_b128 v[132:135], v144
	ds_read_b128 v[136:139], v144 offset:1024
	ds_read_b128 v[140:143], v144 offset:2048
	ds_read_b128 v[144:147], v144 offset:3072
	s_cmp_eq_u32 s51, 28
	s_cselect_b32 s25, s15, s21
	s_cselect_b32 s24, s47, s20
	s_cselect_b32 s21, s1, s50
	s_cselect_b32 s20, s48, s49
	ds_read_b128 v[148:151], v224
	ds_read_b128 v[152:155], v224 offset:1024
	ds_read_b128 v[156:159], v224 offset:2048
	ds_read_b128 v[160:163], v224 offset:3072
	ds_read_b128 v[164:167], v224 offset:4096
	ds_read_b128 v[168:171], v224 offset:5120
	ds_read_b128 v[172:175], v224 offset:6144
	ds_read_b128 v[176:179], v224 offset:7168
	s_add_i32 s54, 0, 0x14000
	v_add_u32_e32 v202, s54, v1
	ds_read_b128 v[180:183], v202
	ds_read_b128 v[184:187], v202 offset:1024
	ds_read_b128 v[188:191], v202 offset:2048
	ds_read_b128 v[202:205], v202 offset:3072
	s_add_i32 m0, s31, 0xc000
	s_nop 0
	global_load_lds_dwordx4 v198, s[6:7]
	s_add_i32 m0, s31, 0xe000
	s_nop 0
	global_load_lds_dwordx4 v200, s[6:7]
	s_waitcnt lgkmcnt(0)
	s_setprio 1
	s_barrier
	v_mfma_f32_16x16x32_bf16 v[128:131], v[132:135], v[148:151], 0
	v_mfma_f32_16x16x32_bf16 v[124:127], v[140:143], v[148:151], 0
	v_mfma_f32_16x16x32_bf16 v[112:115], v[132:135], v[156:159], 0
	v_mfma_f32_16x16x32_bf16 v[108:111], v[140:143], v[156:159], 0
	v_mfma_f32_16x16x32_bf16 v[100:103], v[132:135], v[164:167], 0
	v_mfma_f32_16x16x32_bf16 v[92:95], v[140:143], v[164:167], 0
	v_mfma_f32_16x16x32_bf16 v[84:87], v[132:135], v[172:175], 0
	v_mfma_f32_16x16x32_bf16 v[76:79], v[140:143], v[172:175], 0
	v_mfma_f32_16x16x32_bf16 v[128:131], v[136:139], v[152:155], v[128:131]
	v_mfma_f32_16x16x32_bf16 v[124:127], v[144:147], v[152:155], v[124:127]
	v_mfma_f32_16x16x32_bf16 v[112:115], v[136:139], v[160:163], v[112:115]
	v_mfma_f32_16x16x32_bf16 v[108:111], v[144:147], v[160:163], v[108:111]
	v_mfma_f32_16x16x32_bf16 v[100:103], v[136:139], v[168:171], v[100:103]
	v_mfma_f32_16x16x32_bf16 v[92:95], v[144:147], v[168:171], v[92:95]
	v_mfma_f32_16x16x32_bf16 v[84:87], v[136:139], v[176:179], v[84:87]
	v_mfma_f32_16x16x32_bf16 v[76:79], v[144:147], v[176:179], v[76:79]
	v_mfma_f32_16x16x32_bf16 v[120:123], v[180:183], v[148:151], 0
	v_mfma_f32_16x16x32_bf16 v[116:119], v[188:191], v[148:151], 0
	v_mfma_f32_16x16x32_bf16 v[104:107], v[180:183], v[156:159], 0
	v_mfma_f32_16x16x32_bf16 v[96:99], v[188:191], v[156:159], 0
	v_mfma_f32_16x16x32_bf16 v[88:91], v[180:183], v[164:167], 0
	v_mfma_f32_16x16x32_bf16 v[80:83], v[188:191], v[164:167], 0
	v_mfma_f32_16x16x32_bf16 v[72:75], v[180:183], v[172:175], 0
	v_mfma_f32_16x16x32_bf16 v[68:71], v[188:191], v[172:175], 0
	v_mfma_f32_16x16x32_bf16 v[120:123], v[184:187], v[152:155], v[120:123]
	v_mfma_f32_16x16x32_bf16 v[116:119], v[202:205], v[152:155], v[116:119]
	v_mfma_f32_16x16x32_bf16 v[104:107], v[184:187], v[160:163], v[104:107]
	v_mfma_f32_16x16x32_bf16 v[96:99], v[202:205], v[160:163], v[96:99]
	v_mfma_f32_16x16x32_bf16 v[88:91], v[184:187], v[168:171], v[88:91]
	v_mfma_f32_16x16x32_bf16 v[80:83], v[202:205], v[168:171], v[80:83]
	v_mfma_f32_16x16x32_bf16 v[72:75], v[184:187], v[176:179], v[72:75]
	v_mfma_f32_16x16x32_bf16 v[68:71], v[202:205], v[176:179], v[68:71]
	s_barrier
	s_setprio 0
	ds_read_b128 v[148:151], v224 offset:16384
	ds_read_b128 v[152:155], v224 offset:17408
	ds_read_b128 v[156:159], v224 offset:18432
	ds_read_b128 v[160:163], v224 offset:19456
	ds_read_b128 v[164:167], v224 offset:20480
	ds_read_b128 v[168:171], v224 offset:21504
	ds_read_b128 v[172:175], v224 offset:22528
	ds_read_b128 v[176:179], v224 offset:23552
	s_add_i32 s52, s52, s30
	v_lshl_add_u64 v[206:207], s[20:21], 0, v[2:3]
	s_mov_b32 m0, s52
	s_nop 0
	global_load_lds_dwordx4 v[206:207], off
	v_lshl_add_u64 v[208:209], s[20:21], 0, v[192:193]
	s_add_i32 m0, s52, 0x2000
	s_nop 0
	global_load_lds_dwordx4 v[208:209], off
	s_mov_b32 m0, s31
	v_lshl_add_u64 v[210:211], s[24:25], 0, v[196:197]
	global_load_lds_dwordx4 v[210:211], off
	v_lshl_add_u64 v[212:213], s[24:25], 0, v[194:195]
	s_mov_b32 m0, s35
	s_nop 0
	global_load_lds_dwordx4 v[212:213], off
	s_add_u32 s52, s20, 0x80000
	s_addc_u32 s53, s21, 0
	s_add_i32 s54, s54, s30
	s_mov_b32 m0, s54
	s_nop 0
	global_load_lds_dwordx4 v2, s[52:53]
	s_add_i32 m0, s54, 0x2000
	s_nop 0
	global_load_lds_dwordx4 v192, s[52:53]
	s_waitcnt lgkmcnt(0)
	s_setprio 1
	s_barrier
; #define PG8_STAGE(bufoff, gbase, voff) do { _Pragma("unroll") for (int _i = 0; _i < 2; ++_i) \
;         __builtin_amdgcn_global_load_lds((const unsigned*)((const char*)(gbase) + (voff)[_i]), (LAS unsigned*)(lds + (bufoff) + ldsw + _i * 8192), 16, 0, 0); } while (0)
; #define PG8_LDA(dst, b, h) do { _Pragma("unroll") for (int m = 0; m < 4; ++m) _Pragma("unroll") for (int k = 0; k < 2; ++k) dst[m][k] = *(const LAS bf16x8*)(lds + PG8_SA(b, h) + aoff + m * 2048 + k * 1024); } while (0)
; #define PG8_LDB(dst, b, h) do { _Pragma("unroll") for (int n = 0; n < 2; ++n) _Pragma("unroll") for (int k = 0; k < 2; ++k) dst[n][k] = *(const LAS bf16x8*)(lds + PG8_SB(b, h) + boff + n * 2048 + k * 1024); } while (0)
; #define PG8_MMA(ai, bj, At, Bt) do { __builtin_amdgcn_s_setprio(1); _Pragma("unroll") for (int m = 0; m < 4; ++m) _Pragma("unroll") for (int n = 0; n < 2; ++n) _Pragma("unroll") for (int k = 0; k < 2; ++k) \
;         acc[ai][bj][m][n] = __builtin_amdgcn_mfma_f32_16x16x32_bf16(Bt[n][k], At[m][k], acc[ai][bj][m][n], 0, 0, 0); __builtin_amdgcn_s_setprio(0); } while (0)
; #define PG8_WAIT_V(n) asm volatile("s_waitcnt vmcnt(" #n ")" ::: "memory")
; #define PG8_WAIT_L(n) asm volatile("s_waitcnt lgkmcnt(" #n ")" ::: "memory")
; #define PG8_BAR __builtin_amdgcn_s_barrier()
; #define PG8_SCHED __builtin_amdgcn_sched_barrier(0)
; template <class Epi, class Sched>
; __device__ __forceinline__ void gemm_phase(LAS unsigned char* lds, const Gemm g, const Sched& S, const Epi& E) {
;     ...
;             PG8_WAIT_V(6); PG8_BAR; PG8_MMA(1, 1, At, B1); PG8_BAR;
;             PG8_LDB(B0, 1, 0); PG8_SCHED; PG8_LDA(At, 1, 0); PG8_STAGE(PG8_SA(0, 1), a2 + hstepA, voffA);
;             PG8_WAIT_L(8); PG8_BAR; PG8_WAIT_L(0); PG8_MMA(0, 0, At, B0); PG8_BAR; PG8_SCHED;
;             PG8_LDB(B1, 1, 1); PG8_STAGE(PG8_SB(1, 0), b3, voffB);
;             PG8_BAR; PG8_WAIT_L(0); PG8_MMA(0, 1, At, B1); PG8_BAR;
;             PG8_LDA(At, 1, 1); PG8_STAGE(PG8_SA(1, 0), a3, voffA);
	v_mfma_f32_16x16x32_bf16 v[64:67], v[132:135], v[148:151], 0
	v_mfma_f32_16x16x32_bf16 v[60:63], v[140:143], v[148:151], 0
	v_mfma_f32_16x16x32_bf16 v[52:55], v[132:135], v[156:159], 0
	v_mfma_f32_16x16x32_bf16 v[44:47], v[140:143], v[156:159], 0
	v_mfma_f32_16x16x32_bf16 v[36:39], v[132:135], v[164:167], 0
	v_mfma_f32_16x16x32_bf16 v[28:31], v[140:143], v[164:167], 0
	v_mfma_f32_16x16x32_bf16 v[20:23], v[132:135], v[172:175], 0
	v_mfma_f32_16x16x32_bf16 v[12:15], v[140:143], v[172:175], 0
	v_mfma_f32_16x16x32_bf16 v[64:67], v[136:139], v[152:155], v[64:67]
	v_mfma_f32_16x16x32_bf16 v[60:63], v[144:147], v[152:155], v[60:63]
	v_mfma_f32_16x16x32_bf16 v[52:55], v[136:139], v[160:163], v[52:55]
	v_mfma_f32_16x16x32_bf16 v[44:47], v[144:147], v[160:163], v[44:47]
	v_mfma_f32_16x16x32_bf16 v[36:39], v[136:139], v[168:171], v[36:39]
	v_mfma_f32_16x16x32_bf16 v[28:31], v[144:147], v[168:171], v[28:31]
	v_mfma_f32_16x16x32_bf16 v[20:23], v[136:139], v[176:179], v[20:23]
	v_mfma_f32_16x16x32_bf16 v[12:15], v[144:147], v[176:179], v[12:15]
	v_mfma_f32_16x16x32_bf16 v[56:59], v[180:183], v[148:151], 0
	v_mfma_f32_16x16x32_bf16 v[48:51], v[188:191], v[148:151], 0
	v_mfma_f32_16x16x32_bf16 v[40:43], v[180:183], v[156:159], 0
	v_mfma_f32_16x16x32_bf16 v[32:35], v[188:191], v[156:159], 0
	v_mfma_f32_16x16x32_bf16 v[24:27], v[180:183], v[164:167], 0
	v_mfma_f32_16x16x32_bf16 v[16:19], v[188:191], v[164:167], 0
	v_mfma_f32_16x16x32_bf16 v[8:11], v[180:183], v[172:175], 0
	v_mfma_f32_16x16x32_bf16 v[4:7], v[188:191], v[172:175], 0
	v_mfma_f32_16x16x32_bf16 v[56:59], v[184:187], v[152:155], v[56:59]
	v_mfma_f32_16x16x32_bf16 v[48:51], v[202:205], v[152:155], v[48:51]
	v_mfma_f32_16x16x32_bf16 v[40:43], v[184:187], v[160:163], v[40:43]
	v_mfma_f32_16x16x32_bf16 v[32:35], v[202:205], v[160:163], v[32:35]
	v_mfma_f32_16x16x32_bf16 v[24:27], v[184:187], v[168:171], v[24:27]
	v_mfma_f32_16x16x32_bf16 v[16:19], v[202:205], v[168:171], v[16:19]
	v_mfma_f32_16x16x32_bf16 v[8:11], v[184:187], v[176:179], v[8:11]
	v_mfma_f32_16x16x32_bf16 v[4:7], v[202:205], v[176:179], v[4:7]
	s_barrier
	s_setprio 0
	s_add_i32 s52, 0, 0x18000
	v_add_u32_e32 v144, s52, v1
	ds_read_b128 v[132:135], v144
	ds_read_b128 v[136:139], v144 offset:1024
	ds_read_b128 v[140:143], v144 offset:2048
	ds_read_b128 v[144:147], v144 offset:3072
	s_add_u32 s24, s24, 0x80000
	s_addc_u32 s25, s25, 0
	ds_read_b128 v[148:151], v224 offset:32768
	ds_read_b128 v[152:155], v224 offset:33792
	ds_read_b128 v[156:159], v224 offset:34816
	ds_read_b128 v[160:163], v224 offset:35840
	ds_read_b128 v[164:167], v224 offset:36864
	ds_read_b128 v[168:171], v224 offset:37888
	ds_read_b128 v[172:175], v224 offset:38912
	ds_read_b128 v[176:179], v224 offset:39936
	s_mov_b32 m0, s36
	s_nop 0
	global_load_lds_dwordx4 v196, s[24:25]
	s_mov_b32 m0, s37
	s_nop 0
	global_load_lds_dwordx4 v194, s[24:25]
	s_add_i32 s24, 0, 0x1c000
	v_add_u32_e32 v202, s24, v1
	ds_read_b128 v[180:183], v202
	ds_read_b128 v[184:187], v202 offset:1024
	ds_read_b128 v[188:191], v202 offset:2048
	ds_read_b128 v[202:205], v202 offset:3072
	s_waitcnt lgkmcnt(0)
	s_setprio 1
	s_waitcnt vmcnt(8)
	s_barrier
	v_mfma_f32_16x16x32_bf16 v[128:131], v[132:135], v[148:151], v[128:131]
	v_mfma_f32_16x16x32_bf16 v[124:127], v[140:143], v[148:151], v[124:127]
	v_mfma_f32_16x16x32_bf16 v[112:115], v[132:135], v[156:159], v[112:115]
	v_mfma_f32_16x16x32_bf16 v[108:111], v[140:143], v[156:159], v[108:111]
	v_mfma_f32_16x16x32_bf16 v[100:103], v[132:135], v[164:167], v[100:103]
	v_mfma_f32_16x16x32_bf16 v[92:95], v[140:143], v[164:167], v[92:95]
	v_mfma_f32_16x16x32_bf16 v[84:87], v[132:135], v[172:175], v[84:87]
	v_mfma_f32_16x16x32_bf16 v[76:79], v[140:143], v[172:175], v[76:79]
	v_mfma_f32_16x16x32_bf16 v[128:131], v[136:139], v[152:155], v[128:131]
	v_mfma_f32_16x16x32_bf16 v[124:127], v[144:147], v[152:155], v[124:127]
	v_mfma_f32_16x16x32_bf16 v[112:115], v[136:139], v[160:163], v[112:115]
	v_mfma_f32_16x16x32_bf16 v[108:111], v[144:147], v[160:163], v[108:111]
	v_mfma_f32_16x16x32_bf16 v[100:103], v[136:139], v[168:171], v[100:103]
	v_mfma_f32_16x16x32_bf16 v[92:95], v[144:147], v[168:171], v[92:95]
	v_mfma_f32_16x16x32_bf16 v[84:87], v[136:139], v[176:179], v[84:87]
	v_mfma_f32_16x16x32_bf16 v[76:79], v[144:147], v[176:179], v[76:79]
	v_mfma_f32_16x16x32_bf16 v[120:123], v[180:183], v[148:151], v[120:123]
	v_mfma_f32_16x16x32_bf16 v[116:119], v[188:191], v[148:151], v[116:119]
	v_mfma_f32_16x16x32_bf16 v[104:107], v[180:183], v[156:159], v[104:107]
	v_mfma_f32_16x16x32_bf16 v[96:99], v[188:191], v[156:159], v[96:99]
	v_mfma_f32_16x16x32_bf16 v[88:91], v[180:183], v[164:167], v[88:91]
	v_mfma_f32_16x16x32_bf16 v[80:83], v[188:191], v[164:167], v[80:83]
	v_mfma_f32_16x16x32_bf16 v[72:75], v[180:183], v[172:175], v[72:75]
	v_mfma_f32_16x16x32_bf16 v[68:71], v[188:191], v[172:175], v[68:71]
	v_mfma_f32_16x16x32_bf16 v[120:123], v[184:187], v[152:155], v[120:123]
	v_mfma_f32_16x16x32_bf16 v[116:119], v[202:205], v[152:155], v[116:119]
	v_mfma_f32_16x16x32_bf16 v[104:107], v[184:187], v[160:163], v[104:107]
	v_mfma_f32_16x16x32_bf16 v[96:99], v[202:205], v[160:163], v[96:99]
	v_mfma_f32_16x16x32_bf16 v[88:91], v[184:187], v[168:171], v[88:91]
	v_mfma_f32_16x16x32_bf16 v[80:83], v[202:205], v[168:171], v[80:83]
	v_mfma_f32_16x16x32_bf16 v[72:75], v[184:187], v[176:179], v[72:75]
	v_mfma_f32_16x16x32_bf16 v[68:71], v[202:205], v[176:179], v[68:71]
	s_barrier
; #define PG8_STAGE(bufoff, gbase, voff) do { _Pragma("unroll") for (int _i = 0; _i < 2; ++_i) \
;         __builtin_amdgcn_global_load_lds((const unsigned*)((const char*)(gbase) + (voff)[_i]), (LAS unsigned*)(lds + (bufoff) + ldsw + _i * 8192), 16, 0, 0); } while (0)
; #define PG8_LDA(dst, b, h) do { _Pragma("unroll") for (int m = 0; m < 4; ++m) _Pragma("unroll") for (int k = 0; k < 2; ++k) dst[m][k] = *(const LAS bf16x8*)(lds + PG8_SA(b, h) + aoff + m * 2048 + k * 1024); } while (0)
; #define PG8_MMA(ai, bj, At, Bt) do { __builtin_amdgcn_s_setprio(1); _Pragma("unroll") for (int m = 0; m < 4; ++m) _Pragma("unroll") for (int n = 0; n < 2; ++n) _Pragma("unroll") for (int k = 0; k < 2; ++k) \
;         acc[ai][bj][m][n] = __builtin_amdgcn_mfma_f32_16x16x32_bf16(Bt[n][k], At[m][k], acc[ai][bj][m][n], 0, 0, 0); __builtin_amdgcn_s_setprio(0); } while (0)
; #define PG8_WAIT_V(n) asm volatile("s_waitcnt vmcnt(" #n ")" ::: "memory")
; #define PG8_WAIT_L(n) asm volatile("s_waitcnt lgkmcnt(" #n ")" ::: "memory")
; #define PG8_BAR __builtin_amdgcn_s_barrier()
; #define PG8_SCHED __builtin_amdgcn_sched_barrier(0)
; template <class Epi, class Sched>
; __device__ __forceinline__ void gemm_phase(LAS unsigned char* lds, const Gemm g, const Sched& S, const Epi& E) {
;     ...
;             PG8_LDA(At, 1, 1); PG8_STAGE(PG8_SA(1, 0), a3, voffA);
;             PG8_BAR; PG8_WAIT_L(0); PG8_MMA(1, 0, At, B0); PG8_BAR; PG8_SCHED;
;             PG8_STAGE(PG8_SB(1, 1), b3 + hstepB, voffB);
;             PG8_WAIT_V(6); PG8_BAR; PG8_MMA(1, 1, At, B1); PG8_BAR;
	s_setprio 0
	ds_read_b128 v[148:151], v224 offset:49152
	ds_read_b128 v[152:155], v224 offset:50176
	ds_read_b128 v[156:159], v224 offset:51200
	ds_read_b128 v[160:163], v224 offset:52224
	ds_read_b128 v[164:167], v224 offset:53248
	ds_read_b128 v[168:171], v224 offset:54272
	ds_read_b128 v[172:175], v224 offset:55296
	ds_read_b128 v[176:179], v224 offset:56320
	s_add_i32 s25, s52, s30
	v_lshl_add_u64 v[206:207], v[206:207], 0, s[8:9]
	s_mov_b32 m0, s25
	s_nop 0
	global_load_lds_dwordx4 v[206:207], off
	v_lshl_add_u64 v[206:207], v[208:209], 0, s[8:9]
	s_add_i32 m0, s25, 0x2000
	s_nop 0
	global_load_lds_dwordx4 v[206:207], off
	s_mov_b32 m0, s42
	v_lshl_add_u64 v[206:207], v[210:211], 0, s[8:9]
	global_load_lds_dwordx4 v[206:207], off
	v_lshl_add_u64 v[206:207], v[212:213], 0, s[8:9]
	s_mov_b32 m0, s43
	s_nop 0
	global_load_lds_dwordx4 v[206:207], off
	s_add_u32 s20, s20, 0x80080
	s_addc_u32 s21, s21, 0
	s_add_i32 s24, s24, s30
	s_mov_b32 m0, s24
	s_nop 0
	global_load_lds_dwordx4 v2, s[20:21]
	s_add_i32 m0, s24, 0x2000
	s_nop 0
	global_load_lds_dwordx4 v192, s[20:21]
	s_add_i32 s51, s51, 2
	s_add_u32 s6, s6, 0x100
	s_addc_u32 s7, s7, 0
	s_add_u32 s49, s49, 0x100
	s_addc_u32 s50, s50, 0
	s_cmp_gt_u32 s51, 29
	s_waitcnt lgkmcnt(0)
	s_waitcnt vmcnt(6)
	s_setprio 1
	s_barrier
	v_mfma_f32_16x16x32_bf16 v[64:67], v[132:135], v[148:151], v[64:67]
	v_mfma_f32_16x16x32_bf16 v[60:63], v[140:143], v[148:151], v[60:63]
	v_mfma_f32_16x16x32_bf16 v[52:55], v[132:135], v[156:159], v[52:55]
	v_mfma_f32_16x16x32_bf16 v[44:47], v[140:143], v[156:159], v[44:47]
	v_mfma_f32_16x16x32_bf16 v[36:39], v[132:135], v[164:167], v[36:39]
	v_mfma_f32_16x16x32_bf16 v[28:31], v[140:143], v[164:167], v[28:31]
	v_mfma_f32_16x16x32_bf16 v[20:23], v[132:135], v[172:175], v[20:23]
	v_mfma_f32_16x16x32_bf16 v[12:15], v[140:143], v[172:175], v[12:15]
	v_mfma_f32_16x16x32_bf16 v[64:67], v[136:139], v[152:155], v[64:67]
	v_mfma_f32_16x16x32_bf16 v[60:63], v[144:147], v[152:155], v[60:63]
	v_mfma_f32_16x16x32_bf16 v[52:55], v[136:139], v[160:163], v[52:55]
	v_mfma_f32_16x16x32_bf16 v[44:47], v[144:147], v[160:163], v[44:47]
	v_mfma_f32_16x16x32_bf16 v[36:39], v[136:139], v[168:171], v[36:39]
	v_mfma_f32_16x16x32_bf16 v[28:31], v[144:147], v[168:171], v[28:31]
	v_mfma_f32_16x16x32_bf16 v[20:23], v[136:139], v[176:179], v[20:23]
	v_mfma_f32_16x16x32_bf16 v[12:15], v[144:147], v[176:179], v[12:15]
	v_mfma_f32_16x16x32_bf16 v[56:59], v[180:183], v[148:151], v[56:59]
	v_mfma_f32_16x16x32_bf16 v[48:51], v[188:191], v[148:151], v[48:51]
	v_mfma_f32_16x16x32_bf16 v[40:43], v[180:183], v[156:159], v[40:43]
	v_mfma_f32_16x16x32_bf16 v[32:35], v[188:191], v[156:159], v[32:35]
	v_mfma_f32_16x16x32_bf16 v[24:27], v[180:183], v[164:167], v[24:27]
	v_mfma_f32_16x16x32_bf16 v[16:19], v[188:191], v[164:167], v[16:19]
	v_mfma_f32_16x16x32_bf16 v[8:11], v[180:183], v[172:175], v[8:11]
	v_mfma_f32_16x16x32_bf16 v[4:7], v[188:191], v[172:175], v[4:7]
	v_mfma_f32_16x16x32_bf16 v[56:59], v[184:187], v[152:155], v[56:59]
	v_mfma_f32_16x16x32_bf16 v[48:51], v[202:205], v[152:155], v[48:51]
	v_mfma_f32_16x16x32_bf16 v[40:43], v[184:187], v[160:163], v[40:43]
	v_mfma_f32_16x16x32_bf16 v[32:35], v[202:205], v[160:163], v[32:35]
	v_mfma_f32_16x16x32_bf16 v[24:27], v[184:187], v[168:171], v[24:27]
	v_mfma_f32_16x16x32_bf16 v[16:19], v[202:205], v[168:171], v[16:19]
	v_mfma_f32_16x16x32_bf16 v[8:11], v[184:187], v[176:179], v[8:11]
	v_mfma_f32_16x16x32_bf16 v[4:7], v[202:205], v[176:179], v[4:7]
	s_barrier
	s_setprio 0

; #define PG8_WAIT_V(n) asm volatile("s_waitcnt vmcnt(" #n ")" ::: "memory")
; template <class Epi, class Sched>
; __device__ __forceinline__ void gemm_phase(LAS unsigned char* lds, const Gemm g, const Sched& S, const Epi& E) {
;     const int tid = opaque_tid(), wid = __builtin_amdgcn_readfirstlane(tid >> 6), lane = tid & 63, wr = wid >> 2, wc = wid & 3, fr = lane & 15, fq = lane >> 4;
;     const int K = g.K, nt = K / BK, lda = g.lda;
;     unsigned voffA[2], voffB[2];
; #pragma unroll
;     for (int i = 0; i < 2; ++i) { int R, C; stage_rc(tid * 16 + i * 8192, R, C); const int Rb = Epi::PERM ? ((R & ~31) + perm32(R & 31)) : R;
;         voffA[i] = (unsigned)(R * lda + C) * 2u; voffB[i] = (unsigned)(Rb * K + C) * 2u; }
;     const size_t kstep = (size_t)(BK * 2);
;     const size_t hstepA = (size_t)HALF * lda * 2, hstepB = (size_t)HALF * K * 2;
;     const size_t tstepA = 2 * hstepA, tstepB = 2 * hstepB;
;     const unsigned ldsw = (unsigned)wid * 1024u;
;     const int aoff = lds_byte(wr * 64 + fr, fq * 8), boff = lds_byte(wc * 32 + fr, fq * 8);
;     ...
;     Unit cur, nxt; int ui = 0;
;     if (!S.next(0, cur)) return;
;     f32x4 acc[2][2][4][2];
; #pragma unroll
;     for (int a = 0; a < 2; ++a)
; #pragma unroll
;         for (int b = 0; b < 2; ++b)
; #pragma unroll
;             for (int m = 0; m < 4; ++m)
; #pragma unroll
;                 for (int n = 0; n < 2; ++n) acc[a][b][m][n] = (f32x4){0.f, 0.f, 0.f, 0.f};
;     bf16x8 At[4][2], B0[2][2], B1[2][2];
;     const char* cA = (const char*)g.A + (size_t)cur.pm * tstepA; const char* cB = (const char*)g.Bt + (size_t)cur.pn * tstepB;
;     S.a_ready(cur);
;     PG8_STAGE(PG8_SB(0, 0), cB, voffB); PG8_STAGE(PG8_SA(0, 0), cA, voffA); PG8_STAGE(PG8_SB(0, 1), cB + hstepB, voffB); PG8_STAGE(PG8_SA(0, 1), cA + hstepA, voffA);
;     if (wr == 1) PG8_BAR;
;     PG8_WAIT_V(4); PG8_BAR;
;     PG8_STAGE(PG8_SB(1, 0), cB + kstep, voffB); PG8_STAGE(PG8_SA(1, 0), cA + kstep, voffA); PG8_STAGE(PG8_SB(1, 1), cB + hstepB + kstep, voffB);
;     PG8_WAIT_V(6); PG8_BAR;
; __global__ void __launch_bounds__(NTHR, 2) mega(Args args) {
;     ...
;             pg8::Gemm g{RES, (const bf16_t*)(ws + WS_W_UP + layer * SZ_W_UP), M, FF2, D, D};
;             pg8::StaticOrder S; S.init(M, FF2, F.G, F.bid);
;             pg8::EpiFfnGate E{(bf16_t*)(ws + WS_ACT), F.in[I_F_CONVW] + (size_t)layer * 3 * FF, F.in[I_F_CONVB] + (size_t)layer * FF,
.LBB0_1519:
	v_readlane_b32 s29, v255, 27
	s_mul_i32 s28, s29, 0x10800
	s_mul_hi_u32 s15, s29, 0x10800
	s_waitcnt lgkmcnt(0)
	s_add_u32 s36, s40, s28
	s_addc_u32 s37, s41, s15
	s_mul_i32 s28, s29, 0x5800
	v_readlane_b32 s58, v254, 23
	s_mul_hi_u32 s15, s29, 0x5800
	s_add_u32 s42, s42, s28
	v_mov_b32_e32 v181, v3
	v_readlane_b32 s59, v254, 24
	s_addc_u32 s43, s43, s15
	s_and_b32 s40, s14, 3
	s_add_i32 m0, s20, 0x18000
	v_lshl_add_u64 v[4:5], v[4:5], 0, s[8:9]
	v_lshl_add_u64 v[14:15], s[58:59], 0, v[180:181]
	v_mov_b32_e32 v177, v3
	s_lshl_b32 s28, s5, 6
	s_lshl_b32 s35, s5, 13
	s_lshl_b32 s29, s40, 5
	s_lshl_b32 s38, s40, 12
	s_waitcnt vmcnt(2)
	s_barrier
	global_load_lds_dwordx4 v[4:5], off
	v_lshl_add_u64 v[4:5], v[6:7], 0, s[8:9]
	s_add_i32 m0, s20, 0x1a000
	s_add_i32 s30, s20, 0x8000
	s_add_i32 s31, s20, 0xa000
	v_lshl_add_u64 v[16:17], s[58:59], 0, v[176:177]
	global_load_lds_dwordx4 v[4:5], off
	v_lshl_add_u64 v[4:5], v[14:15], 0, s[8:9]
	s_mov_b32 m0, s30
	s_add_u32 s14, s6, 0x80080
	global_load_lds_dwordx4 v[4:5], off
	v_lshl_add_u64 v[4:5], v[16:17], 0, s[8:9]
	s_mov_b32 m0, s31
	s_addc_u32 s15, s7, 0
	global_load_lds_dwordx4 v[4:5], off
	s_add_i32 m0, s20, 0x1c000
	v_lshl_add_u64 v[4:5], s[14:15], 0, v[178:179]
	global_load_lds_dwordx4 v[4:5], off
	v_lshl_add_u64 v[4:5], s[14:15], 0, v[174:175]
	s_add_i32 m0, s20, 0x1e000
	s_movk_i32 s14, 0x3c0
	global_load_lds_dwordx4 v[4:5], off
	v_and_b32_e32 v4, 48, v1
	v_lshlrev_b32_e32 v5, 6, v1
	v_lshlrev_b32_e32 v1, 2, v1
	v_and_or_b32 v4, v5, s14, v4
	v_and_b32_e32 v1, 32, v1
	s_and_b32 s14, s4, 0xffffff00
	v_bitop3_b32 v5, v4, s35, v1 bitop3:0xde
	s_add_i32 s35, s14, 0
	s_lshl_b32 s14, s5, 5
	s_lshl_b32 s15, s40, 3
	v_bitop3_b32 v1, v4, s38, v1 bitop3:0xde
	s_or_b32 s38, s15, s14
	s_add_i32 s35, s35, 0x21000
	s_add_i32 s39, s38, 64
	s_cmpk_gt_u32 s4, 0xff
	s_cselect_b64 s[44:45], -1, 0
	s_lshl_b32 s40, s40, 8
	s_cmp_lg_u32 s5, 1
	s_cselect_b64 s[14:15], -1, 0
	v_cndmask_b32_e64 v4, 0, 1, s[14:15]
	s_and_b64 s[14:15], s[14:15], exec
	s_cselect_b32 s14, 0, 2
	v_readfirstlane_b32 s15, v4
	s_cselect_b32 s5, 0x400, 0
	s_or_b32 s14, s14, s15
	s_lshl_b32 s14, s14, 10
	v_lshlrev_b32_e32 v4, 15, v11
	s_cmpk_lt_u32 s4, 0x100
	v_and_b32_e32 v4, 0xffff0000, v4
	s_cselect_b64 s[46:47], -1, 0
	s_add_u32 s48, s36, 0x5800
	v_lshl_add_u32 v4, v10, 12, v4
	v_and_b32_e32 v6, 1, v11
	s_addc_u32 s49, s37, 0
	v_lshl_or_b32 v4, v6, 6, v4
	s_add_u32 s50, s36, 0xb000
	v_lshl_add_u32 v182, v12, 1, v4
	v_lshlrev_b32_e32 v4, 15, v2
	s_addc_u32 s51, s37, 0
	s_add_i32 s62, 0, 0x20000
	v_and_b32_e32 v4, 0xffff0000, v4
	s_waitcnt vmcnt(0)
	s_add_i32 s63, s62, s5
	v_lshl_add_u32 v4, v8, 12, v4
	v_and_b32_e32 v2, 1, v2
	v_readlane_b32 s4, v254, 21
	s_add_i32 s64, s62, s14
	v_lshl_or_b32 v2, v2, 6, v4
	v_readlane_b32 s5, v254, 22
	s_mov_b32 s66, 0
	s_add_i32 s63, s63, s40
	s_add_i32 s64, s64, s40
	v_mov_b32_e32 v183, v3
	v_lshl_add_u32 v184, v9, 1, v2
	v_mov_b32_e32 v185, v3
	v_add_u32_e32 v207, 0, v5
	v_readlane_b32 s53, v254, 18
	s_mov_b32 s52, s4
	s_mov_b64 s[4:5], s[58:59]
	s_barrier
	s_branch .LBB0_1521

; #define PG8_STAGE(bufoff, gbase, voff) do { _Pragma("unroll") for (int _i = 0; _i < 2; ++_i) \
;         __builtin_amdgcn_global_load_lds((const unsigned*)((const char*)(gbase) + (voff)[_i]), (LAS unsigned*)(lds + (bufoff) + ldsw + _i * 8192), 16, 0, 0); } while (0)
; #define PG8_LDA(dst, b, h) do { _Pragma("unroll") for (int m = 0; m < 4; ++m) _Pragma("unroll") for (int k = 0; k < 2; ++k) dst[m][k] = *(const LAS bf16x8*)(lds + PG8_SA(b, h) + aoff + m * 2048 + k * 1024); } while (0)
; #define PG8_LDB(dst, b, h) do { _Pragma("unroll") for (int n = 0; n < 2; ++n) _Pragma("unroll") for (int k = 0; k < 2; ++k) dst[n][k] = *(const LAS bf16x8*)(lds + PG8_SB(b, h) + boff + n * 2048 + k * 1024); } while (0)
; #define PG8_WAIT_V(n) asm volatile("s_waitcnt vmcnt(" #n ")" ::: "memory")
; #define PG8_WAIT_L(n) asm volatile("s_waitcnt lgkmcnt(" #n ")" ::: "memory")
; #define PG8_BAR __builtin_amdgcn_s_barrier()
; #define PG8_SCHED __builtin_amdgcn_sched_barrier(0)
; template <class Epi, class Sched>
; __device__ __forceinline__ void gemm_phase(LAS unsigned char* lds, const Gemm g, const Sched& S, const Epi& E) {
;     ...
;         const bool has_next = S.next(ui + 1, nxt);
;         const char* nA = has_next ? (const char*)g.A + (size_t)nxt.pm * tstepA : cA; const char* nB = has_next ? (const char*)g.Bt + (size_t)nxt.pn * tstepB : cB;
;         for (int t = 0; t < nt; t += 2) {
;             const bool last = (t == nt - 2);
;             const char* a1 = cA + (size_t)(t + 1) * kstep;
;             const char* a2 = last ? nA : cA + (size_t)(t + 2) * kstep; const char* b2 = last ? nB : cB + (size_t)(t + 2) * kstep;
;             const char* a3 = a2 + kstep; const char* b3 = b2 + kstep;
;             if (last && has_next) S.a_ready(nxt);
;             PG8_LDB(B0, 0, 0); PG8_SCHED; PG8_LDA(At, 0, 0); PG8_STAGE(PG8_SA(1, 1), a1 + hstepA, voffA);
;             PG8_WAIT_L(8); PG8_BAR; PG8_WAIT_L(0); PG8_MMA(0, 0, At, B0); PG8_BAR; PG8_SCHED;
;             PG8_LDB(B1, 0, 1); PG8_STAGE(PG8_SB(0, 0), b2, voffB);
;             PG8_BAR; PG8_WAIT_L(0); PG8_MMA(0, 1, At, B1); PG8_BAR;
;             PG8_LDA(At, 0, 1); PG8_STAGE(PG8_SA(0, 0), a2, voffA);
;             PG8_BAR; PG8_WAIT_L(0); PG8_MMA(1, 0, At, B0); PG8_BAR; PG8_SCHED;
;             PG8_STAGE(PG8_SB(0, 1), b2 + hstepB, voffB);
;             PG8_WAIT_V(6); PG8_BAR; PG8_MMA(1, 1, At, B1); PG8_BAR;
.LBB0_1525:
	v_mov_b64_e32 v[4:5], 0x1600
	s_ashr_i32 s57, s56, 31
	v_cmp_lt_i64_e32 vcc, s[14:15], v[4:5]
	s_lshl_b64 s[14:15], s[56:57], 20
	s_add_u32 s58, s88, s14
	s_addc_u32 s59, s89, s15
	s_and_b64 s[14:15], vcc, exec
	s_cselect_b32 s57, s59, s5
	s_cselect_b32 s67, s58, s4
	s_ashr_i32 s55, s54, 31
	s_lshl_b64 s[14:15], s[54:55], 20
	s_add_u32 s60, s2, s14
	s_addc_u32 s61, s18, s15
	s_and_b64 s[14:15], vcc, exec
	s_cselect_b32 s55, s61, s7
	s_cselect_b32 s68, s60, s6
	s_add_u32 s4, s4, 0x80080
	s_addc_u32 s5, s5, 0
	s_add_u32 s69, s6, 0x100
	s_addc_u32 s70, s7, 0
	s_mov_b32 s71, -2
	s_setprio 0
	s_add_u32 s6, s4, 0xfff80080
	s_addc_u32 s7, s5, -1
	s_add_i32 s72, 0, 0x10000
	v_add_u32_e32 v2, s72, v1
	ds_read_b128 v[132:135], v2
	ds_read_b128 v[136:139], v2 offset:1024
	ds_read_b128 v[140:143], v2 offset:2048
	ds_read_b128 v[144:147], v2 offset:3072
	s_cmp_eq_u32 s71, 28
	s_cselect_b32 s15, s57, s7
	s_cselect_b32 s14, s67, s6
	s_cselect_b32 s7, s55, s70
	s_cselect_b32 s6, s68, s69
	ds_read_b128 v[148:151], v207
	ds_read_b128 v[152:155], v207 offset:1024
	ds_read_b128 v[156:159], v207 offset:2048
	ds_read_b128 v[160:163], v207 offset:3072
	ds_read_b128 v[164:167], v207 offset:4096
	ds_read_b128 v[168:171], v207 offset:5120
	ds_read_b128 v[186:189], v207 offset:6144
	ds_read_b128 v[190:193], v207 offset:7168
	s_add_i32 s74, 0, 0x14000
	v_add_u32_e32 v2, s74, v1
	ds_read_b128 v[194:197], v2
	ds_read_b128 v[198:201], v2 offset:1024
	ds_read_b128 v[202:205], v2 offset:2048
	ds_read_b128 v[208:211], v2 offset:3072
	s_add_i32 m0, s20, 0xc000
	s_nop 0
	global_load_lds_dwordx4 v182, s[4:5]
	s_add_i32 m0, s20, 0xe000
	s_nop 0
	global_load_lds_dwordx4 v184, s[4:5]
	s_waitcnt lgkmcnt(0)
	s_setprio 1
	s_barrier
	v_mfma_f32_16x16x32_bf16 v[68:71], v[132:135], v[148:151], 0
	v_mfma_f32_16x16x32_bf16 v[72:75], v[140:143], v[148:151], 0
	v_mfma_f32_16x16x32_bf16 v[120:123], v[132:135], v[156:159], 0
	v_mfma_f32_16x16x32_bf16 v[116:119], v[140:143], v[156:159], 0
	v_mfma_f32_16x16x32_bf16 v[112:115], v[132:135], v[164:167], 0
	v_mfma_f32_16x16x32_bf16 v[108:111], v[140:143], v[164:167], 0
	v_mfma_f32_16x16x32_bf16 v[104:107], v[132:135], v[186:189], 0
	v_mfma_f32_16x16x32_bf16 v[100:103], v[140:143], v[186:189], 0
	v_mfma_f32_16x16x32_bf16 v[68:71], v[136:139], v[152:155], v[68:71]
	v_mfma_f32_16x16x32_bf16 v[72:75], v[144:147], v[152:155], v[72:75]
	v_mfma_f32_16x16x32_bf16 v[120:123], v[136:139], v[160:163], v[120:123]
	v_mfma_f32_16x16x32_bf16 v[116:119], v[144:147], v[160:163], v[116:119]
	v_mfma_f32_16x16x32_bf16 v[112:115], v[136:139], v[168:171], v[112:115]
	v_mfma_f32_16x16x32_bf16 v[108:111], v[144:147], v[168:171], v[108:111]
	v_mfma_f32_16x16x32_bf16 v[104:107], v[136:139], v[190:193], v[104:107]
	v_mfma_f32_16x16x32_bf16 v[100:103], v[144:147], v[190:193], v[100:103]
	v_mfma_f32_16x16x32_bf16 v[76:79], v[194:197], v[148:151], 0
	v_mfma_f32_16x16x32_bf16 v[80:83], v[202:205], v[148:151], 0
	v_mfma_f32_16x16x32_bf16 v[96:99], v[194:197], v[156:159], 0
	v_mfma_f32_16x16x32_bf16 v[92:95], v[202:205], v[156:159], 0
	v_mfma_f32_16x16x32_bf16 v[88:91], v[194:197], v[164:167], 0
	v_mfma_f32_16x16x32_bf16 v[84:87], v[202:205], v[164:167], 0
	v_mfma_f32_16x16x32_bf16 v[128:131], v[194:197], v[186:189], 0
	v_mfma_f32_16x16x32_bf16 v[124:127], v[202:205], v[186:189], 0
	v_mfma_f32_16x16x32_bf16 v[76:79], v[198:201], v[152:155], v[76:79]
	v_mfma_f32_16x16x32_bf16 v[80:83], v[208:211], v[152:155], v[80:83]
	v_mfma_f32_16x16x32_bf16 v[96:99], v[198:201], v[160:163], v[96:99]
	v_mfma_f32_16x16x32_bf16 v[92:95], v[208:211], v[160:163], v[92:95]
	v_mfma_f32_16x16x32_bf16 v[88:91], v[198:201], v[168:171], v[88:91]
	v_mfma_f32_16x16x32_bf16 v[84:87], v[208:211], v[168:171], v[84:87]
	v_mfma_f32_16x16x32_bf16 v[128:131], v[198:201], v[190:193], v[128:131]
	v_mfma_f32_16x16x32_bf16 v[124:127], v[208:211], v[190:193], v[124:127]
	s_barrier
	s_setprio 0
	ds_read_b128 v[148:151], v207 offset:16384
	ds_read_b128 v[152:155], v207 offset:17408
	ds_read_b128 v[156:159], v207 offset:18432
	ds_read_b128 v[160:163], v207 offset:19456
	ds_read_b128 v[164:167], v207 offset:20480
	ds_read_b128 v[168:171], v207 offset:21504
	ds_read_b128 v[186:189], v207 offset:22528
	ds_read_b128 v[190:193], v207 offset:23552
	s_add_i32 s72, s72, s19
	v_lshl_add_u64 v[172:173], s[6:7], 0, v[178:179]
	s_mov_b32 m0, s72
	s_nop 0
	global_load_lds_dwordx4 v[172:173], off
	v_lshl_add_u64 v[212:213], s[6:7], 0, v[174:175]
	s_add_i32 m0, s72, 0x2000
	s_nop 0
	global_load_lds_dwordx4 v[212:213], off
	s_mov_b32 m0, s20
	v_lshl_add_u64 v[216:217], s[14:15], 0, v[180:181]
	global_load_lds_dwordx4 v[216:217], off
	v_lshl_add_u64 v[218:219], s[14:15], 0, v[176:177]
	s_mov_b32 m0, s21
	s_nop 0
	global_load_lds_dwordx4 v[218:219], off
	s_add_u32 s72, s6, 0x80000
	s_addc_u32 s73, s7, 0
	s_add_i32 s74, s74, s19
	s_mov_b32 m0, s74
	s_nop 0
	global_load_lds_dwordx4 v178, s[72:73]
	s_add_i32 m0, s74, 0x2000
	s_nop 0
	global_load_lds_dwordx4 v174, s[72:73]
	s_waitcnt lgkmcnt(0)
	s_setprio 1
	s_barrier
; #define PG8_STAGE(bufoff, gbase, voff) do { _Pragma("unroll") for (int _i = 0; _i < 2; ++_i) \
;         __builtin_amdgcn_global_load_lds((const unsigned*)((const char*)(gbase) + (voff)[_i]), (LAS unsigned*)(lds + (bufoff) + ldsw + _i * 8192), 16, 0, 0); } while (0)
; #define PG8_LDA(dst, b, h) do { _Pragma("unroll") for (int m = 0; m < 4; ++m) _Pragma("unroll") for (int k = 0; k < 2; ++k) dst[m][k] = *(const LAS bf16x8*)(lds + PG8_SA(b, h) + aoff + m * 2048 + k * 1024); } while (0)
; #define PG8_LDB(dst, b, h) do { _Pragma("unroll") for (int n = 0; n < 2; ++n) _Pragma("unroll") for (int k = 0; k < 2; ++k) dst[n][k] = *(const LAS bf16x8*)(lds + PG8_SB(b, h) + boff + n * 2048 + k * 1024); } while (0)
; #define PG8_MMA(ai, bj, At, Bt) do { __builtin_amdgcn_s_setprio(1); _Pragma("unroll") for (int m = 0; m < 4; ++m) _Pragma("unroll") for (int n = 0; n < 2; ++n) _Pragma("unroll") for (int k = 0; k < 2; ++k) \
;         acc[ai][bj][m][n] = __builtin_amdgcn_mfma_f32_16x16x32_bf16(Bt[n][k], At[m][k], acc[ai][bj][m][n], 0, 0, 0); __builtin_amdgcn_s_setprio(0); } while (0)
; #define PG8_WAIT_V(n) asm volatile("s_waitcnt vmcnt(" #n ")" ::: "memory")
; #define PG8_WAIT_L(n) asm volatile("s_waitcnt lgkmcnt(" #n ")" ::: "memory")
; #define PG8_BAR __builtin_amdgcn_s_barrier()
; #define PG8_SCHED __builtin_amdgcn_sched_barrier(0)
; template <class Epi, class Sched>
; __device__ __forceinline__ void gemm_phase(LAS unsigned char* lds, const Gemm g, const Sched& S, const Epi& E) {
;     ...
;             PG8_WAIT_V(6); PG8_BAR; PG8_MMA(1, 1, At, B1); PG8_BAR;
;             PG8_LDB(B0, 1, 0); PG8_SCHED; PG8_LDA(At, 1, 0); PG8_STAGE(PG8_SA(0, 1), a2 + hstepA, voffA);
;             PG8_WAIT_L(8); PG8_BAR; PG8_WAIT_L(0); PG8_MMA(0, 0, At, B0); PG8_BAR; PG8_SCHED;
;             PG8_LDB(B1, 1, 1); PG8_STAGE(PG8_SB(1, 0), b3, voffB);
;             PG8_BAR; PG8_WAIT_L(0); PG8_MMA(0, 1, At, B1); PG8_BAR;
;             PG8_LDA(At, 1, 1); PG8_STAGE(PG8_SA(1, 0), a3, voffA);
	v_mfma_f32_16x16x32_bf16 v[56:59], v[132:135], v[148:151], 0
	v_mfma_f32_16x16x32_bf16 v[52:55], v[140:143], v[148:151], 0
	v_mfma_f32_16x16x32_bf16 v[48:51], v[132:135], v[156:159], 0
	v_mfma_f32_16x16x32_bf16 v[44:47], v[140:143], v[156:159], 0
	v_mfma_f32_16x16x32_bf16 v[40:43], v[132:135], v[164:167], 0
	v_mfma_f32_16x16x32_bf16 v[36:39], v[140:143], v[164:167], 0
	v_mfma_f32_16x16x32_bf16 v[32:35], v[132:135], v[186:189], 0
	v_mfma_f32_16x16x32_bf16 v[28:31], v[140:143], v[186:189], 0
	v_mfma_f32_16x16x32_bf16 v[56:59], v[136:139], v[152:155], v[56:59]
	v_mfma_f32_16x16x32_bf16 v[52:55], v[144:147], v[152:155], v[52:55]
	v_mfma_f32_16x16x32_bf16 v[48:51], v[136:139], v[160:163], v[48:51]
	v_mfma_f32_16x16x32_bf16 v[44:47], v[144:147], v[160:163], v[44:47]
	v_mfma_f32_16x16x32_bf16 v[40:43], v[136:139], v[168:171], v[40:43]
	v_mfma_f32_16x16x32_bf16 v[36:39], v[144:147], v[168:171], v[36:39]
	v_mfma_f32_16x16x32_bf16 v[32:35], v[136:139], v[190:193], v[32:35]
	v_mfma_f32_16x16x32_bf16 v[28:31], v[144:147], v[190:193], v[28:31]
	v_mfma_f32_16x16x32_bf16 v[24:27], v[194:197], v[148:151], 0
	v_mfma_f32_16x16x32_bf16 v[20:23], v[202:205], v[148:151], 0
	v_mfma_f32_16x16x32_bf16 v[16:19], v[194:197], v[156:159], 0
	v_mfma_f32_16x16x32_bf16 v[12:15], v[202:205], v[156:159], 0
	v_mfma_f32_16x16x32_bf16 v[8:11], v[194:197], v[164:167], 0
	v_mfma_f32_16x16x32_bf16 v[4:7], v[202:205], v[164:167], 0
	v_mfma_f32_16x16x32_bf16 v[60:63], v[194:197], v[186:189], 0
	v_mfma_f32_16x16x32_bf16 v[64:67], v[202:205], v[186:189], 0
	v_mfma_f32_16x16x32_bf16 v[24:27], v[198:201], v[152:155], v[24:27]
	v_mfma_f32_16x16x32_bf16 v[20:23], v[208:211], v[152:155], v[20:23]
	v_mfma_f32_16x16x32_bf16 v[16:19], v[198:201], v[160:163], v[16:19]
	v_mfma_f32_16x16x32_bf16 v[12:15], v[208:211], v[160:163], v[12:15]
	v_mfma_f32_16x16x32_bf16 v[8:11], v[198:201], v[168:171], v[8:11]
	v_mfma_f32_16x16x32_bf16 v[4:7], v[208:211], v[168:171], v[4:7]
	v_mfma_f32_16x16x32_bf16 v[60:63], v[198:201], v[190:193], v[60:63]
	v_mfma_f32_16x16x32_bf16 v[64:67], v[208:211], v[190:193], v[64:67]
	s_barrier
	s_setprio 0
	s_add_i32 s72, 0, 0x18000
	v_add_u32_e32 v2, s72, v1
	ds_read_b128 v[132:135], v2
	ds_read_b128 v[136:139], v2 offset:1024
	ds_read_b128 v[140:143], v2 offset:2048
	ds_read_b128 v[144:147], v2 offset:3072
	s_add_u32 s14, s14, 0x80000
	s_addc_u32 s15, s15, 0
	ds_read_b128 v[148:151], v207 offset:32768
	ds_read_b128 v[152:155], v207 offset:33792
	ds_read_b128 v[156:159], v207 offset:34816
	ds_read_b128 v[160:163], v207 offset:35840
	ds_read_b128 v[164:167], v207 offset:36864
	ds_read_b128 v[168:171], v207 offset:37888
	ds_read_b128 v[186:189], v207 offset:38912
	ds_read_b128 v[190:193], v207 offset:39936
	s_mov_b32 m0, s24
	s_nop 0
	global_load_lds_dwordx4 v180, s[14:15]
	s_mov_b32 m0, s25
	s_nop 0
	global_load_lds_dwordx4 v176, s[14:15]
	s_add_i32 s14, 0, 0x1c000
	v_add_u32_e32 v2, s14, v1
	ds_read_b128 v[194:197], v2
	ds_read_b128 v[198:201], v2 offset:1024
	ds_read_b128 v[202:205], v2 offset:2048
	ds_read_b128 v[208:211], v2 offset:3072
	s_waitcnt lgkmcnt(0)
	s_setprio 1
	s_waitcnt vmcnt(8)
	s_barrier
	v_mfma_f32_16x16x32_bf16 v[68:71], v[132:135], v[148:151], v[68:71]
	v_mfma_f32_16x16x32_bf16 v[72:75], v[140:143], v[148:151], v[72:75]
	v_mfma_f32_16x16x32_bf16 v[120:123], v[132:135], v[156:159], v[120:123]
	v_mfma_f32_16x16x32_bf16 v[116:119], v[140:143], v[156:159], v[116:119]
	v_mfma_f32_16x16x32_bf16 v[112:115], v[132:135], v[164:167], v[112:115]
	v_mfma_f32_16x16x32_bf16 v[108:111], v[140:143], v[164:167], v[108:111]
	v_mfma_f32_16x16x32_bf16 v[104:107], v[132:135], v[186:189], v[104:107]
	v_mfma_f32_16x16x32_bf16 v[100:103], v[140:143], v[186:189], v[100:103]
	v_mfma_f32_16x16x32_bf16 v[68:71], v[136:139], v[152:155], v[68:71]
	v_mfma_f32_16x16x32_bf16 v[72:75], v[144:147], v[152:155], v[72:75]
	v_mfma_f32_16x16x32_bf16 v[120:123], v[136:139], v[160:163], v[120:123]
	v_mfma_f32_16x16x32_bf16 v[116:119], v[144:147], v[160:163], v[116:119]
	v_mfma_f32_16x16x32_bf16 v[112:115], v[136:139], v[168:171], v[112:115]
	v_mfma_f32_16x16x32_bf16 v[108:111], v[144:147], v[168:171], v[108:111]
	v_mfma_f32_16x16x32_bf16 v[104:107], v[136:139], v[190:193], v[104:107]
	v_mfma_f32_16x16x32_bf16 v[100:103], v[144:147], v[190:193], v[100:103]
	v_mfma_f32_16x16x32_bf16 v[76:79], v[194:197], v[148:151], v[76:79]
	v_mfma_f32_16x16x32_bf16 v[80:83], v[202:205], v[148:151], v[80:83]
	v_mfma_f32_16x16x32_bf16 v[96:99], v[194:197], v[156:159], v[96:99]
	v_mfma_f32_16x16x32_bf16 v[92:95], v[202:205], v[156:159], v[92:95]
	v_mfma_f32_16x16x32_bf16 v[88:91], v[194:197], v[164:167], v[88:91]
	v_mfma_f32_16x16x32_bf16 v[84:87], v[202:205], v[164:167], v[84:87]
	v_mfma_f32_16x16x32_bf16 v[128:131], v[194:197], v[186:189], v[128:131]
	v_mfma_f32_16x16x32_bf16 v[124:127], v[202:205], v[186:189], v[124:127]
	v_mfma_f32_16x16x32_bf16 v[76:79], v[198:201], v[152:155], v[76:79]
	v_mfma_f32_16x16x32_bf16 v[80:83], v[208:211], v[152:155], v[80:83]
	v_mfma_f32_16x16x32_bf16 v[96:99], v[198:201], v[160:163], v[96:99]
	v_mfma_f32_16x16x32_bf16 v[92:95], v[208:211], v[160:163], v[92:95]
	v_mfma_f32_16x16x32_bf16 v[88:91], v[198:201], v[168:171], v[88:91]
	v_mfma_f32_16x16x32_bf16 v[84:87], v[208:211], v[168:171], v[84:87]
	v_mfma_f32_16x16x32_bf16 v[128:131], v[198:201], v[190:193], v[128:131]
	v_mfma_f32_16x16x32_bf16 v[124:127], v[208:211], v[190:193], v[124:127]
	s_barrier
; #define PG8_STAGE(bufoff, gbase, voff) do { _Pragma("unroll") for (int _i = 0; _i < 2; ++_i) \
;         __builtin_amdgcn_global_load_lds((const unsigned*)((const char*)(gbase) + (voff)[_i]), (LAS unsigned*)(lds + (bufoff) + ldsw + _i * 8192), 16, 0, 0); } while (0)
; #define PG8_LDA(dst, b, h) do { _Pragma("unroll") for (int m = 0; m < 4; ++m) _Pragma("unroll") for (int k = 0; k < 2; ++k) dst[m][k] = *(const LAS bf16x8*)(lds + PG8_SA(b, h) + aoff + m * 2048 + k * 1024); } while (0)
; #define PG8_MMA(ai, bj, At, Bt) do { __builtin_amdgcn_s_setprio(1); _Pragma("unroll") for (int m = 0; m < 4; ++m) _Pragma("unroll") for (int n = 0; n < 2; ++n) _Pragma("unroll") for (int k = 0; k < 2; ++k) \
;         acc[ai][bj][m][n] = __builtin_amdgcn_mfma_f32_16x16x32_bf16(Bt[n][k], At[m][k], acc[ai][bj][m][n], 0, 0, 0); __builtin_amdgcn_s_setprio(0); } while (0)
; #define PG8_WAIT_V(n) asm volatile("s_waitcnt vmcnt(" #n ")" ::: "memory")
; #define PG8_WAIT_L(n) asm volatile("s_waitcnt lgkmcnt(" #n ")" ::: "memory")
; #define PG8_BAR __builtin_amdgcn_s_barrier()
; #define PG8_SCHED __builtin_amdgcn_sched_barrier(0)
; template <class Epi, class Sched>
; __device__ __forceinline__ void gemm_phase(LAS unsigned char* lds, const Gemm g, const Sched& S, const Epi& E) {
;     ...
;             PG8_LDA(At, 1, 1); PG8_STAGE(PG8_SA(1, 0), a3, voffA);
;             PG8_BAR; PG8_WAIT_L(0); PG8_MMA(1, 0, At, B0); PG8_BAR; PG8_SCHED;
;             PG8_STAGE(PG8_SB(1, 1), b3 + hstepB, voffB);
;             PG8_WAIT_V(6); PG8_BAR; PG8_MMA(1, 1, At, B1); PG8_BAR;
	s_setprio 0
	ds_read_b128 v[148:151], v207 offset:49152
	ds_read_b128 v[152:155], v207 offset:50176
	ds_read_b128 v[156:159], v207 offset:51200
	ds_read_b128 v[160:163], v207 offset:52224
	ds_read_b128 v[164:167], v207 offset:53248
	ds_read_b128 v[168:171], v207 offset:54272
	ds_read_b128 v[186:189], v207 offset:55296
	ds_read_b128 v[190:193], v207 offset:56320
	s_add_i32 s15, s72, s19
	v_lshl_add_u64 v[172:173], v[172:173], 0, s[8:9]
	s_mov_b32 m0, s15
	s_nop 0
	global_load_lds_dwordx4 v[172:173], off
	v_lshl_add_u64 v[172:173], v[212:213], 0, s[8:9]
	s_add_i32 m0, s15, 0x2000
	s_nop 0
	global_load_lds_dwordx4 v[172:173], off
	s_mov_b32 m0, s30
	v_lshl_add_u64 v[172:173], v[216:217], 0, s[8:9]
	global_load_lds_dwordx4 v[172:173], off
	v_lshl_add_u64 v[172:173], v[218:219], 0, s[8:9]
	s_mov_b32 m0, s31
	s_nop 0
	global_load_lds_dwordx4 v[172:173], off
	s_add_u32 s6, s6, 0x80080
	s_addc_u32 s7, s7, 0
	s_add_i32 s14, s14, s19
	s_mov_b32 m0, s14
	s_nop 0
	global_load_lds_dwordx4 v178, s[6:7]
	s_add_i32 m0, s14, 0x2000
	s_nop 0
	global_load_lds_dwordx4 v174, s[6:7]
	s_add_i32 s71, s71, 2
	s_add_u32 s4, s4, 0x100
	s_addc_u32 s5, s5, 0
	s_add_u32 s69, s69, 0x100
	s_addc_u32 s70, s70, 0
	s_cmp_gt_u32 s71, 29
	s_waitcnt lgkmcnt(0)
	s_waitcnt vmcnt(6)
	s_setprio 1
	s_barrier
	v_mfma_f32_16x16x32_bf16 v[56:59], v[132:135], v[148:151], v[56:59]
	v_mfma_f32_16x16x32_bf16 v[52:55], v[140:143], v[148:151], v[52:55]
	v_mfma_f32_16x16x32_bf16 v[48:51], v[132:135], v[156:159], v[48:51]
	v_mfma_f32_16x16x32_bf16 v[44:47], v[140:143], v[156:159], v[44:47]
	v_mfma_f32_16x16x32_bf16 v[40:43], v[132:135], v[164:167], v[40:43]
	v_mfma_f32_16x16x32_bf16 v[36:39], v[140:143], v[164:167], v[36:39]
	v_mfma_f32_16x16x32_bf16 v[32:35], v[132:135], v[186:189], v[32:35]
	v_mfma_f32_16x16x32_bf16 v[28:31], v[140:143], v[186:189], v[28:31]
	v_mfma_f32_16x16x32_bf16 v[56:59], v[136:139], v[152:155], v[56:59]
	v_mfma_f32_16x16x32_bf16 v[52:55], v[144:147], v[152:155], v[52:55]
	v_mfma_f32_16x16x32_bf16 v[48:51], v[136:139], v[160:163], v[48:51]
	v_mfma_f32_16x16x32_bf16 v[44:47], v[144:147], v[160:163], v[44:47]
	v_mfma_f32_16x16x32_bf16 v[40:43], v[136:139], v[168:171], v[40:43]
	v_mfma_f32_16x16x32_bf16 v[36:39], v[144:147], v[168:171], v[36:39]
	v_mfma_f32_16x16x32_bf16 v[32:35], v[136:139], v[190:193], v[32:35]
	v_mfma_f32_16x16x32_bf16 v[28:31], v[144:147], v[190:193], v[28:31]
	v_mfma_f32_16x16x32_bf16 v[24:27], v[194:197], v[148:151], v[24:27]
	v_mfma_f32_16x16x32_bf16 v[20:23], v[202:205], v[148:151], v[20:23]
	v_mfma_f32_16x16x32_bf16 v[16:19], v[194:197], v[156:159], v[16:19]
	v_mfma_f32_16x16x32_bf16 v[12:15], v[202:205], v[156:159], v[12:15]
	v_mfma_f32_16x16x32_bf16 v[8:11], v[194:197], v[164:167], v[8:11]
	v_mfma_f32_16x16x32_bf16 v[4:7], v[202:205], v[164:167], v[4:7]
	v_mfma_f32_16x16x32_bf16 v[60:63], v[194:197], v[186:189], v[60:63]
	v_mfma_f32_16x16x32_bf16 v[64:67], v[202:205], v[186:189], v[64:67]
	v_mfma_f32_16x16x32_bf16 v[24:27], v[198:201], v[152:155], v[24:27]
	v_mfma_f32_16x16x32_bf16 v[20:23], v[208:211], v[152:155], v[20:23]
	v_mfma_f32_16x16x32_bf16 v[16:19], v[198:201], v[160:163], v[16:19]
	v_mfma_f32_16x16x32_bf16 v[12:15], v[208:211], v[160:163], v[12:15]
	v_mfma_f32_16x16x32_bf16 v[8:11], v[198:201], v[168:171], v[8:11]
	v_mfma_f32_16x16x32_bf16 v[4:7], v[208:211], v[168:171], v[4:7]
	v_mfma_f32_16x16x32_bf16 v[60:63], v[198:201], v[190:193], v[60:63]
	v_mfma_f32_16x16x32_bf16 v[64:67], v[208:211], v[190:193], v[64:67]
	s_barrier
	s_setprio 0

; __device__ __forceinline__ int opaque_tid() { int t = threadIdx.x; asm volatile("" : "+v"(t)); return t; }
; #define PG8_STAGE(bufoff, gbase, voff) do { _Pragma("unroll") for (int _i = 0; _i < 2; ++_i) \
;         __builtin_amdgcn_global_load_lds((const unsigned*)((const char*)(gbase) + (voff)[_i]), (LAS unsigned*)(lds + (bufoff) + ldsw + _i * 8192), 16, 0, 0); } while (0)
; #define PG8_BAR __builtin_amdgcn_s_barrier()
; template <class Epi, class Sched>
; __device__ __forceinline__ void gemm_phase(LAS unsigned char* lds, const Gemm g, const Sched& S, const Epi& E) {
;     const int tid = opaque_tid(), wid = __builtin_amdgcn_readfirstlane(tid >> 6), lane = tid & 63, wr = wid >> 2, wc = wid & 3, fr = lane & 15, fq = lane >> 4;
;     const int K = g.K, nt = K / BK, lda = g.lda;
;     unsigned voffA[2], voffB[2];
; #pragma unroll
;     for (int i = 0; i < 2; ++i) { int R, C; stage_rc(tid * 16 + i * 8192, R, C); const int Rb = Epi::PERM ? ((R & ~31) + perm32(R & 31)) : R;
;         voffA[i] = (unsigned)(R * lda + C) * 2u; voffB[i] = (unsigned)(Rb * K + C) * 2u; }
;     const size_t kstep = (size_t)(BK * 2);
;     const size_t hstepA = (size_t)HALF * lda * 2, hstepB = (size_t)HALF * K * 2;
;     const size_t tstepA = 2 * hstepA, tstepB = 2 * hstepB;
;     const unsigned ldsw = (unsigned)wid * 1024u;
;     const int aoff = lds_byte(wr * 64 + fr, fq * 8), boff = lds_byte(wc * 32 + fr, fq * 8);
;     ...
;     Unit cur, nxt; int ui = 0;
;     if (!S.next(0, cur)) return;
;     f32x4 acc[2][2][4][2];
; #pragma unroll
;     for (int a = 0; a < 2; ++a)
; #pragma unroll
;         for (int b = 0; b < 2; ++b)
; #pragma unroll
;             for (int m = 0; m < 4; ++m)
; #pragma unroll
;                 for (int n = 0; n < 2; ++n) acc[a][b][m][n] = (f32x4){0.f, 0.f, 0.f, 0.f};
;     bf16x8 At[4][2], B0[2][2], B1[2][2];
;     const char* cA = (const char*)g.A + (size_t)cur.pm * tstepA; const char* cB = (const char*)g.Bt + (size_t)cur.pn * tstepB;
;     S.a_ready(cur);
;     PG8_STAGE(PG8_SB(0, 0), cB, voffB); PG8_STAGE(PG8_SA(0, 0), cA, voffA); PG8_STAGE(PG8_SB(0, 1), cB + hstepB, voffB); PG8_STAGE(PG8_SA(0, 1), cA + hstepA, voffA);
;     if (wr == 1) PG8_BAR;
;     PG8_WAIT_V(4); PG8_BAR;
;     PG8_STAGE(PG8_SB(1, 0), cB + kstep, voffB); PG8_STAGE(PG8_SA(1, 0), cA + kstep, voffA); PG8_STAGE(PG8_SB(1, 1), cB + hstepB + kstep, voffB);
;     PG8_WAIT_V(6); PG8_BAR;
.LBB0_1654:
	v_lshl_add_u64 v[12:13], s[14:15], 0, v[2:3]
	v_mov_b32_e32 v193, v3
	v_readlane_b32 s6, v254, 29
	s_lshl_b32 s0, s0, 5
	v_lshl_add_u64 v[14:15], s[14:15], 0, v[192:193]
	v_mov_b32_e32 v197, v3
	v_readlane_b32 s7, v254, 30
	s_and_b32 s37, s0, 0x60
	s_add_i32 m0, s29, 0x18000
	v_lshl_add_u64 v[12:13], v[12:13], 0, s[8:9]
	v_lshl_add_u64 v[16:17], s[6:7], 0, v[196:197]
	v_mov_b32_e32 v195, v3
	s_lshl_b32 s36, s1, 6
	s_lshl_b32 s4, s1, 13
	s_lshl_b32 s5, s37, 7
	s_waitcnt vmcnt(2)
	s_barrier
	global_load_lds_dwordx4 v[12:13], off
	v_lshl_add_u64 v[12:13], v[14:15], 0, s[8:9]
	s_add_i32 m0, s29, 0x1a000
	s_add_i32 s38, s29, 0x8000
	s_add_i32 s39, s29, 0xa000
	v_lshl_add_u64 v[18:19], s[6:7], 0, v[194:195]
	global_load_lds_dwordx4 v[12:13], off
	v_lshl_add_u64 v[12:13], v[16:17], 0, s[8:9]
	s_mov_b32 m0, s38
	s_add_u32 s0, s14, 0x160080
	global_load_lds_dwordx4 v[12:13], off
	v_lshl_add_u64 v[12:13], v[18:19], 0, s[8:9]
	s_mov_b32 m0, s39
	s_addc_u32 s1, s15, 0
	global_load_lds_dwordx4 v[12:13], off
	s_add_i32 m0, s29, 0x1c000
	v_lshl_add_u64 v[12:13], s[0:1], 0, v[2:3]
	global_load_lds_dwordx4 v[12:13], off
	v_lshl_add_u64 v[12:13], s[0:1], 0, v[192:193]
	s_add_i32 m0, s29, 0x1e000
	s_movk_i32 s0, 0x3c0
	global_load_lds_dwordx4 v[12:13], off
	v_and_b32_e32 v12, 48, v1
	v_lshlrev_b32_e32 v13, 6, v1
	v_lshlrev_b32_e32 v1, 2, v1
	v_and_or_b32 v12, v13, s0, v12
	v_and_b32_e32 v1, 32, v1
	v_bitop3_b32 v13, v12, s4, v1 bitop3:0xde
	s_movk_i32 s4, 0x1600
	v_bitop3_b32 v1, s5, v12, v1 bitop3:0xf6
	v_lshrrev_b32_e32 v9, 1, v9
	v_mul_lo_u32 v8, v8, s4
	s_mov_b32 s5, 0x16000
	v_mad_u64_u32 v[8:9], s[0:1], v9, s5, v[8:9]
	v_or_b32_e32 v8, v8, v10
	v_add_lshl_u32 v8, v8, v11, 1
	v_mov_b32_e32 v9, v3
	s_mov_b64 s[18:19], 0x160080
	v_lshl_add_u64 v[198:199], v[8:9], 0, s[18:19]
	v_lshrrev_b32_e32 v8, 1, v4
	v_mul_lo_u32 v4, v5, s4
	v_mad_u64_u32 v[4:5], s[0:1], v8, s5, v[4:5]
	s_waitcnt vmcnt(0)
	v_or_b32_e32 v4, v4, v6
	v_add_lshl_u32 v4, v4, v7, 1
	v_mov_b32_e32 v5, v3
	v_readlane_b32 s0, v254, 27
	v_lshl_add_u64 v[200:201], v[4:5], 0, s[18:19]
	s_mov_b32 s46, 0
	v_add_u32_e32 v224, 0, v13
	v_readlane_b32 s49, v254, 1
	s_mov_b32 s50, s0
	s_barrier
	v_readlane_b32 s1, v254, 28

; #define PG8_STAGE(bufoff, gbase, voff) do { _Pragma("unroll") for (int _i = 0; _i < 2; ++_i) \
;         __builtin_amdgcn_global_load_lds((const unsigned*)((const char*)(gbase) + (voff)[_i]), (LAS unsigned*)(lds + (bufoff) + ldsw + _i * 8192), 16, 0, 0); } while (0)
; #define PG8_LDA(dst, b, h) do { _Pragma("unroll") for (int m = 0; m < 4; ++m) _Pragma("unroll") for (int k = 0; k < 2; ++k) dst[m][k] = *(const LAS bf16x8*)(lds + PG8_SA(b, h) + aoff + m * 2048 + k * 1024); } while (0)
; #define PG8_LDB(dst, b, h) do { _Pragma("unroll") for (int n = 0; n < 2; ++n) _Pragma("unroll") for (int k = 0; k < 2; ++k) dst[n][k] = *(const LAS bf16x8*)(lds + PG8_SB(b, h) + boff + n * 2048 + k * 1024); } while (0)
; #define PG8_MMA(ai, bj, At, Bt) do { __builtin_amdgcn_s_setprio(1); _Pragma("unroll") for (int m = 0; m < 4; ++m) _Pragma("unroll") for (int n = 0; n < 2; ++n) _Pragma("unroll") for (int k = 0; k < 2; ++k) \
;         acc[ai][bj][m][n] = __builtin_amdgcn_mfma_f32_16x16x32_bf16(Bt[n][k], At[m][k], acc[ai][bj][m][n], 0, 0, 0); __builtin_amdgcn_s_setprio(0); } while (0)
; #define PG8_WAIT_V(n) asm volatile("s_waitcnt vmcnt(" #n ")" ::: "memory")
; #define PG8_BAR __builtin_amdgcn_s_barrier()
; template <class Epi, class Sched>
; __device__ __forceinline__ void gemm_phase(LAS unsigned char* lds, const Gemm g, const Sched& S, const Epi& E) {
;     ...
;         for (int t = 0; t < nt; t += 2) {
;             const bool last = (t == nt - 2);
;             const char* a1 = cA + (size_t)(t + 1) * kstep;
;             const char* a2 = last ? nA : cA + (size_t)(t + 2) * kstep; const char* b2 = last ? nB : cB + (size_t)(t + 2) * kstep;
;             const char* a3 = a2 + kstep; const char* b3 = b2 + kstep;
;             if (last && has_next) S.a_ready(nxt);
;             PG8_LDB(B0, 0, 0); PG8_SCHED; PG8_LDA(At, 0, 0); PG8_STAGE(PG8_SA(1, 1), a1 + hstepA, voffA);
;             PG8_WAIT_L(8); PG8_BAR; PG8_WAIT_L(0); PG8_MMA(0, 0, At, B0); PG8_BAR; PG8_SCHED;
;             PG8_LDB(B1, 0, 1); PG8_STAGE(PG8_SB(0, 0), b2, voffB);
;             PG8_BAR; PG8_WAIT_L(0); PG8_MMA(0, 1, At, B1); PG8_BAR;
;             PG8_LDA(At, 0, 1); PG8_STAGE(PG8_SA(0, 0), a2, voffA);
;             PG8_BAR; PG8_WAIT_L(0); PG8_MMA(1, 0, At, B0); PG8_BAR; PG8_SCHED;
;             PG8_STAGE(PG8_SB(0, 1), b2 + hstepB, voffB);
;             PG8_WAIT_V(6); PG8_BAR; PG8_MMA(1, 1, At, B1); PG8_BAR;
.LBB0_1665:
	s_add_u32 s42, s14, 0x100
	s_addc_u32 s43, s15, 0
	s_mov_b32 s44, -2
	s_setprio 0
	s_add_u32 s14, s6, 0x100
	s_addc_u32 s15, s7, 0
	s_add_i32 s45, 0, 0x10000
	v_add_u32_e32 v144, s45, v1
	ds_read_b128 v[132:135], v144
	ds_read_b128 v[136:139], v144 offset:1024
	ds_read_b128 v[140:143], v144 offset:2048
	ds_read_b128 v[144:147], v144 offset:3072
	s_cmpk_eq_i32 s44, 0x54
	s_cselect_b32 s21, s1, s15
	s_cselect_b32 s20, s0, s14
	s_cselect_b32 s19, s5, s43
	s_cselect_b32 s18, s4, s42
	ds_read_b128 v[148:151], v224
	ds_read_b128 v[152:155], v224 offset:1024
	ds_read_b128 v[156:159], v224 offset:2048
	ds_read_b128 v[160:163], v224 offset:3072
	ds_read_b128 v[164:167], v224 offset:4096
	ds_read_b128 v[168:171], v224 offset:5120
	ds_read_b128 v[172:175], v224 offset:6144
	ds_read_b128 v[176:179], v224 offset:7168
	s_add_i32 s51, 0, 0x14000
	v_add_u32_e32 v202, s51, v1
	ds_read_b128 v[180:183], v202
	ds_read_b128 v[184:187], v202 offset:1024
	ds_read_b128 v[188:191], v202 offset:2048
	ds_read_b128 v[202:205], v202 offset:3072
	s_add_i32 m0, s29, 0xc000
	s_nop 0
	global_load_lds_dwordx4 v198, s[6:7]
	s_add_i32 m0, s29, 0xe000
	s_nop 0
	global_load_lds_dwordx4 v200, s[6:7]
	s_waitcnt lgkmcnt(0)
	s_setprio 1
	s_barrier
	v_mfma_f32_16x16x32_bf16 v[128:131], v[132:135], v[148:151], 0
	v_mfma_f32_16x16x32_bf16 v[124:127], v[140:143], v[148:151], 0
	v_mfma_f32_16x16x32_bf16 v[112:115], v[132:135], v[156:159], 0
	v_mfma_f32_16x16x32_bf16 v[108:111], v[140:143], v[156:159], 0
	v_mfma_f32_16x16x32_bf16 v[100:103], v[132:135], v[164:167], 0
	v_mfma_f32_16x16x32_bf16 v[92:95], v[140:143], v[164:167], 0
	v_mfma_f32_16x16x32_bf16 v[84:87], v[132:135], v[172:175], 0
	v_mfma_f32_16x16x32_bf16 v[76:79], v[140:143], v[172:175], 0
	v_mfma_f32_16x16x32_bf16 v[128:131], v[136:139], v[152:155], v[128:131]
	v_mfma_f32_16x16x32_bf16 v[124:127], v[144:147], v[152:155], v[124:127]
	v_mfma_f32_16x16x32_bf16 v[112:115], v[136:139], v[160:163], v[112:115]
	v_mfma_f32_16x16x32_bf16 v[108:111], v[144:147], v[160:163], v[108:111]
	v_mfma_f32_16x16x32_bf16 v[100:103], v[136:139], v[168:171], v[100:103]
	v_mfma_f32_16x16x32_bf16 v[92:95], v[144:147], v[168:171], v[92:95]
	v_mfma_f32_16x16x32_bf16 v[84:87], v[136:139], v[176:179], v[84:87]
	v_mfma_f32_16x16x32_bf16 v[76:79], v[144:147], v[176:179], v[76:79]
	v_mfma_f32_16x16x32_bf16 v[120:123], v[180:183], v[148:151], 0
	v_mfma_f32_16x16x32_bf16 v[116:119], v[188:191], v[148:151], 0
	v_mfma_f32_16x16x32_bf16 v[104:107], v[180:183], v[156:159], 0
	v_mfma_f32_16x16x32_bf16 v[96:99], v[188:191], v[156:159], 0
	v_mfma_f32_16x16x32_bf16 v[88:91], v[180:183], v[164:167], 0
	v_mfma_f32_16x16x32_bf16 v[80:83], v[188:191], v[164:167], 0
	v_mfma_f32_16x16x32_bf16 v[72:75], v[180:183], v[172:175], 0
	v_mfma_f32_16x16x32_bf16 v[68:71], v[188:191], v[172:175], 0
	v_mfma_f32_16x16x32_bf16 v[120:123], v[184:187], v[152:155], v[120:123]
	v_mfma_f32_16x16x32_bf16 v[116:119], v[202:205], v[152:155], v[116:119]
	v_mfma_f32_16x16x32_bf16 v[104:107], v[184:187], v[160:163], v[104:107]
	v_mfma_f32_16x16x32_bf16 v[96:99], v[202:205], v[160:163], v[96:99]
	v_mfma_f32_16x16x32_bf16 v[88:91], v[184:187], v[168:171], v[88:91]
	v_mfma_f32_16x16x32_bf16 v[80:83], v[202:205], v[168:171], v[80:83]
	v_mfma_f32_16x16x32_bf16 v[72:75], v[184:187], v[176:179], v[72:75]
	v_mfma_f32_16x16x32_bf16 v[68:71], v[202:205], v[176:179], v[68:71]
	s_barrier
	s_setprio 0
	ds_read_b128 v[148:151], v224 offset:16384
	ds_read_b128 v[152:155], v224 offset:17408
	ds_read_b128 v[156:159], v224 offset:18432
	ds_read_b128 v[160:163], v224 offset:19456
	ds_read_b128 v[164:167], v224 offset:20480
	ds_read_b128 v[168:171], v224 offset:21504
	ds_read_b128 v[172:175], v224 offset:22528
	ds_read_b128 v[176:179], v224 offset:23552
	s_add_i32 s6, s45, s28
	v_lshl_add_u64 v[206:207], s[18:19], 0, v[2:3]
	s_mov_b32 m0, s6
	s_nop 0
	global_load_lds_dwordx4 v[206:207], off
	v_lshl_add_u64 v[208:209], s[18:19], 0, v[192:193]
	s_add_i32 m0, s6, 0x2000
	s_nop 0
	global_load_lds_dwordx4 v[208:209], off
	s_mov_b32 m0, s29
	v_lshl_add_u64 v[210:211], s[20:21], 0, v[196:197]
	global_load_lds_dwordx4 v[210:211], off
	v_lshl_add_u64 v[212:213], s[20:21], 0, v[194:195]
	s_mov_b32 m0, s30
	s_nop 0
	global_load_lds_dwordx4 v[212:213], off
	s_add_u32 s6, s18, 0x160000
	s_addc_u32 s7, s19, 0
	s_add_i32 s45, s51, s28
	s_mov_b32 m0, s45
	s_nop 0
	global_load_lds_dwordx4 v2, s[6:7]
	s_add_i32 m0, s45, 0x2000
	s_nop 0
	global_load_lds_dwordx4 v192, s[6:7]
	s_waitcnt lgkmcnt(0)
	s_setprio 1
	s_barrier
	v_mfma_f32_16x16x32_bf16 v[64:67], v[132:135], v[148:151], 0
	v_mfma_f32_16x16x32_bf16 v[60:63], v[140:143], v[148:151], 0
	v_mfma_f32_16x16x32_bf16 v[52:55], v[132:135], v[156:159], 0
	v_mfma_f32_16x16x32_bf16 v[44:47], v[140:143], v[156:159], 0
	v_mfma_f32_16x16x32_bf16 v[36:39], v[132:135], v[164:167], 0
	v_mfma_f32_16x16x32_bf16 v[28:31], v[140:143], v[164:167], 0
	v_mfma_f32_16x16x32_bf16 v[20:23], v[132:135], v[172:175], 0
	v_mfma_f32_16x16x32_bf16 v[12:15], v[140:143], v[172:175], 0
	v_mfma_f32_16x16x32_bf16 v[64:67], v[136:139], v[152:155], v[64:67]
	v_mfma_f32_16x16x32_bf16 v[60:63], v[144:147], v[152:155], v[60:63]
	v_mfma_f32_16x16x32_bf16 v[52:55], v[136:139], v[160:163], v[52:55]
	v_mfma_f32_16x16x32_bf16 v[44:47], v[144:147], v[160:163], v[44:47]
	v_mfma_f32_16x16x32_bf16 v[36:39], v[136:139], v[168:171], v[36:39]
	v_mfma_f32_16x16x32_bf16 v[28:31], v[144:147], v[168:171], v[28:31]
	v_mfma_f32_16x16x32_bf16 v[20:23], v[136:139], v[176:179], v[20:23]
	v_mfma_f32_16x16x32_bf16 v[12:15], v[144:147], v[176:179], v[12:15]
	v_mfma_f32_16x16x32_bf16 v[56:59], v[180:183], v[148:151], 0
	v_mfma_f32_16x16x32_bf16 v[48:51], v[188:191], v[148:151], 0
	v_mfma_f32_16x16x32_bf16 v[40:43], v[180:183], v[156:159], 0
	v_mfma_f32_16x16x32_bf16 v[32:35], v[188:191], v[156:159], 0
	v_mfma_f32_16x16x32_bf16 v[24:27], v[180:183], v[164:167], 0
	v_mfma_f32_16x16x32_bf16 v[16:19], v[188:191], v[164:167], 0
	v_mfma_f32_16x16x32_bf16 v[8:11], v[180:183], v[172:175], 0
	v_mfma_f32_16x16x32_bf16 v[4:7], v[188:191], v[172:175], 0
	v_mfma_f32_16x16x32_bf16 v[56:59], v[184:187], v[152:155], v[56:59]
	v_mfma_f32_16x16x32_bf16 v[48:51], v[202:205], v[152:155], v[48:51]
	v_mfma_f32_16x16x32_bf16 v[40:43], v[184:187], v[160:163], v[40:43]
	v_mfma_f32_16x16x32_bf16 v[32:35], v[202:205], v[160:163], v[32:35]
	v_mfma_f32_16x16x32_bf16 v[24:27], v[184:187], v[168:171], v[24:27]
	v_mfma_f32_16x16x32_bf16 v[16:19], v[202:205], v[168:171], v[16:19]
	v_mfma_f32_16x16x32_bf16 v[8:11], v[184:187], v[176:179], v[8:11]
	v_mfma_f32_16x16x32_bf16 v[4:7], v[202:205], v[176:179], v[4:7]
	s_barrier
; #define PG8_STAGE(bufoff, gbase, voff) do { _Pragma("unroll") for (int _i = 0; _i < 2; ++_i) \
;         __builtin_amdgcn_global_load_lds((const unsigned*)((const char*)(gbase) + (voff)[_i]), (LAS unsigned*)(lds + (bufoff) + ldsw + _i * 8192), 16, 0, 0); } while (0)
; #define PG8_LDA(dst, b, h) do { _Pragma("unroll") for (int m = 0; m < 4; ++m) _Pragma("unroll") for (int k = 0; k < 2; ++k) dst[m][k] = *(const LAS bf16x8*)(lds + PG8_SA(b, h) + aoff + m * 2048 + k * 1024); } while (0)
; #define PG8_LDB(dst, b, h) do { _Pragma("unroll") for (int n = 0; n < 2; ++n) _Pragma("unroll") for (int k = 0; k < 2; ++k) dst[n][k] = *(const LAS bf16x8*)(lds + PG8_SB(b, h) + boff + n * 2048 + k * 1024); } while (0)
; #define PG8_MMA(ai, bj, At, Bt) do { __builtin_amdgcn_s_setprio(1); _Pragma("unroll") for (int m = 0; m < 4; ++m) _Pragma("unroll") for (int n = 0; n < 2; ++n) _Pragma("unroll") for (int k = 0; k < 2; ++k) \
;         acc[ai][bj][m][n] = __builtin_amdgcn_mfma_f32_16x16x32_bf16(Bt[n][k], At[m][k], acc[ai][bj][m][n], 0, 0, 0); __builtin_amdgcn_s_setprio(0); } while (0)
; #define PG8_WAIT_V(n) asm volatile("s_waitcnt vmcnt(" #n ")" ::: "memory")
; #define PG8_WAIT_L(n) asm volatile("s_waitcnt lgkmcnt(" #n ")" ::: "memory")
; #define PG8_BAR __builtin_amdgcn_s_barrier()
; #define PG8_SCHED __builtin_amdgcn_sched_barrier(0)
; template <class Epi, class Sched>
; __device__ __forceinline__ void gemm_phase(LAS unsigned char* lds, const Gemm g, const Sched& S, const Epi& E) {
;     ...
;             PG8_WAIT_V(6); PG8_BAR; PG8_MMA(1, 1, At, B1); PG8_BAR;
;             PG8_LDB(B0, 1, 0); PG8_SCHED; PG8_LDA(At, 1, 0); PG8_STAGE(PG8_SA(0, 1), a2 + hstepA, voffA);
;             PG8_WAIT_L(8); PG8_BAR; PG8_WAIT_L(0); PG8_MMA(0, 0, At, B0); PG8_BAR; PG8_SCHED;
;             PG8_LDB(B1, 1, 1); PG8_STAGE(PG8_SB(1, 0), b3, voffB);
;             PG8_BAR; PG8_WAIT_L(0); PG8_MMA(0, 1, At, B1); PG8_BAR;
;             PG8_LDA(At, 1, 1); PG8_STAGE(PG8_SA(1, 0), a3, voffA);
;             PG8_BAR; PG8_WAIT_L(0); PG8_MMA(1, 0, At, B0); PG8_BAR; PG8_SCHED;
;             PG8_STAGE(PG8_SB(1, 1), b3 + hstepB, voffB);
;             PG8_WAIT_V(6); PG8_BAR; PG8_MMA(1, 1, At, B1); PG8_BAR;
	s_setprio 0
	s_add_i32 s45, 0, 0x18000
	v_add_u32_e32 v144, s45, v1
	ds_read_b128 v[132:135], v144
	ds_read_b128 v[136:139], v144 offset:1024
	ds_read_b128 v[140:143], v144 offset:2048
	ds_read_b128 v[144:147], v144 offset:3072
	s_add_u32 s6, s20, 0x160000
	s_addc_u32 s7, s21, 0
	ds_read_b128 v[148:151], v224 offset:32768
	ds_read_b128 v[152:155], v224 offset:33792
	ds_read_b128 v[156:159], v224 offset:34816
	ds_read_b128 v[160:163], v224 offset:35840
	ds_read_b128 v[164:167], v224 offset:36864
	ds_read_b128 v[168:171], v224 offset:37888
	ds_read_b128 v[172:175], v224 offset:38912
	ds_read_b128 v[176:179], v224 offset:39936
	s_mov_b32 m0, s31
	s_nop 0
	global_load_lds_dwordx4 v196, s[6:7]
	s_mov_b32 m0, s35
	s_nop 0
	global_load_lds_dwordx4 v194, s[6:7]
	s_add_i32 s20, 0, 0x1c000
	v_add_u32_e32 v202, s20, v1
	ds_read_b128 v[180:183], v202
	ds_read_b128 v[184:187], v202 offset:1024
	ds_read_b128 v[188:191], v202 offset:2048
	ds_read_b128 v[202:205], v202 offset:3072
	s_waitcnt lgkmcnt(0)
	s_setprio 1
	s_waitcnt vmcnt(8)
	s_barrier
	v_mfma_f32_16x16x32_bf16 v[128:131], v[132:135], v[148:151], v[128:131]
	v_mfma_f32_16x16x32_bf16 v[124:127], v[140:143], v[148:151], v[124:127]
	v_mfma_f32_16x16x32_bf16 v[112:115], v[132:135], v[156:159], v[112:115]
	v_mfma_f32_16x16x32_bf16 v[108:111], v[140:143], v[156:159], v[108:111]
	v_mfma_f32_16x16x32_bf16 v[100:103], v[132:135], v[164:167], v[100:103]
	v_mfma_f32_16x16x32_bf16 v[92:95], v[140:143], v[164:167], v[92:95]
	v_mfma_f32_16x16x32_bf16 v[84:87], v[132:135], v[172:175], v[84:87]
	v_mfma_f32_16x16x32_bf16 v[76:79], v[140:143], v[172:175], v[76:79]
	v_mfma_f32_16x16x32_bf16 v[128:131], v[136:139], v[152:155], v[128:131]
	v_mfma_f32_16x16x32_bf16 v[124:127], v[144:147], v[152:155], v[124:127]
	v_mfma_f32_16x16x32_bf16 v[112:115], v[136:139], v[160:163], v[112:115]
	v_mfma_f32_16x16x32_bf16 v[108:111], v[144:147], v[160:163], v[108:111]
	v_mfma_f32_16x16x32_bf16 v[100:103], v[136:139], v[168:171], v[100:103]
	v_mfma_f32_16x16x32_bf16 v[92:95], v[144:147], v[168:171], v[92:95]
	v_mfma_f32_16x16x32_bf16 v[84:87], v[136:139], v[176:179], v[84:87]
	v_mfma_f32_16x16x32_bf16 v[76:79], v[144:147], v[176:179], v[76:79]
	v_mfma_f32_16x16x32_bf16 v[120:123], v[180:183], v[148:151], v[120:123]
	v_mfma_f32_16x16x32_bf16 v[116:119], v[188:191], v[148:151], v[116:119]
	v_mfma_f32_16x16x32_bf16 v[104:107], v[180:183], v[156:159], v[104:107]
	v_mfma_f32_16x16x32_bf16 v[96:99], v[188:191], v[156:159], v[96:99]
	v_mfma_f32_16x16x32_bf16 v[88:91], v[180:183], v[164:167], v[88:91]
	v_mfma_f32_16x16x32_bf16 v[80:83], v[188:191], v[164:167], v[80:83]
	v_mfma_f32_16x16x32_bf16 v[72:75], v[180:183], v[172:175], v[72:75]
	v_mfma_f32_16x16x32_bf16 v[68:71], v[188:191], v[172:175], v[68:71]
	v_mfma_f32_16x16x32_bf16 v[120:123], v[184:187], v[152:155], v[120:123]
	v_mfma_f32_16x16x32_bf16 v[116:119], v[202:205], v[152:155], v[116:119]
	v_mfma_f32_16x16x32_bf16 v[104:107], v[184:187], v[160:163], v[104:107]
	v_mfma_f32_16x16x32_bf16 v[96:99], v[202:205], v[160:163], v[96:99]
	v_mfma_f32_16x16x32_bf16 v[88:91], v[184:187], v[168:171], v[88:91]
	v_mfma_f32_16x16x32_bf16 v[80:83], v[202:205], v[168:171], v[80:83]
	v_mfma_f32_16x16x32_bf16 v[72:75], v[184:187], v[176:179], v[72:75]
	v_mfma_f32_16x16x32_bf16 v[68:71], v[202:205], v[176:179], v[68:71]
	s_barrier
	s_setprio 0
	ds_read_b128 v[148:151], v224 offset:49152
	ds_read_b128 v[152:155], v224 offset:50176
	ds_read_b128 v[156:159], v224 offset:51200
	ds_read_b128 v[160:163], v224 offset:52224
	ds_read_b128 v[164:167], v224 offset:53248
	ds_read_b128 v[168:171], v224 offset:54272
	ds_read_b128 v[172:175], v224 offset:55296
	ds_read_b128 v[176:179], v224 offset:56320
	s_add_i32 s6, s45, s28
	v_lshl_add_u64 v[206:207], v[206:207], 0, s[8:9]
	s_mov_b32 m0, s6
	s_nop 0
	global_load_lds_dwordx4 v[206:207], off
	v_lshl_add_u64 v[206:207], v[208:209], 0, s[8:9]
	s_add_i32 m0, s6, 0x2000
	s_nop 0
	global_load_lds_dwordx4 v[206:207], off
	s_mov_b32 m0, s38
	v_lshl_add_u64 v[206:207], v[210:211], 0, s[8:9]
	global_load_lds_dwordx4 v[206:207], off
	v_lshl_add_u64 v[206:207], v[212:213], 0, s[8:9]
	s_mov_b32 m0, s39
	s_nop 0
	global_load_lds_dwordx4 v[206:207], off
	s_add_u32 s6, s18, 0x160080
	s_addc_u32 s7, s19, 0
	s_add_i32 s18, s20, s28
	s_mov_b32 m0, s18
	s_nop 0
	global_load_lds_dwordx4 v2, s[6:7]
	s_add_i32 m0, s18, 0x2000
	s_nop 0
	global_load_lds_dwordx4 v192, s[6:7]
	s_add_i32 s44, s44, 2
	s_add_u32 s42, s42, 0x100
	s_addc_u32 s43, s43, 0
	s_cmpk_gt_u32 s44, 0x55
	s_mov_b64 s[6:7], s[14:15]
	s_waitcnt lgkmcnt(0)
	s_waitcnt vmcnt(6)
	s_setprio 1
	s_barrier
	v_mfma_f32_16x16x32_bf16 v[64:67], v[132:135], v[148:151], v[64:67]
	v_mfma_f32_16x16x32_bf16 v[60:63], v[140:143], v[148:151], v[60:63]
	v_mfma_f32_16x16x32_bf16 v[52:55], v[132:135], v[156:159], v[52:55]
	v_mfma_f32_16x16x32_bf16 v[44:47], v[140:143], v[156:159], v[44:47]
	v_mfma_f32_16x16x32_bf16 v[36:39], v[132:135], v[164:167], v[36:39]
	v_mfma_f32_16x16x32_bf16 v[28:31], v[140:143], v[164:167], v[28:31]
	v_mfma_f32_16x16x32_bf16 v[20:23], v[132:135], v[172:175], v[20:23]
	v_mfma_f32_16x16x32_bf16 v[12:15], v[140:143], v[172:175], v[12:15]
	v_mfma_f32_16x16x32_bf16 v[64:67], v[136:139], v[152:155], v[64:67]
	v_mfma_f32_16x16x32_bf16 v[60:63], v[144:147], v[152:155], v[60:63]
	v_mfma_f32_16x16x32_bf16 v[52:55], v[136:139], v[160:163], v[52:55]
	v_mfma_f32_16x16x32_bf16 v[44:47], v[144:147], v[160:163], v[44:47]
	v_mfma_f32_16x16x32_bf16 v[36:39], v[136:139], v[168:171], v[36:39]
	v_mfma_f32_16x16x32_bf16 v[28:31], v[144:147], v[168:171], v[28:31]
	v_mfma_f32_16x16x32_bf16 v[20:23], v[136:139], v[176:179], v[20:23]
	v_mfma_f32_16x16x32_bf16 v[12:15], v[144:147], v[176:179], v[12:15]
	v_mfma_f32_16x16x32_bf16 v[56:59], v[180:183], v[148:151], v[56:59]
	v_mfma_f32_16x16x32_bf16 v[48:51], v[188:191], v[148:151], v[48:51]
	v_mfma_f32_16x16x32_bf16 v[40:43], v[180:183], v[156:159], v[40:43]
	v_mfma_f32_16x16x32_bf16 v[32:35], v[188:191], v[156:159], v[32:35]
	v_mfma_f32_16x16x32_bf16 v[24:27], v[180:183], v[164:167], v[24:27]
	v_mfma_f32_16x16x32_bf16 v[16:19], v[188:191], v[164:167], v[16:19]
	v_mfma_f32_16x16x32_bf16 v[8:11], v[180:183], v[172:175], v[8:11]
	v_mfma_f32_16x16x32_bf16 v[4:7], v[188:191], v[172:175], v[4:7]
	v_mfma_f32_16x16x32_bf16 v[56:59], v[184:187], v[152:155], v[56:59]
	v_mfma_f32_16x16x32_bf16 v[48:51], v[202:205], v[152:155], v[48:51]
	v_mfma_f32_16x16x32_bf16 v[40:43], v[184:187], v[160:163], v[40:43]
	v_mfma_f32_16x16x32_bf16 v[32:35], v[202:205], v[160:163], v[32:35]
	v_mfma_f32_16x16x32_bf16 v[24:27], v[184:187], v[168:171], v[24:27]
	v_mfma_f32_16x16x32_bf16 v[16:19], v[202:205], v[168:171], v[16:19]
	v_mfma_f32_16x16x32_bf16 v[8:11], v[184:187], v[176:179], v[8:11]
	v_mfma_f32_16x16x32_bf16 v[4:7], v[202:205], v[176:179], v[4:7]
	s_barrier
	s_setprio 0
